# instruction diet: grouped LDS waits, scalar branch for softmax-reference path, saddr-form K/V prefetch addressing, merged vmcnt waits in GEMM, double-buffered P fragment
# speedup vs baseline: 1.0171x; 1.0171x over previous
; __device__ __forceinline__ void as_load(AStage& g, const u16* kg, const u16* vg, int kt) {
;   const u16* kp = kg + (size_t)kt * 6144;
;   g.k0 = *(const u32x4*)(kp); g.k1 = *(const u32x4*)(kp + 2048); g.k2 = *(const u32x4*)(kp + 4096);
;   const u16* vp = vg + (size_t)kt * 4096;
;   g.v0 = *(const u32x4*)(vp); g.v1 = *(const u32x4*)(vp + 2048);
; __device__ __forceinline__ void attn_tile(const u16* sb, const bf16x8 (&qa)[6], f32x16& o0, f32x16& o1, f32x16& lacc,
;                                           float& m, bool& mz, int r, int h, bool first) {
;   const u16* kp = sb + r * KLD + h * 8;
;   f32x16 s0, s1;
;   __builtin_amdgcn_s_setprio(1);
;   if (mz) {
; #pragma unroll
;     for (int i = 0; i < 16; ++i) { s0[i] = 0.f; s1[i] = 0.f; }
;     attn_qk(kp, qa, s0, s1);
;   } else {
; #pragma unroll
;     for (int i = 0; i < 16; ++i) { s0[i] = -m; s1[i] = -m; }
;     attn_qk(kp, qa, s0, s1);
;   }
.LBB0_456:
	s_add_i32 s58, s45, -1
	s_cmp_lt_i32 s58, s44
	s_cselect_b64 s[0:1], -1, 0
	s_cmp_ge_i32 s58, s44
	s_cbranch_scc1 .LBB0_458
	s_add_u32 s60, s42, 0xd000
	s_addc_u32 s61, s43, 0
	global_load_dwordx4 v[90:93], v134, s[60:61] offset:-4096
	global_load_dwordx4 v[94:97], v134, s[60:61]
	s_add_u32 s60, s42, 0xe000
	s_addc_u32 s61, s43, 0
	global_load_dwordx4 v[106:109], v134, s[60:61]
	s_add_u32 s60, s46, 0x9000
	s_addc_u32 s61, s47, 0
	global_load_dwordx4 v[114:117], v134, s[60:61] offset:-4096
	global_load_dwordx4 v[122:125], v134, s[60:61]
.LBB0_458:
	ds_read_b128 v[214:217], v157
	ds_read_b128 v[218:221], v157 offset:6656
	ds_read_b128 v[222:225], v157 offset:32
	ds_read_b128 v[226:229], v157 offset:6688
	ds_read_b128 v[230:233], v157 offset:64
	ds_read_b128 v[234:237], v157 offset:6720
	ds_read_b128 v[238:241], v157 offset:96
	ds_read_b128 v[242:245], v157 offset:6752
	ds_read_b128 v[246:249], v157 offset:128
	ds_read_b128 v[250:253], v157 offset:6784
	ds_read_b128 v[142:145], v157 offset:160
	ds_read_b128 v[146:149], v157 offset:6816
	s_setprio 1
	s_cmp_lg_u64 s[48:49], 0
	s_cbranch_scc1 .Lmz_e
	v_xor_b32_e32 v34, 0x80000000, v162
	v_mov_b32_e32 v35, v34
	v_mov_b32_e32 v36, v34
	v_mov_b32_e32 v37, v34
	v_mov_b32_e32 v38, v34
	v_mov_b32_e32 v39, v34
	v_mov_b32_e32 v40, v34
	v_mov_b32_e32 v41, v34
	v_mov_b32_e32 v42, v34
	v_mov_b32_e32 v43, v34
	v_mov_b32_e32 v44, v34
	v_mov_b32_e32 v45, v34
	v_mov_b32_e32 v46, v34
	v_mov_b32_e32 v47, v34
	v_mov_b32_e32 v48, v34
	v_mov_b32_e32 v49, v34
	s_waitcnt lgkmcnt(8)
	s_nop 0
	v_mfma_f32_32x32x16_bf16 v[50:65], v[214:217], v[66:69], v[34:49]
	v_mfma_f32_32x32x16_bf16 v[34:49], v[218:221], v[66:69], v[34:49]
	v_mfma_f32_32x32x16_bf16 v[50:65], v[222:225], v[70:73], v[50:65]
	v_mfma_f32_32x32x16_bf16 v[34:49], v[226:229], v[70:73], v[34:49]
	s_waitcnt lgkmcnt(4)
	v_mfma_f32_32x32x16_bf16 v[50:65], v[230:233], v[74:77], v[50:65]
	v_mfma_f32_32x32x16_bf16 v[34:49], v[234:237], v[74:77], v[34:49]
	v_mfma_f32_32x32x16_bf16 v[50:65], v[238:241], v[78:81], v[50:65]
	v_mfma_f32_32x32x16_bf16 v[34:49], v[242:245], v[78:81], v[34:49]
	s_waitcnt lgkmcnt(0)
	v_mfma_f32_32x32x16_bf16 v[50:65], v[246:249], v[82:85], v[50:65]
	v_mfma_f32_32x32x16_bf16 v[34:49], v[250:253], v[82:85], v[34:49]
	v_mfma_f32_32x32x16_bf16 v[50:65], v[142:145], v[86:89], v[50:65]
	v_mfma_f32_32x32x16_bf16 v[34:49], v[146:149], v[86:89], v[34:49]
	s_branch .Lqkd_e
.Lmz_e:
	s_waitcnt lgkmcnt(8)
	v_mfma_f32_32x32x16_bf16 v[50:65], v[214:217], v[66:69], 0
	v_mfma_f32_32x32x16_bf16 v[34:49], v[218:221], v[66:69], 0
	v_mfma_f32_32x32x16_bf16 v[50:65], v[222:225], v[70:73], v[50:65]
	v_mfma_f32_32x32x16_bf16 v[34:49], v[226:229], v[70:73], v[34:49]
	s_waitcnt lgkmcnt(4)
	v_mfma_f32_32x32x16_bf16 v[50:65], v[230:233], v[74:77], v[50:65]
	v_mfma_f32_32x32x16_bf16 v[34:49], v[234:237], v[74:77], v[34:49]
	v_mfma_f32_32x32x16_bf16 v[50:65], v[238:241], v[78:81], v[50:65]
	v_mfma_f32_32x32x16_bf16 v[34:49], v[242:245], v[78:81], v[34:49]
	s_waitcnt lgkmcnt(0)
	v_mfma_f32_32x32x16_bf16 v[50:65], v[246:249], v[82:85], v[50:65]
	v_mfma_f32_32x32x16_bf16 v[34:49], v[250:253], v[82:85], v[34:49]
	v_mfma_f32_32x32x16_bf16 v[50:65], v[142:145], v[86:89], v[50:65]
	v_mfma_f32_32x32x16_bf16 v[34:49], v[146:149], v[86:89], v[34:49]
; __device__ __forceinline__ void attn_tile(const u16* sb, const bf16x8 (&qa)[6], f32x16& o0, f32x16& o1, f32x16& lacc,
;                                           float& m, bool& mz, int r, int h, bool first) {
;     ...
;   __builtin_amdgcn_s_setprio(0);
;   float mxa = max3f(s0[0], s0[1], s0[2]), mxb = max3f(s0[3], s0[4], s0[5]);
;   float mxc = max3f(s0[6], s0[7], s0[8]), mxd = max3f(s0[9], s0[10], s0[11]);
;   mxa = max3f(mxa, s0[12], s0[13]); mxb = max3f(mxb, s0[14], s0[15]);
;   mxc = max3f(mxc, s1[0], s1[1]); mxd = max3f(mxd, s1[2], s1[3]);
;   mxa = max3f(mxa, s1[4], s1[5]); mxb = max3f(mxb, s1[6], s1[7]);
;   mxc = max3f(mxc, s1[8], s1[9]); mxd = max3f(mxd, s1[10], s1[11]);
;   mxa = max3f(mxa, s1[12], s1[13]); mxb = max3f(mxb, s1[14], s1[15]);
;   const float lm = max3f(mxa, mxb, fmaxf(mxc, mxd));
;   bool slow;
;   if (first) {
;     const float mx = fmaxf(lm, __shfl_xor(lm, 32));
;     slow = __any(mx > 30.f || mx < -30.f);
;   } else {
;     slow = __any(lm > 30.f);
;   }
;   if (slow) {
;     const float mx = fmaxf(lm, __shfl_xor(lm, 32));
;     const float d = first ? mx : fmaxf(mx, 0.f);
;     const float alpha = first ? 1.f : __builtin_amdgcn_exp2f(-d);
;     m += d;
;     mz = false;
; #pragma unroll
;     for (int i = 0; i < 16; ++i) { s0[i] -= d; s1[i] -= d; o0[i] *= alpha; o1[i] *= alpha; }
;     lacc[0] *= alpha;
;   }
;   float pa = 0.f, pb = 0.f, pc = 0.f, pd = 0.f;
; #pragma unroll
;   for (int i = 0; i < 16; ++i) {
;     s0[i] = __builtin_amdgcn_exp2f(s0[i]); s1[i] = __builtin_amdgcn_exp2f(s1[i]);
;     if ((i & 3) == 0) pa += s0[i] + s1[i];
;     else if ((i & 3) == 1) pb += s0[i] + s1[i];
;     else if ((i & 3) == 2) pc += s0[i] + s1[i];
;     else pd += s0[i] + s1[i];
;   }
;   lacc[0] += (pa + pb) + (pc + pd);
;   const u16* vp = sb + 64 * KLD + r * VLD + 8 * h;
;   __builtin_amdgcn_s_setprio(1);
; #pragma unroll
;   for (int kb = 0; kb < 2; ++kb) {
; #pragma unroll
;     for (int s = 0; s < 2; ++s) {
;       const bf16x8 pf = pack_p(kb == 0 ? s0 : s1, 8 * s);
;       const int koff = kb * 32 + 16 * s;
;       const bf16x8 v0 = *(const bf16x8*)(vp + koff);
;       const bf16x8 v1 = *(const bf16x8*)(vp + 32 * VLD + koff);
;       o0 = mfma32(v0, pf, o0);
;       o1 = mfma32(v1, pf, o1);
;     }
;   }
;   __builtin_amdgcn_s_setprio(0);
.Lqkd_e:
	ds_read_b128 v[214:217], v163 offset:13312
	ds_read_b128 v[218:221], v163 offset:17920
	ds_read_b128 v[222:225], v163 offset:13344
	ds_read_b128 v[226:229], v163 offset:17952
	ds_read_b128 v[230:233], v163 offset:13376
	ds_read_b128 v[234:237], v163 offset:17984
	ds_read_b128 v[238:241], v163 offset:13408
	ds_read_b128 v[242:245], v163 offset:18016
	s_nop 1
	s_setprio 0
	v_max3_f32 v142, v50, v51, v52
	v_max3_f32 v144, v56, v57, v58
	v_max3_f32 v145, v59, v60, v61
	v_max3_f32 v143, v53, v54, v55
	v_max3_f32 v142, v142, v62, v63
	v_max3_f32 v144, v144, v34, v35
	v_max3_f32 v145, v145, v36, v37
	v_max3_f32 v143, v143, v64, v65
	v_max3_f32 v142, v142, v38, v39
	v_max3_f32 v144, v144, v42, v43
	v_max3_f32 v145, v145, v44, v45
	v_max3_f32 v143, v143, v40, v41
	v_max3_f32 v142, v142, v46, v47
	v_max_f32_e32 v145, v145, v145
	v_max_f32_e32 v144, v144, v144
	v_max3_f32 v143, v143, v48, v49
	v_max_f32_e32 v144, v144, v145
	v_max3_f32 v142, v142, v143, v144
	v_cmp_lt_f32_e32 vcc, s5, v142
	s_cbranch_vccz .LBB0_464
	ds_bpermute_b32 v143, v161, v142
	s_andn2_b64 s[48:49], s[48:49], exec
	s_waitcnt lgkmcnt(0)
	v_max3_f32 v142, v142, v143, 0
	v_exp_f32_e64 v144, -v142
	v_add_f32_e32 v162, v162, v142
	v_pk_add_f32 v[50:51], v[50:51], v[142:143] op_sel_hi:[1,0] neg_lo:[0,1] neg_hi:[0,1]
	v_pk_add_f32 v[34:35], v[34:35], v[142:143] op_sel_hi:[1,0] neg_lo:[0,1] neg_hi:[0,1]
	v_pk_add_f32 v[52:53], v[52:53], v[142:143] op_sel_hi:[1,0] neg_lo:[0,1] neg_hi:[0,1]
	v_pk_add_f32 v[36:37], v[36:37], v[142:143] op_sel_hi:[1,0] neg_lo:[0,1] neg_hi:[0,1]
	v_pk_add_f32 v[54:55], v[54:55], v[142:143] op_sel_hi:[1,0] neg_lo:[0,1] neg_hi:[0,1]
	v_pk_add_f32 v[38:39], v[38:39], v[142:143] op_sel_hi:[1,0] neg_lo:[0,1] neg_hi:[0,1]
	v_pk_add_f32 v[56:57], v[56:57], v[142:143] op_sel_hi:[1,0] neg_lo:[0,1] neg_hi:[0,1]
	v_pk_add_f32 v[40:41], v[40:41], v[142:143] op_sel_hi:[1,0] neg_lo:[0,1] neg_hi:[0,1]
	v_pk_add_f32 v[58:59], v[58:59], v[142:143] op_sel_hi:[1,0] neg_lo:[0,1] neg_hi:[0,1]
	v_pk_add_f32 v[42:43], v[42:43], v[142:143] op_sel_hi:[1,0] neg_lo:[0,1] neg_hi:[0,1]
	v_pk_add_f32 v[60:61], v[60:61], v[142:143] op_sel_hi:[1,0] neg_lo:[0,1] neg_hi:[0,1]
	v_pk_add_f32 v[44:45], v[44:45], v[142:143] op_sel_hi:[1,0] neg_lo:[0,1] neg_hi:[0,1]
	v_pk_add_f32 v[62:63], v[62:63], v[142:143] op_sel_hi:[1,0] neg_lo:[0,1] neg_hi:[0,1]
	v_pk_add_f32 v[46:47], v[46:47], v[142:143] op_sel_hi:[1,0] neg_lo:[0,1] neg_hi:[0,1]
	v_pk_add_f32 v[64:65], v[64:65], v[142:143] op_sel_hi:[1,0] neg_lo:[0,1] neg_hi:[0,1]
	v_pk_add_f32 v[48:49], v[48:49], v[142:143] op_sel_hi:[1,0] neg_lo:[0,1] neg_hi:[0,1]
	v_pk_mul_f32 v[32:33], v[32:33], v[144:145] op_sel_hi:[1,0]
	v_pk_mul_f32 v[30:31], v[30:31], v[144:145] op_sel_hi:[1,0]
	v_pk_mul_f32 v[28:29], v[28:29], v[144:145] op_sel_hi:[1,0]
	v_pk_mul_f32 v[26:27], v[26:27], v[144:145] op_sel_hi:[1,0]
	v_pk_mul_f32 v[24:25], v[24:25], v[144:145] op_sel_hi:[1,0]
	v_pk_mul_f32 v[22:23], v[22:23], v[144:145] op_sel_hi:[1,0]
	v_pk_mul_f32 v[20:21], v[20:21], v[144:145] op_sel_hi:[1,0]
	v_pk_mul_f32 v[18:19], v[18:19], v[144:145] op_sel_hi:[1,0]
	v_pk_mul_f32 v[16:17], v[16:17], v[144:145] op_sel_hi:[1,0]
	v_pk_mul_f32 v[14:15], v[14:15], v[144:145] op_sel_hi:[1,0]
	v_pk_mul_f32 v[12:13], v[12:13], v[144:145] op_sel_hi:[1,0]
	v_pk_mul_f32 v[10:11], v[10:11], v[144:145] op_sel_hi:[1,0]
	v_pk_mul_f32 v[8:9], v[8:9], v[144:145] op_sel_hi:[1,0]
	v_pk_mul_f32 v[6:7], v[6:7], v[144:145] op_sel_hi:[1,0]
	v_pk_mul_f32 v[4:5], v[4:5], v[144:145] op_sel_hi:[1,0]
	v_pk_mul_f32 v[2:3], v[2:3], v[144:145] op_sel_hi:[1,0]
	v_mul_f32_e32 v136, v136, v144
.LBB0_464:
	v_exp_f32_e32 v147, v53
	v_exp_f32_e32 v149, v37
	v_exp_f32_e32 v145, v57
	v_exp_f32_e32 v53, v41
	v_exp_f32_e32 v143, v61
	v_exp_f32_e32 v45, v45
	v_exp_f32_e32 v37, v65
	v_exp_f32_e32 v41, v49
	v_exp_f32_e32 v146, v34
	v_exp_f32_e32 v152, v35
	v_exp_f32_e32 v153, v36
	v_exp_f32_e32 v144, v38
	v_exp_f32_e32 v150, v39
	v_exp_f32_e32 v151, v40
	v_exp_f32_e32 v142, v42
	v_exp_f32_e32 v38, v43
	v_exp_f32_e32 v39, v44
	v_exp_f32_e32 v36, v46
	v_exp_f32_e32 v34, v47
	v_exp_f32_e32 v35, v48
	v_exp_f32_e32 v148, v50
	v_exp_f32_e32 v50, v51
	v_exp_f32_e32 v51, v52
	v_exp_f32_e32 v52, v54
	v_exp_f32_e32 v48, v55
	v_exp_f32_e32 v49, v56
	v_exp_f32_e32 v44, v58
	v_exp_f32_e32 v46, v59
	v_exp_f32_e32 v47, v60
	v_exp_f32_e32 v40, v62
	v_exp_f32_e32 v42, v63
	v_exp_f32_e32 v43, v64
	s_setprio 1
	v_cvt_pk_bf16_f32 v58, v148, v50
	v_cvt_pk_bf16_f32 v59, v51, v147
	v_cvt_pk_bf16_f32 v60, v52, v48
	v_cvt_pk_bf16_f32 v61, v49, v145
	v_cvt_pk_bf16_f32 v246, v44, v46
	v_cvt_pk_bf16_f32 v247, v47, v143
	v_cvt_pk_bf16_f32 v248, v40, v42
	v_cvt_pk_bf16_f32 v249, v43, v37
	s_waitcnt lgkmcnt(0)
	v_mfma_f32_32x32x16_bf16 v[18:33], v[214:217], v[58:61], v[18:33]
	v_mfma_f32_32x32x16_bf16 v[2:17], v[218:221], v[58:61], v[2:17]
	v_cvt_pk_bf16_f32 v58, v146, v152
	v_cvt_pk_bf16_f32 v59, v153, v149
	v_cvt_pk_bf16_f32 v60, v144, v150
	v_cvt_pk_bf16_f32 v61, v151, v53
	v_mfma_f32_32x32x16_bf16 v[18:33], v[222:225], v[246:249], v[18:33]
	v_mfma_f32_32x32x16_bf16 v[2:17], v[226:229], v[246:249], v[2:17]
	v_cvt_pk_bf16_f32 v246, v142, v38
	v_cvt_pk_bf16_f32 v247, v39, v45
	v_cvt_pk_bf16_f32 v248, v36, v34
	v_cvt_pk_bf16_f32 v249, v35, v41
	v_mfma_f32_32x32x16_bf16 v[18:33], v[230:233], v[58:61], v[18:33]
	v_mfma_f32_32x32x16_bf16 v[2:17], v[234:237], v[58:61], v[2:17]
	v_mfma_f32_32x32x16_bf16 v[18:33], v[238:241], v[246:249], v[18:33]
	v_mfma_f32_32x32x16_bf16 v[2:17], v[242:245], v[246:249], v[2:17]
	s_setprio 0
	s_cmp_lg_u64 s[0:1], 0
	s_cbranch_scc0 .Lattn_w0
	s_waitcnt vmcnt(5)
	s_branch .Lattn_w1

; __device__ __forceinline__ void attn_tile(const u16* sb, const bf16x8 (&qa)[6], f32x16& o0, f32x16& o1, f32x16& lacc,
;                                           float& m, bool& mz, int r, int h, bool first) {
;     ...
;   float pa = 0.f, pb = 0.f, pc = 0.f, pd = 0.f;
; #pragma unroll
;   for (int i = 0; i < 16; ++i) {
;     s0[i] = __builtin_amdgcn_exp2f(s0[i]); s1[i] = __builtin_amdgcn_exp2f(s1[i]);
;     if ((i & 3) == 0) pa += s0[i] + s1[i];
;     else if ((i & 3) == 1) pb += s0[i] + s1[i];
;     else if ((i & 3) == 2) pc += s0[i] + s1[i];
;     else pd += s0[i] + s1[i];
;   }
;   lacc[0] += (pa + pb) + (pc + pd);
; __device__ void item_attn(PP p, int qb, int b, int hh, u16* lds) {
;     ...
;   for (int kt = 0; kt < ntiles; kt += 2) {
;     if (kt + 2 < ntiles) as_load(B, kg, vg, kt + 2);
;     attn_tile(lds, qa, oa0, oa1, lacc, ma, mz, r, h, kt == 0);
;     as_store(A, lds + ATT_STAGE, kl0, kl1, kl2, vl);
;     __syncthreads();
;     if (kt + 3 < ntiles) as_load(A, kg, vg, kt + 3);
;     if (kt + 1 < my_ntiles) attn_tile(lds + ATT_STAGE, qa, oa0, oa1, lacc, ma, mz, r, h, false);
;     if (kt + 2 < ntiles) as_store(B, lds, kl0, kl1, kl2, vl);
.Lattn_w1:
	s_cmp_ge_i32 s45, s44
	ds_write_b128 v0, v[98:101] offset:22528
	ds_write_b128 v154, v[102:105] offset:22528
	ds_write_b128 v155, v[110:113] offset:22528
	ds_write_b128 v156, v[118:121] offset:35840
	ds_write_b128 v156, v[126:129] offset:40448
	s_waitcnt lgkmcnt(0)
	s_barrier
	s_cbranch_scc1 .LBB0_466
	s_add_u32 s60, s42, 0x10000
	s_addc_u32 s61, s43, 0
	global_load_dwordx4 v[98:101], v134, s[60:61] offset:-4096
	global_load_dwordx4 v[102:105], v134, s[60:61]
	s_add_u32 s60, s42, 0x11000
	s_addc_u32 s61, s43, 0
	global_load_dwordx4 v[110:113], v134, s[60:61]
	s_add_u32 s60, s46, 0xb000
	s_addc_u32 s61, s47, 0
	global_load_dwordx4 v[118:121], v134, s[60:61] offset:-4096
	global_load_dwordx4 v[126:129], v134, s[60:61]
.LBB0_466:
	v_pk_add_f32 v[50:51], v[50:51], v[152:153]
	v_pk_add_f32 v[48:49], v[48:49], v[150:151]
	v_pk_add_f32 v[38:39], v[46:47], v[38:39]
	v_pk_add_f32 v[48:49], v[48:49], v[50:51]
	v_pk_add_f32 v[34:35], v[42:43], v[34:35]
	v_pk_add_f32 v[38:39], v[38:39], v[48:49]
	v_pk_add_f32 v[42:43], v[52:53], v[144:145]
	v_pk_add_f32 v[34:35], v[34:35], v[38:39]
	v_pk_add_f32 v[38:39], v[148:149], v[146:147]
	v_pk_add_f32 v[36:37], v[40:41], v[36:37]
	v_cmp_lt_i32_e32 vcc, s45, v165
	v_pk_add_f32 v[38:39], v[42:43], v[38:39]
	v_pk_add_f32 v[42:43], v[44:45], v[142:143]
	s_nop 0
	v_pk_add_f32 v[38:39], v[42:43], v[38:39]
	s_nop 0
	v_pk_add_f32 v[36:37], v[36:37], v[38:39]
	s_nop 0
	v_pk_add_f32 v[34:35], v[34:35], v[36:37]
	s_nop 0
	v_add_f32_e32 v34, v34, v35
	v_add_f32_e32 v136, v136, v34
	s_and_saveexec_b64 s[40:41], vcc
	s_cbranch_execz .LBB0_475
	ds_read_b128 v[214:217], v137 offset:22528
	ds_read_b128 v[218:221], v137 offset:29184
	ds_read_b128 v[222:225], v137 offset:22560
	ds_read_b128 v[226:229], v137 offset:29216
	ds_read_b128 v[230:233], v137 offset:22592
	ds_read_b128 v[234:237], v137 offset:29248
	ds_read_b128 v[238:241], v137 offset:22624
	ds_read_b128 v[242:245], v137 offset:29280
	ds_read_b128 v[246:249], v137 offset:22656
	ds_read_b128 v[250:253], v137 offset:29312
	ds_read_b128 v[142:145], v137 offset:22688
	ds_read_b128 v[146:149], v137 offset:29344
	s_setprio 1
	s_cmp_lg_u64 s[48:49], 0
	s_cbranch_scc1 .Lmz_o
	v_xor_b32_e32 v34, 0x80000000, v162
	v_mov_b32_e32 v35, v34
	v_mov_b32_e32 v36, v34
	v_mov_b32_e32 v37, v34
	v_mov_b32_e32 v38, v34
	v_mov_b32_e32 v39, v34
	v_mov_b32_e32 v40, v34
	v_mov_b32_e32 v41, v34
	v_mov_b32_e32 v42, v34
	v_mov_b32_e32 v43, v34
	v_mov_b32_e32 v44, v34
	v_mov_b32_e32 v45, v34
	v_mov_b32_e32 v46, v34
	v_mov_b32_e32 v47, v34
	v_mov_b32_e32 v48, v34
	v_mov_b32_e32 v49, v34
	s_waitcnt lgkmcnt(8)
	s_nop 0
	v_mfma_f32_32x32x16_bf16 v[50:65], v[214:217], v[66:69], v[34:49]
	v_mfma_f32_32x32x16_bf16 v[34:49], v[218:221], v[66:69], v[34:49]
	v_mfma_f32_32x32x16_bf16 v[50:65], v[222:225], v[70:73], v[50:65]
	v_mfma_f32_32x32x16_bf16 v[34:49], v[226:229], v[70:73], v[34:49]
	s_waitcnt lgkmcnt(4)
	v_mfma_f32_32x32x16_bf16 v[50:65], v[230:233], v[74:77], v[50:65]
	v_mfma_f32_32x32x16_bf16 v[34:49], v[234:237], v[74:77], v[34:49]
	v_mfma_f32_32x32x16_bf16 v[50:65], v[238:241], v[78:81], v[50:65]
	v_mfma_f32_32x32x16_bf16 v[34:49], v[242:245], v[78:81], v[34:49]
	s_waitcnt lgkmcnt(0)
	v_mfma_f32_32x32x16_bf16 v[50:65], v[246:249], v[82:85], v[50:65]
	v_mfma_f32_32x32x16_bf16 v[34:49], v[250:253], v[82:85], v[34:49]
	v_mfma_f32_32x32x16_bf16 v[50:65], v[142:145], v[86:89], v[50:65]
	v_mfma_f32_32x32x16_bf16 v[34:49], v[146:149], v[86:89], v[34:49]
	s_branch .Lqkd_o

; __device__ __forceinline__ void attn_tile(const u16* sb, const bf16x8 (&qa)[6], f32x16& o0, f32x16& o1, f32x16& lacc,
;                                           float& m, bool& mz, int r, int h, bool first) {
;     ...
;   float mxa = max3f(s0[0], s0[1], s0[2]), mxb = max3f(s0[3], s0[4], s0[5]);
;   float mxc = max3f(s0[6], s0[7], s0[8]), mxd = max3f(s0[9], s0[10], s0[11]);
;   mxa = max3f(mxa, s0[12], s0[13]); mxb = max3f(mxb, s0[14], s0[15]);
;   mxc = max3f(mxc, s1[0], s1[1]); mxd = max3f(mxd, s1[2], s1[3]);
;   mxa = max3f(mxa, s1[4], s1[5]); mxb = max3f(mxb, s1[6], s1[7]);
;   mxc = max3f(mxc, s1[8], s1[9]); mxd = max3f(mxd, s1[10], s1[11]);
;   mxa = max3f(mxa, s1[12], s1[13]); mxb = max3f(mxb, s1[14], s1[15]);
;   const float lm = max3f(mxa, mxb, fmaxf(mxc, mxd));
;   bool slow;
;   if (first) {
;     const float mx = fmaxf(lm, __shfl_xor(lm, 32));
;     slow = __any(mx > 30.f || mx < -30.f);
;   } else {
;     slow = __any(lm > 30.f);
;   }
;   if (slow) {
;     const float mx = fmaxf(lm, __shfl_xor(lm, 32));
;     const float d = first ? mx : fmaxf(mx, 0.f);
;     const float alpha = first ? 1.f : __builtin_amdgcn_exp2f(-d);
;     m += d;
;     mz = false;
; #pragma unroll
;     for (int i = 0; i < 16; ++i) { s0[i] -= d; s1[i] -= d; o0[i] *= alpha; o1[i] *= alpha; }
;     lacc[0] *= alpha;
;   }
.Lqkd_o:
	ds_read_b128 v[214:217], v163 offset:35840
	ds_read_b128 v[218:221], v163 offset:40448
	ds_read_b128 v[222:225], v163 offset:35872
	ds_read_b128 v[226:229], v163 offset:40480
	ds_read_b128 v[230:233], v163 offset:35904
	ds_read_b128 v[234:237], v163 offset:40512
	ds_read_b128 v[238:241], v163 offset:35936
	ds_read_b128 v[242:245], v163 offset:40544
	s_nop 1
	s_setprio 0
	v_max3_f32 v138, v50, v51, v52
	v_max3_f32 v140, v56, v57, v58
	v_max3_f32 v141, v59, v60, v61
	v_max3_f32 v139, v53, v54, v55
	v_max3_f32 v138, v138, v62, v63
	v_max3_f32 v140, v140, v34, v35
	v_max3_f32 v141, v141, v36, v37
	v_max3_f32 v139, v139, v64, v65
	v_max3_f32 v138, v138, v38, v39
	v_max3_f32 v140, v140, v42, v43
	v_max3_f32 v141, v141, v44, v45
	v_max3_f32 v139, v139, v40, v41
	v_max3_f32 v138, v138, v46, v47
	v_max_f32_e32 v141, v141, v141
	v_max_f32_e32 v140, v140, v140
	v_max3_f32 v139, v139, v48, v49
	v_max_f32_e32 v140, v140, v141
	v_max3_f32 v138, v138, v139, v140
	v_cmp_lt_f32_e32 vcc, s5, v138
	s_cbranch_vccz .LBB0_473
	ds_bpermute_b32 v139, v161, v138
	s_andn2_b64 s[50:51], s[48:49], exec
	s_waitcnt lgkmcnt(0)
	v_max3_f32 v138, v138, v139, 0
	v_exp_f32_e64 v140, -v138
	v_add_f32_e32 v162, v162, v138
	v_pk_add_f32 v[50:51], v[50:51], v[138:139] op_sel_hi:[1,0] neg_lo:[0,1] neg_hi:[0,1]
	v_pk_add_f32 v[34:35], v[34:35], v[138:139] op_sel_hi:[1,0] neg_lo:[0,1] neg_hi:[0,1]
	v_pk_add_f32 v[52:53], v[52:53], v[138:139] op_sel_hi:[1,0] neg_lo:[0,1] neg_hi:[0,1]
	v_pk_add_f32 v[36:37], v[36:37], v[138:139] op_sel_hi:[1,0] neg_lo:[0,1] neg_hi:[0,1]
	v_pk_add_f32 v[54:55], v[54:55], v[138:139] op_sel_hi:[1,0] neg_lo:[0,1] neg_hi:[0,1]
	v_pk_add_f32 v[38:39], v[38:39], v[138:139] op_sel_hi:[1,0] neg_lo:[0,1] neg_hi:[0,1]
	v_pk_add_f32 v[56:57], v[56:57], v[138:139] op_sel_hi:[1,0] neg_lo:[0,1] neg_hi:[0,1]
	v_pk_add_f32 v[40:41], v[40:41], v[138:139] op_sel_hi:[1,0] neg_lo:[0,1] neg_hi:[0,1]
	v_pk_add_f32 v[58:59], v[58:59], v[138:139] op_sel_hi:[1,0] neg_lo:[0,1] neg_hi:[0,1]
	v_pk_add_f32 v[42:43], v[42:43], v[138:139] op_sel_hi:[1,0] neg_lo:[0,1] neg_hi:[0,1]
	v_pk_add_f32 v[60:61], v[60:61], v[138:139] op_sel_hi:[1,0] neg_lo:[0,1] neg_hi:[0,1]
	v_pk_add_f32 v[44:45], v[44:45], v[138:139] op_sel_hi:[1,0] neg_lo:[0,1] neg_hi:[0,1]
	v_pk_add_f32 v[62:63], v[62:63], v[138:139] op_sel_hi:[1,0] neg_lo:[0,1] neg_hi:[0,1]
	v_pk_add_f32 v[46:47], v[46:47], v[138:139] op_sel_hi:[1,0] neg_lo:[0,1] neg_hi:[0,1]
	v_pk_add_f32 v[64:65], v[64:65], v[138:139] op_sel_hi:[1,0] neg_lo:[0,1] neg_hi:[0,1]
	v_pk_add_f32 v[48:49], v[48:49], v[138:139] op_sel_hi:[1,0] neg_lo:[0,1] neg_hi:[0,1]
	v_pk_mul_f32 v[32:33], v[32:33], v[140:141] op_sel_hi:[1,0]
	v_pk_mul_f32 v[30:31], v[30:31], v[140:141] op_sel_hi:[1,0]
	v_pk_mul_f32 v[28:29], v[28:29], v[140:141] op_sel_hi:[1,0]
	v_pk_mul_f32 v[26:27], v[26:27], v[140:141] op_sel_hi:[1,0]
	v_pk_mul_f32 v[24:25], v[24:25], v[140:141] op_sel_hi:[1,0]
	v_pk_mul_f32 v[22:23], v[22:23], v[140:141] op_sel_hi:[1,0]
	v_pk_mul_f32 v[20:21], v[20:21], v[140:141] op_sel_hi:[1,0]
	v_pk_mul_f32 v[18:19], v[18:19], v[140:141] op_sel_hi:[1,0]
	v_pk_mul_f32 v[16:17], v[16:17], v[140:141] op_sel_hi:[1,0]
	v_pk_mul_f32 v[14:15], v[14:15], v[140:141] op_sel_hi:[1,0]
	v_pk_mul_f32 v[12:13], v[12:13], v[140:141] op_sel_hi:[1,0]
	v_pk_mul_f32 v[10:11], v[10:11], v[140:141] op_sel_hi:[1,0]
	v_pk_mul_f32 v[8:9], v[8:9], v[140:141] op_sel_hi:[1,0]
	v_pk_mul_f32 v[6:7], v[6:7], v[140:141] op_sel_hi:[1,0]
	v_pk_mul_f32 v[4:5], v[4:5], v[140:141] op_sel_hi:[1,0]
	v_pk_mul_f32 v[2:3], v[2:3], v[140:141] op_sel_hi:[1,0]
	v_mul_f32_e32 v136, v136, v140
	s_branch .LBB0_474

; __device__ __forceinline__ void attn_tile(const u16* sb, const bf16x8 (&qa)[6], f32x16& o0, f32x16& o1, f32x16& lacc,
;                                           float& m, bool& mz, int r, int h, bool first) {
;     ...
;   float pa = 0.f, pb = 0.f, pc = 0.f, pd = 0.f;
; #pragma unroll
;   for (int i = 0; i < 16; ++i) {
;     s0[i] = __builtin_amdgcn_exp2f(s0[i]); s1[i] = __builtin_amdgcn_exp2f(s1[i]);
;     if ((i & 3) == 0) pa += s0[i] + s1[i];
;     else if ((i & 3) == 1) pb += s0[i] + s1[i];
;     else if ((i & 3) == 2) pc += s0[i] + s1[i];
;     else pd += s0[i] + s1[i];
;   }
;   lacc[0] += (pa + pb) + (pc + pd);
;   const u16* vp = sb + 64 * KLD + r * VLD + 8 * h;
;   __builtin_amdgcn_s_setprio(1);
; #pragma unroll
;   for (int kb = 0; kb < 2; ++kb) {
; #pragma unroll
;     for (int s = 0; s < 2; ++s) {
;       const bf16x8 pf = pack_p(kb == 0 ? s0 : s1, 8 * s);
;       const int koff = kb * 32 + 16 * s;
;       const bf16x8 v0 = *(const bf16x8*)(vp + koff);
;       const bf16x8 v1 = *(const bf16x8*)(vp + 32 * VLD + koff);
;       o0 = mfma32(v0, pf, o0);
;       o1 = mfma32(v1, pf, o1);
;     }
;   }
;   __builtin_amdgcn_s_setprio(0);
.LBB0_474:
	v_exp_f32_e32 v148, v35
	v_exp_f32_e32 v149, v36
	v_exp_f32_e32 v142, v38
	v_exp_f32_e32 v150, v39
	v_exp_f32_e32 v38, v51
	v_exp_f32_e32 v39, v52
	v_exp_f32_e32 v139, v53
	v_exp_f32_e32 v53, v41
	v_exp_f32_e32 v151, v40
	v_exp_f32_e32 v40, v55
	v_exp_f32_e32 v41, v56
	v_exp_f32_e32 v144, v42
	v_exp_f32_e32 v42, v43
	v_exp_f32_e32 v43, v44
	v_exp_f32_e32 v140, v50
	v_exp_f32_e32 v50, v59
	v_exp_f32_e32 v51, v60
	v_exp_f32_e32 v146, v46
	v_exp_f32_e32 v46, v47
	v_exp_f32_e32 v47, v48
	v_exp_f32_e32 v52, v54
	v_exp_f32_e32 v54, v63
	v_exp_f32_e32 v55, v64
	v_exp_f32_e32 v141, v37
	v_exp_f32_e32 v138, v34
	v_pk_add_f32 v[34:35], v[38:39], v[148:149]
	v_exp_f32_e32 v143, v57
	v_pk_add_f32 v[36:37], v[40:41], v[150:151]
	v_exp_f32_e32 v145, v61
	v_exp_f32_e32 v45, v45
	v_exp_f32_e32 v44, v58
	v_pk_add_f32 v[34:35], v[36:37], v[34:35]
	v_pk_add_f32 v[36:37], v[50:51], v[42:43]
	v_exp_f32_e32 v147, v65
	v_exp_f32_e32 v49, v49
	v_exp_f32_e32 v48, v62
	v_pk_add_f32 v[34:35], v[36:37], v[34:35]
	v_pk_add_f32 v[36:37], v[54:55], v[46:47]
	v_pk_add_f32 v[56:57], v[52:53], v[142:143]
	v_pk_add_f32 v[34:35], v[36:37], v[34:35]
	v_pk_add_f32 v[36:37], v[140:141], v[138:139]
	s_nop 0
	s_nop 0
	v_pk_add_f32 v[36:37], v[56:57], v[36:37]
	v_pk_add_f32 v[56:57], v[44:45], v[144:145]
	s_nop 0
	v_pk_add_f32 v[36:37], v[56:57], v[36:37]
	v_pk_add_f32 v[56:57], v[48:49], v[146:147]
	s_nop 0
	v_pk_add_f32 v[36:37], v[56:57], v[36:37]
	s_nop 0
	v_pk_add_f32 v[34:35], v[34:35], v[36:37]
	s_nop 0
	v_add_f32_e32 v34, v34, v35
	v_add_f32_e32 v136, v136, v34
	s_setprio 1
	v_cvt_pk_bf16_f32 v38, v140, v38
	v_cvt_pk_bf16_f32 v39, v39, v139
	v_cvt_pk_bf16_f32 v40, v52, v40
	v_cvt_pk_bf16_f32 v41, v41, v143
	v_cvt_pk_bf16_f32 v246, v44, v50
	v_cvt_pk_bf16_f32 v247, v51, v145
	v_cvt_pk_bf16_f32 v248, v48, v54
	v_cvt_pk_bf16_f32 v249, v55, v147
	s_waitcnt lgkmcnt(0)
	v_mfma_f32_32x32x16_bf16 v[18:33], v[214:217], v[38:41], v[18:33]
	v_mfma_f32_32x32x16_bf16 v[2:17], v[218:221], v[38:41], v[2:17]
	v_cvt_pk_bf16_f32 v38, v138, v148
	v_cvt_pk_bf16_f32 v39, v149, v141
	v_cvt_pk_bf16_f32 v40, v142, v150
	v_cvt_pk_bf16_f32 v41, v151, v53
	v_mfma_f32_32x32x16_bf16 v[18:33], v[222:225], v[246:249], v[18:33]
	v_mfma_f32_32x32x16_bf16 v[2:17], v[226:229], v[246:249], v[2:17]
	v_cvt_pk_bf16_f32 v246, v144, v42
	v_cvt_pk_bf16_f32 v247, v43, v45
	v_cvt_pk_bf16_f32 v248, v146, v46
	v_cvt_pk_bf16_f32 v249, v47, v49
	v_mfma_f32_32x32x16_bf16 v[18:33], v[230:233], v[38:41], v[18:33]
	v_mfma_f32_32x32x16_bf16 v[2:17], v[234:237], v[38:41], v[2:17]
	v_mfma_f32_32x32x16_bf16 v[18:33], v[238:241], v[246:249], v[18:33]
	v_mfma_f32_32x32x16_bf16 v[2:17], v[242:245], v[246:249], v[2:17]
	s_setprio 0
	s_andn2_b64 s[48:49], s[48:49], exec
	s_and_b64 s[50:51], s[50:51], exec
	s_or_b64 s[48:49], s[48:49], s[50:51]

; __device__ __forceinline__ void gemm_kstep(const u16* sb, int wn, int wt, int r, int h, f32x16 (&acc)[2][2]) {
;   const u16* bw = sb + (wn * 64 + r) * LDT + h * 8;
;   const u16* bx = sb + TILE_U16 + (wt * 64 + r) * LDT + h * 8;
;   __builtin_amdgcn_s_setprio(1);
; #pragma unroll
;   for (int ks = 0; ks < 4; ++ks) {
;     bf16x8 a0 = *(const bf16x8*)(bw + ks * 16);
;     bf16x8 a1 = *(const bf16x8*)(bw + 32 * LDT + ks * 16);
;     bf16x8 b0 = *(const bf16x8*)(bx + ks * 16);
;     bf16x8 b1 = *(const bf16x8*)(bx + 32 * LDT + ks * 16);
;     acc[0][0] = mfma32(a0, b0, acc[0][0]);
;     acc[0][1] = mfma32(a0, b1, acc[0][1]);
;     acc[1][0] = mfma32(a1, b0, acc[1][0]);
;     acc[1][1] = mfma32(a1, b1, acc[1][1]);
;   }
;   __builtin_amdgcn_s_setprio(0);
; __device__ void gemm_phase(const u16* __restrict__ Wb, int ldw, const u16* __restrict__ Xb, int ldx, int K,
;                            u16* __restrict__ outb, int ldo, int ntn, int ntiles, u16* lds) {
;     ...
;       gemm_kstep(lds + 2 * TILE_U16, wn, wt, r, h, acc);
;       if (kt + 2 < nk) gs_store(B, lds, lo);
;       __syncthreads();
;     }
;     stage_bf16(lds, acc);
;     __syncthreads();
;     u16* out = outb + (size_t)GP_MT(q) * 128 * ldo + GP_NT(q) * 128;
; #pragma unroll
;     for (int i = 0; i < 8; ++i) {
;       const int id = tid + 256 * i;
;       const int row = id >> 4, c = id & 15;
;       uint4 v = *(const uint4*)(lds + row * 136 + c * 8);
;       *(uint4*)(out + (size_t)row * ldo + c * 8) = v;
;     }
;     __syncthreads();
.LBB0_597:
	s_setprio 1
	ds_read_b128 v[158:161], v140 offset:36864
	ds_read_b128 v[162:165], v141 offset:55296
	ds_read_b128 v[166:169], v141 offset:59904
	ds_read_b128 v[214:217], v140 offset:41472
	ds_read_b128 v[218:221], v140 offset:36896
	ds_read_b128 v[222:225], v141 offset:55328
	ds_read_b128 v[226:229], v141 offset:59936
	ds_read_b128 v[230:233], v140 offset:41504
	s_waitcnt lgkmcnt(4)
	v_mfma_f32_32x32x16_bf16 v[50:65], v[158:161], v[162:165], v[50:65]
	v_mfma_f32_32x32x16_bf16 v[34:49], v[158:161], v[166:169], v[34:49]
	v_mfma_f32_32x32x16_bf16 v[18:33], v[214:217], v[162:165], v[18:33]
	v_mfma_f32_32x32x16_bf16 v[2:17], v[214:217], v[166:169], v[2:17]
	ds_read_b128 v[158:161], v140 offset:36928
	ds_read_b128 v[162:165], v141 offset:55360
	ds_read_b128 v[166:169], v141 offset:59968
	ds_read_b128 v[214:217], v140 offset:41536
	s_waitcnt lgkmcnt(4)
	v_mfma_f32_32x32x16_bf16 v[50:65], v[218:221], v[222:225], v[50:65]
	v_mfma_f32_32x32x16_bf16 v[34:49], v[218:221], v[226:229], v[34:49]
	v_mfma_f32_32x32x16_bf16 v[18:33], v[230:233], v[222:225], v[18:33]
	v_mfma_f32_32x32x16_bf16 v[2:17], v[230:233], v[226:229], v[2:17]
	ds_read_b128 v[218:221], v140 offset:36960
	ds_read_b128 v[222:225], v141 offset:55392
	ds_read_b128 v[226:229], v141 offset:60000
	ds_read_b128 v[230:233], v140 offset:41568
	s_waitcnt lgkmcnt(4)
	v_mfma_f32_32x32x16_bf16 v[50:65], v[158:161], v[162:165], v[50:65]
	v_mfma_f32_32x32x16_bf16 v[34:49], v[158:161], v[166:169], v[34:49]
	v_mfma_f32_32x32x16_bf16 v[18:33], v[214:217], v[162:165], v[18:33]
	v_mfma_f32_32x32x16_bf16 v[2:17], v[214:217], v[166:169], v[2:17]
	s_waitcnt lgkmcnt(0)
	v_mfma_f32_32x32x16_bf16 v[50:65], v[218:221], v[222:225], v[50:65]
	v_mfma_f32_32x32x16_bf16 v[34:49], v[218:221], v[226:229], v[34:49]
	v_mfma_f32_32x32x16_bf16 v[18:33], v[230:233], v[222:225], v[18:33]
	v_mfma_f32_32x32x16_bf16 v[2:17], v[230:233], v[226:229], v[2:17]
	s_setprio 0
	s_and_b32 s0, s39, 0xffff
	s_mul_i32 s0, s0, 0xe38f
	s_lshr_b32 s0, s0, 23
	v_mov_b32_e32 v158, v174
	s_lshl_b32 s1, s0, 3
	s_mulk_i32 s0, 0x90
	s_barrier
	s_sub_i32 s0, s39, s0
	v_lshrrev_b32_e32 v160, 2, v158
	v_and_b32_e32 v160, 8, v160
	s_add_i32 s1, s18, s1
	s_and_b32 s39, s0, 0xffff
	s_and_b32 s0, s0, 7
	v_and_b32_e32 v159, 0x5f, v158
	v_and_or_b32 v158, v158, s29, v160
	s_or_b32 s0, s1, s0
	v_mad_u32_u24 v158, v159, s28, v158
	s_mul_hi_u32 s1, s0, 0x90000
	s_mul_i32 s0, s0, 0x90000
	v_cvt_pk_bf16_f32 v53, v52, v53
	v_cvt_pk_bf16_f32 v52, v50, v51
	v_cvt_pk_bf16_f32 v51, v56, v57
	v_cvt_pk_bf16_f32 v50, v54, v55
	v_cvt_pk_bf16_f32 v37, v36, v37
	v_cvt_pk_bf16_f32 v36, v34, v35
	v_cvt_pk_bf16_f32 v35, v40, v41
	v_cvt_pk_bf16_f32 v34, v38, v39
	v_add_u32_e32 v38, 0x2000, v158
	v_cvt_pk_bf16_f32 v21, v20, v21
	v_cvt_pk_bf16_f32 v20, v18, v19
	v_cvt_pk_bf16_f32 v19, v24, v25
	v_cvt_pk_bf16_f32 v18, v22, v23
	v_cvt_pk_bf16_f32 v5, v4, v5
	v_cvt_pk_bf16_f32 v4, v2, v3
	v_cvt_pk_bf16_f32 v3, v8, v9
	v_cvt_pk_bf16_f32 v2, v6, v7
	s_add_u32 s0, s42, s0
	ds_write2_b64 v158, v[52:53], v[50:51] offset1:2
	v_cvt_pk_bf16_f32 v51, v60, v61
	v_cvt_pk_bf16_f32 v50, v58, v59
	v_cvt_pk_bf16_f32 v53, v64, v65
	v_cvt_pk_bf16_f32 v52, v62, v63
	ds_write2_b64 v38, v[36:37], v[34:35] offset0:64 offset1:66
	v_cvt_pk_bf16_f32 v35, v44, v45
	v_cvt_pk_bf16_f32 v34, v42, v43
	v_cvt_pk_bf16_f32 v37, v48, v49
	v_cvt_pk_bf16_f32 v36, v46, v47
	ds_write2_b64 v158, v[20:21], v[18:19] offset0:8 offset1:10
	v_cvt_pk_bf16_f32 v19, v28, v29
	v_cvt_pk_bf16_f32 v18, v26, v27
	v_cvt_pk_bf16_f32 v21, v32, v33
	v_cvt_pk_bf16_f32 v20, v30, v31
	ds_write2_b64 v38, v[4:5], v[2:3] offset0:72 offset1:74
	v_cvt_pk_bf16_f32 v3, v12, v13
	v_cvt_pk_bf16_f32 v2, v10, v11
	v_cvt_pk_bf16_f32 v5, v16, v17
	v_cvt_pk_bf16_f32 v4, v14, v15
	s_addc_u32 s1, s43, s1
	s_lshl_b32 s39, s39, 5
	ds_write2_b64 v158, v[50:51], v[52:53] offset0:4 offset1:6
	ds_write2_b64 v38, v[34:35], v[36:37] offset0:68 offset1:70
	ds_write2_b64 v158, v[18:19], v[20:21] offset0:12 offset1:14
	ds_write2_b64 v38, v[2:3], v[4:5] offset0:76 offset1:78
	s_waitcnt lgkmcnt(0)
	s_barrier
	s_and_b32 s39, s39, 0x1f00
	ds_read_b128 v[2:5], v190
	ds_read_b128 v[6:9], v191
	s_add_u32 s0, s0, s39
	s_addc_u32 s1, s1, 0
	v_lshl_add_u64 v[14:15], s[0:1], 0, v[0:1]
	v_lshl_add_u64 v[10:11], v[14:15], 0, v[142:143]
	s_waitcnt lgkmcnt(1)
	global_store_dwordx4 v[10:11], v[2:5], off
	ds_read_b128 v[2:5], v192
	v_lshl_add_u64 v[10:11], v[14:15], 0, v[144:145]
	s_waitcnt lgkmcnt(1)
	global_store_dwordx4 v[10:11], v[6:9], off
	ds_read_b128 v[6:9], v193
	v_lshl_add_u64 v[10:11], v[14:15], 0, v[146:147]
	s_waitcnt lgkmcnt(1)
	global_store_dwordx4 v[10:11], v[2:5], off
	ds_read_b128 v[2:5], v194
	v_lshl_add_u64 v[10:11], v[14:15], 0, v[148:149]
	s_waitcnt lgkmcnt(1)
	global_store_dwordx4 v[10:11], v[6:9], off
	v_lshl_add_u64 v[10:11], v[14:15], 0, v[150:151]
	ds_read_b128 v[6:9], v195
	s_waitcnt lgkmcnt(1)
	global_store_dwordx4 v[10:11], v[2:5], off
	ds_read_b128 v[2:5], v196
	ds_read_b128 v[10:13], v197
	v_lshl_add_u64 v[16:17], v[14:15], 0, v[152:153]
	s_waitcnt lgkmcnt(2)
	global_store_dwordx4 v[16:17], v[6:9], off
	s_and_b64 vcc, exec, s[16:17]
	s_mov_b32 s39, s38
	v_lshl_add_u64 v[6:7], v[14:15], 0, v[154:155]
	s_waitcnt lgkmcnt(1)
	global_store_dwordx4 v[6:7], v[2:5], off
	s_nop 1
	v_lshl_add_u64 v[2:3], v[14:15], 0, v[156:157]
	s_waitcnt lgkmcnt(0)
	global_store_dwordx4 v[2:3], v[10:13], off
	s_barrier
	s_cbranch_vccnz .LBB0_602
; __device__ void gemm_phase(const u16* __restrict__ Wb, int ldw, const u16* __restrict__ Xb, int ldx, int K,
;                            u16* __restrict__ outb, int ldo, int ntn, int ntiles, u16* lds) {
;     ...
;   for (; q < L; q += nbl) {
;     const int qn = q + nbl;
;     const bool has_next = qn < L;
;     const int qq = has_next ? qn : q;
;     const u16* gwn = Wb + (size_t)(GP_NT(qq) * 128 + lrow) * ldw + lc * 8;
;     const u16* gxn = Xb + (size_t)(GP_MT(qq) * 128 + lrow) * ldx + lc * 8;
;     f32x16 acc[2][2];
; #pragma unroll
;     for (int a = 0; a < 2; ++a)
; #pragma unroll
;       for (int b = 0; b < 2; ++b)
; #pragma unroll
;         for (int i = 0; i < 16; ++i) acc[a][b][i] = 0.f;
;     gs_store(B, lds, lo);
;     __syncthreads();
;     for (int kt = 0; kt < nk; kt += 2) {
;       if (kt + 2 < nk) gs_load(B, gw, ldw, gx, ldx, (kt + 2) * 64);
;       else if (has_next) gs_load(B, gwn, ldw, gxn, ldx, 0);
;       gemm_kstep(lds, wn, wt, r, h, acc);
;       gs_store(A, lds + 2 * TILE_U16, lo);
;       __syncthreads();
;       if (kt + 3 < nk) gs_load(A, gw, ldw, gx, ldx, (kt + 3) * 64);
.LBB0_598:
	v_mov_b64_e32 v[160:161], v[132:133]
	v_add_co_u32_e32 v162, vcc, s81, v160
	v_mov_b64_e32 v[158:159], v[134:135]
	s_nop 0
	v_addc_co_u32_e32 v163, vcc, 0, v161, vcc
	v_add_co_u32_e32 v164, vcc, s80, v160
	s_waitcnt vmcnt(1)
	ds_write_b128 v188, v[98:101]
	ds_write_b128 v188, v[102:105] offset:4608
	ds_write_b128 v188, v[106:109] offset:9216
	ds_write_b128 v188, v[110:113] offset:13824
	ds_write_b128 v188, v[114:117] offset:18432
	ds_write_b128 v188, v[118:121] offset:23040
	ds_write_b128 v188, v[122:125] offset:27648
	ds_write_b128 v188, v[126:129] offset:32256
	v_addc_co_u32_e32 v165, vcc, 0, v161, vcc
	v_add_co_u32_e32 v166, vcc, s84, v160
	s_waitcnt lgkmcnt(0)
	s_nop 0
	v_addc_co_u32_e32 v167, vcc, 0, v161, vcc
	v_add_co_u32_e32 v168, vcc, s81, v158
	s_barrier
	s_nop 0
	v_addc_co_u32_e32 v169, vcc, 0, v159, vcc
	v_add_co_u32_e32 v170, vcc, s80, v158
	s_nop 1
	v_addc_co_u32_e32 v171, vcc, 0, v159, vcc
	v_add_co_u32_e32 v172, vcc, s84, v158
	global_load_dwordx4 v[98:101], v[160:161], off offset:256
	global_load_dwordx4 v[102:105], v[162:163], off offset:256
	v_addc_co_u32_e32 v173, vcc, 0, v159, vcc
	global_load_dwordx4 v[106:109], v[164:165], off offset:256
	global_load_dwordx4 v[110:113], v[166:167], off offset:256
	global_load_dwordx4 v[114:117], v[158:159], off offset:256
	global_load_dwordx4 v[118:121], v[168:169], off offset:256
	global_load_dwordx4 v[122:125], v[170:171], off offset:256
	global_load_dwordx4 v[126:129], v[172:173], off offset:256
	s_add_i32 s38, s39, s87
	s_cmpk_gt_u32 s38, 0x23f
	s_cselect_b64 s[16:17], -1, 0
	s_cmpk_lt_u32 s38, 0x240
	s_cselect_b64 s[0:1], -1, 0
	s_and_b64 s[40:41], s[0:1], exec
	s_cselect_b32 s40, s38, s39
	s_mul_hi_u32 s41, s40, 0x38e38e39
	s_lshr_b32 s41, s41, 5
	s_mul_i32 s44, s41, 0x90
	s_sub_i32 s40, s40, s44
	s_lshl_b32 s44, s40, 4
	s_and_b32 s40, s40, 7
	s_or_b32 s40, s40, s18
	s_lshl_b32 s41, s41, 10
	s_lshl_b32 s40, s40, 7
	s_and_b32 s44, s44, 0xf80
	s_add_i32 s40, s40, s41
	v_add_u32_e32 v2, s44, v131
	v_add_u32_e32 v4, s40, v131
	v_ashrrev_i32_e32 v3, 31, v2
	v_ashrrev_i32_e32 v5, 31, v4
	v_lshlrev_b64 v[2:3], 11, v[2:3]
	v_lshlrev_b64 v[4:5], 11, v[4:5]
	v_lshl_add_u64 v[132:133], v[136:137], 0, v[2:3]
	v_lshl_add_u64 v[134:135], v[138:139], 0, v[4:5]
	s_setprio 1
	ds_read_b128 v[2:5], v140
	ds_read_b128 v[6:9], v141 offset:18432
	ds_read_b128 v[10:13], v141 offset:23040
	s_waitcnt lgkmcnt(1)
	v_mfma_f32_32x32x16_bf16 v[50:65], v[2:5], v[6:9], 0
	s_waitcnt lgkmcnt(0)
	v_mfma_f32_32x32x16_bf16 v[34:49], v[2:5], v[10:13], 0
	ds_read_b128 v[2:5], v140 offset:4608
	ds_read_b128 v[198:201], v140 offset:32
	ds_read_b128 v[202:205], v141 offset:18464
	ds_read_b128 v[206:209], v141 offset:23072
	s_waitcnt lgkmcnt(1)
	v_mfma_f32_32x32x16_bf16 v[50:65], v[198:201], v[202:205], v[50:65]
	s_waitcnt lgkmcnt(0)
	v_mfma_f32_32x32x16_bf16 v[34:49], v[198:201], v[206:209], v[34:49]
	ds_read_b128 v[198:201], v140 offset:4640
	v_mfma_f32_32x32x16_bf16 v[18:33], v[2:5], v[6:9], 0
	v_mfma_f32_32x32x16_bf16 v[2:17], v[2:5], v[10:13], 0
	s_waitcnt lgkmcnt(0)
	v_mfma_f32_32x32x16_bf16 v[18:33], v[198:201], v[202:205], v[18:33]
	v_mfma_f32_32x32x16_bf16 v[2:17], v[198:201], v[206:209], v[2:17]
	ds_read_b128 v[198:201], v140 offset:64
	ds_read_b128 v[202:205], v141 offset:18496
	ds_read_b128 v[206:209], v141 offset:23104
	s_waitcnt lgkmcnt(1)
	v_mfma_f32_32x32x16_bf16 v[50:65], v[198:201], v[202:205], v[50:65]
	s_waitcnt lgkmcnt(0)
	v_mfma_f32_32x32x16_bf16 v[34:49], v[198:201], v[206:209], v[34:49]
	ds_read_b128 v[198:201], v140 offset:4672
	s_waitcnt lgkmcnt(0)
	v_mfma_f32_32x32x16_bf16 v[18:33], v[198:201], v[202:205], v[18:33]
	v_mfma_f32_32x32x16_bf16 v[2:17], v[198:201], v[206:209], v[2:17]
	ds_read_b128 v[198:201], v140 offset:96
	ds_read_b128 v[202:205], v141 offset:18528
	ds_read_b128 v[206:209], v141 offset:23136
	s_waitcnt lgkmcnt(1)
	v_mfma_f32_32x32x16_bf16 v[50:65], v[198:201], v[202:205], v[50:65]
	s_waitcnt lgkmcnt(0)
	v_mfma_f32_32x32x16_bf16 v[34:49], v[198:201], v[206:209], v[34:49]
	ds_read_b128 v[198:201], v140 offset:4704
	s_waitcnt lgkmcnt(0)
	v_mfma_f32_32x32x16_bf16 v[18:33], v[198:201], v[202:205], v[18:33]
	v_mfma_f32_32x32x16_bf16 v[2:17], v[198:201], v[206:209], v[2:17]
	s_setprio 0
	ds_write_b128 v188, v[66:69] offset:36864
	ds_write_b128 v188, v[70:73] offset:41472
	ds_write_b128 v188, v[74:77] offset:46080
	ds_write_b128 v188, v[78:81] offset:50688
	ds_write_b128 v188, v[82:85] offset:55296
	ds_write_b128 v188, v[86:89] offset:59904
	ds_write_b128 v188, v[90:93] offset:64512
	s_waitcnt vmcnt(8)
	ds_write_b128 v189, v[94:97] offset:13824
	s_waitcnt lgkmcnt(0)
	s_barrier
; __device__ void gemm_phase(const u16* __restrict__ Wb, int ldw, const u16* __restrict__ Xb, int ldx, int K,
;                            u16* __restrict__ outb, int ldo, int ntn, int ntiles, u16* lds) {
;     ...
;     for (int kt = 0; kt < nk; kt += 2) {
;       if (kt + 2 < nk) gs_load(B, gw, ldw, gx, ldx, (kt + 2) * 64);
;       else if (has_next) gs_load(B, gwn, ldw, gxn, ldx, 0);
;       gemm_kstep(lds, wn, wt, r, h, acc);
;       gs_store(A, lds + 2 * TILE_U16, lo);
;       __syncthreads();
;       if (kt + 3 < nk) gs_load(A, gw, ldw, gx, ldx, (kt + 3) * 64);
;       else if (has_next) gs_load(A, gwn, ldw, gxn, ldx, 64);
;       gemm_kstep(lds + 2 * TILE_U16, wn, wt, r, h, acc);
;       if (kt + 2 < nk) gs_store(B, lds, lo);
;       __syncthreads();
	global_load_dwordx4 v[66:69], v[160:161], off offset:384
	global_load_dwordx4 v[70:73], v[162:163], off offset:384
	global_load_dwordx4 v[74:77], v[164:165], off offset:384
	global_load_dwordx4 v[78:81], v[166:167], off offset:384
	global_load_dwordx4 v[82:85], v[158:159], off offset:384
	global_load_dwordx4 v[86:89], v[168:169], off offset:384
	global_load_dwordx4 v[90:93], v[170:171], off offset:384
	global_load_dwordx4 v[94:97], v[172:173], off offset:384
	s_setprio 1
	ds_read_b128 v[198:201], v140 offset:36864
	ds_read_b128 v[202:205], v141 offset:55296
	ds_read_b128 v[206:209], v141 offset:59904
	ds_read_b128 v[214:217], v140 offset:41472
	ds_read_b128 v[218:221], v140 offset:36896
	ds_read_b128 v[222:225], v141 offset:55328
	ds_read_b128 v[226:229], v141 offset:59936
	ds_read_b128 v[230:233], v140 offset:41504
	s_waitcnt lgkmcnt(4)
	v_mfma_f32_32x32x16_bf16 v[50:65], v[198:201], v[202:205], v[50:65]
	v_mfma_f32_32x32x16_bf16 v[34:49], v[198:201], v[206:209], v[34:49]
	v_mfma_f32_32x32x16_bf16 v[18:33], v[214:217], v[202:205], v[18:33]
	v_mfma_f32_32x32x16_bf16 v[2:17], v[214:217], v[206:209], v[2:17]
	ds_read_b128 v[198:201], v140 offset:36928
	ds_read_b128 v[202:205], v141 offset:55360
	ds_read_b128 v[206:209], v141 offset:59968
	ds_read_b128 v[214:217], v140 offset:41536
	s_waitcnt lgkmcnt(4)
	v_mfma_f32_32x32x16_bf16 v[50:65], v[218:221], v[222:225], v[50:65]
	v_mfma_f32_32x32x16_bf16 v[34:49], v[218:221], v[226:229], v[34:49]
	v_mfma_f32_32x32x16_bf16 v[18:33], v[230:233], v[222:225], v[18:33]
	v_mfma_f32_32x32x16_bf16 v[2:17], v[230:233], v[226:229], v[2:17]
	ds_read_b128 v[218:221], v140 offset:36960
	ds_read_b128 v[222:225], v141 offset:55392
	ds_read_b128 v[226:229], v141 offset:60000
	ds_read_b128 v[230:233], v140 offset:41568
	s_waitcnt lgkmcnt(4)
	v_mfma_f32_32x32x16_bf16 v[50:65], v[198:201], v[202:205], v[50:65]
	v_mfma_f32_32x32x16_bf16 v[34:49], v[198:201], v[206:209], v[34:49]
	v_mfma_f32_32x32x16_bf16 v[18:33], v[214:217], v[202:205], v[18:33]
	v_mfma_f32_32x32x16_bf16 v[2:17], v[214:217], v[206:209], v[2:17]
	s_waitcnt lgkmcnt(0)
	v_mfma_f32_32x32x16_bf16 v[50:65], v[218:221], v[222:225], v[50:65]
	v_mfma_f32_32x32x16_bf16 v[34:49], v[218:221], v[226:229], v[34:49]
	v_mfma_f32_32x32x16_bf16 v[18:33], v[230:233], v[222:225], v[18:33]
	v_mfma_f32_32x32x16_bf16 v[2:17], v[230:233], v[226:229], v[2:17]
	s_setprio 0
	s_waitcnt vmcnt(8)
	ds_write_b128 v188, v[98:101]
	ds_write_b128 v188, v[102:105] offset:4608
	ds_write_b128 v188, v[106:109] offset:9216
	ds_write_b128 v188, v[110:113] offset:13824
	ds_write_b128 v188, v[114:117] offset:18432
	ds_write_b128 v188, v[118:121] offset:23040
	ds_write_b128 v188, v[122:125] offset:27648
	ds_write_b128 v188, v[126:129] offset:32256
	s_waitcnt lgkmcnt(0)
	s_barrier
	global_load_dwordx4 v[98:101], v[160:161], off offset:512
	global_load_dwordx4 v[102:105], v[162:163], off offset:512
	global_load_dwordx4 v[106:109], v[164:165], off offset:512
	global_load_dwordx4 v[110:113], v[166:167], off offset:512
	global_load_dwordx4 v[114:117], v[158:159], off offset:512
	global_load_dwordx4 v[118:121], v[168:169], off offset:512
	global_load_dwordx4 v[122:125], v[170:171], off offset:512
	global_load_dwordx4 v[126:129], v[172:173], off offset:512
	s_setprio 1
	ds_read_b128 v[198:201], v140
	ds_read_b128 v[202:205], v141 offset:18432
	ds_read_b128 v[206:209], v141 offset:23040
	ds_read_b128 v[214:217], v140 offset:4608
	ds_read_b128 v[218:221], v140 offset:32
	ds_read_b128 v[222:225], v141 offset:18464
	ds_read_b128 v[226:229], v141 offset:23072
	ds_read_b128 v[230:233], v140 offset:4640
	s_waitcnt lgkmcnt(4)
	v_mfma_f32_32x32x16_bf16 v[50:65], v[198:201], v[202:205], v[50:65]
	v_mfma_f32_32x32x16_bf16 v[34:49], v[198:201], v[206:209], v[34:49]
	v_mfma_f32_32x32x16_bf16 v[18:33], v[214:217], v[202:205], v[18:33]
	v_mfma_f32_32x32x16_bf16 v[2:17], v[214:217], v[206:209], v[2:17]
	ds_read_b128 v[198:201], v140 offset:64
	ds_read_b128 v[202:205], v141 offset:18496
	ds_read_b128 v[206:209], v141 offset:23104
	ds_read_b128 v[214:217], v140 offset:4672
	s_waitcnt lgkmcnt(4)
	v_mfma_f32_32x32x16_bf16 v[50:65], v[218:221], v[222:225], v[50:65]
	v_mfma_f32_32x32x16_bf16 v[34:49], v[218:221], v[226:229], v[34:49]
	v_mfma_f32_32x32x16_bf16 v[18:33], v[230:233], v[222:225], v[18:33]
	v_mfma_f32_32x32x16_bf16 v[2:17], v[230:233], v[226:229], v[2:17]
	ds_read_b128 v[218:221], v140 offset:96
	ds_read_b128 v[222:225], v141 offset:18528
	ds_read_b128 v[226:229], v141 offset:23136
	ds_read_b128 v[230:233], v140 offset:4704
	s_waitcnt lgkmcnt(4)
	v_mfma_f32_32x32x16_bf16 v[50:65], v[198:201], v[202:205], v[50:65]
	v_mfma_f32_32x32x16_bf16 v[34:49], v[198:201], v[206:209], v[34:49]
	v_mfma_f32_32x32x16_bf16 v[18:33], v[214:217], v[202:205], v[18:33]
	v_mfma_f32_32x32x16_bf16 v[2:17], v[214:217], v[206:209], v[2:17]
	s_waitcnt lgkmcnt(0)
	v_mfma_f32_32x32x16_bf16 v[50:65], v[218:221], v[222:225], v[50:65]
	v_mfma_f32_32x32x16_bf16 v[34:49], v[218:221], v[226:229], v[34:49]
	v_mfma_f32_32x32x16_bf16 v[18:33], v[230:233], v[222:225], v[18:33]
	v_mfma_f32_32x32x16_bf16 v[2:17], v[230:233], v[226:229], v[2:17]
	s_setprio 0
	s_waitcnt vmcnt(8)
	ds_write_b128 v188, v[66:69] offset:36864
	ds_write_b128 v188, v[70:73] offset:41472
	ds_write_b128 v188, v[74:77] offset:46080
	ds_write_b128 v188, v[78:81] offset:50688
	ds_write_b128 v188, v[82:85] offset:55296
	ds_write_b128 v188, v[86:89] offset:59904
	ds_write_b128 v188, v[90:93] offset:64512
	ds_write_b128 v189, v[94:97] offset:13824
	s_waitcnt lgkmcnt(0)
	s_barrier
; __device__ void gemm_phase(const u16* __restrict__ Wb, int ldw, const u16* __restrict__ Xb, int ldx, int K,
;                            u16* __restrict__ outb, int ldo, int ntn, int ntiles, u16* lds) {
;     ...
;     for (int kt = 0; kt < nk; kt += 2) {
;       if (kt + 2 < nk) gs_load(B, gw, ldw, gx, ldx, (kt + 2) * 64);
;       else if (has_next) gs_load(B, gwn, ldw, gxn, ldx, 0);
;       gemm_kstep(lds, wn, wt, r, h, acc);
;       gs_store(A, lds + 2 * TILE_U16, lo);
;       __syncthreads();
;       if (kt + 3 < nk) gs_load(A, gw, ldw, gx, ldx, (kt + 3) * 64);
;       else if (has_next) gs_load(A, gwn, ldw, gxn, ldx, 64);
;       gemm_kstep(lds + 2 * TILE_U16, wn, wt, r, h, acc);
;       if (kt + 2 < nk) gs_store(B, lds, lo);
;       __syncthreads();
	global_load_dwordx4 v[66:69], v[160:161], off offset:640
	global_load_dwordx4 v[70:73], v[162:163], off offset:640
	global_load_dwordx4 v[74:77], v[164:165], off offset:640
	global_load_dwordx4 v[78:81], v[166:167], off offset:640
	global_load_dwordx4 v[82:85], v[158:159], off offset:640
	global_load_dwordx4 v[86:89], v[168:169], off offset:640
	global_load_dwordx4 v[90:93], v[170:171], off offset:640
	global_load_dwordx4 v[94:97], v[172:173], off offset:640
	s_setprio 1
	ds_read_b128 v[198:201], v140 offset:36864
	ds_read_b128 v[202:205], v141 offset:55296
	ds_read_b128 v[206:209], v141 offset:59904
	ds_read_b128 v[214:217], v140 offset:41472
	ds_read_b128 v[218:221], v140 offset:36896
	ds_read_b128 v[222:225], v141 offset:55328
	ds_read_b128 v[226:229], v141 offset:59936
	ds_read_b128 v[230:233], v140 offset:41504
	s_waitcnt lgkmcnt(4)
	v_mfma_f32_32x32x16_bf16 v[50:65], v[198:201], v[202:205], v[50:65]
	v_mfma_f32_32x32x16_bf16 v[34:49], v[198:201], v[206:209], v[34:49]
	v_mfma_f32_32x32x16_bf16 v[18:33], v[214:217], v[202:205], v[18:33]
	v_mfma_f32_32x32x16_bf16 v[2:17], v[214:217], v[206:209], v[2:17]
	ds_read_b128 v[198:201], v140 offset:36928
	ds_read_b128 v[202:205], v141 offset:55360
	ds_read_b128 v[206:209], v141 offset:59968
	ds_read_b128 v[214:217], v140 offset:41536
	s_waitcnt lgkmcnt(4)
	v_mfma_f32_32x32x16_bf16 v[50:65], v[218:221], v[222:225], v[50:65]
	v_mfma_f32_32x32x16_bf16 v[34:49], v[218:221], v[226:229], v[34:49]
	v_mfma_f32_32x32x16_bf16 v[18:33], v[230:233], v[222:225], v[18:33]
	v_mfma_f32_32x32x16_bf16 v[2:17], v[230:233], v[226:229], v[2:17]
	ds_read_b128 v[218:221], v140 offset:36960
	ds_read_b128 v[222:225], v141 offset:55392
	ds_read_b128 v[226:229], v141 offset:60000
	ds_read_b128 v[230:233], v140 offset:41568
	s_waitcnt lgkmcnt(4)
	v_mfma_f32_32x32x16_bf16 v[50:65], v[198:201], v[202:205], v[50:65]
	v_mfma_f32_32x32x16_bf16 v[34:49], v[198:201], v[206:209], v[34:49]
	v_mfma_f32_32x32x16_bf16 v[18:33], v[214:217], v[202:205], v[18:33]
	v_mfma_f32_32x32x16_bf16 v[2:17], v[214:217], v[206:209], v[2:17]
	s_waitcnt lgkmcnt(0)
	v_mfma_f32_32x32x16_bf16 v[50:65], v[218:221], v[222:225], v[50:65]
	v_mfma_f32_32x32x16_bf16 v[34:49], v[218:221], v[226:229], v[34:49]
	v_mfma_f32_32x32x16_bf16 v[18:33], v[230:233], v[222:225], v[18:33]
	v_mfma_f32_32x32x16_bf16 v[2:17], v[230:233], v[226:229], v[2:17]
	s_setprio 0
	s_waitcnt vmcnt(8)
	ds_write_b128 v188, v[98:101]
	ds_write_b128 v188, v[102:105] offset:4608
	ds_write_b128 v188, v[106:109] offset:9216
	ds_write_b128 v188, v[110:113] offset:13824
	ds_write_b128 v188, v[114:117] offset:18432
	ds_write_b128 v188, v[118:121] offset:23040
	ds_write_b128 v188, v[122:125] offset:27648
	ds_write_b128 v188, v[126:129] offset:32256
	s_waitcnt lgkmcnt(0)
	s_barrier
	global_load_dwordx4 v[98:101], v[160:161], off offset:768
	global_load_dwordx4 v[102:105], v[162:163], off offset:768
	global_load_dwordx4 v[106:109], v[164:165], off offset:768
	global_load_dwordx4 v[110:113], v[166:167], off offset:768
	global_load_dwordx4 v[114:117], v[158:159], off offset:768
	global_load_dwordx4 v[118:121], v[168:169], off offset:768
	global_load_dwordx4 v[122:125], v[170:171], off offset:768
	global_load_dwordx4 v[126:129], v[172:173], off offset:768
	s_setprio 1
	ds_read_b128 v[198:201], v140
	ds_read_b128 v[202:205], v141 offset:18432
	ds_read_b128 v[206:209], v141 offset:23040
	ds_read_b128 v[214:217], v140 offset:4608
	ds_read_b128 v[218:221], v140 offset:32
	ds_read_b128 v[222:225], v141 offset:18464
	ds_read_b128 v[226:229], v141 offset:23072
	ds_read_b128 v[230:233], v140 offset:4640
	s_waitcnt lgkmcnt(4)
	v_mfma_f32_32x32x16_bf16 v[50:65], v[198:201], v[202:205], v[50:65]
	v_mfma_f32_32x32x16_bf16 v[34:49], v[198:201], v[206:209], v[34:49]
	v_mfma_f32_32x32x16_bf16 v[18:33], v[214:217], v[202:205], v[18:33]
	v_mfma_f32_32x32x16_bf16 v[2:17], v[214:217], v[206:209], v[2:17]
	ds_read_b128 v[198:201], v140 offset:64
	ds_read_b128 v[202:205], v141 offset:18496
	ds_read_b128 v[206:209], v141 offset:23104
	ds_read_b128 v[214:217], v140 offset:4672
	s_waitcnt lgkmcnt(4)
	v_mfma_f32_32x32x16_bf16 v[50:65], v[218:221], v[222:225], v[50:65]
	v_mfma_f32_32x32x16_bf16 v[34:49], v[218:221], v[226:229], v[34:49]
	v_mfma_f32_32x32x16_bf16 v[18:33], v[230:233], v[222:225], v[18:33]
	v_mfma_f32_32x32x16_bf16 v[2:17], v[230:233], v[226:229], v[2:17]
	ds_read_b128 v[218:221], v140 offset:96
	ds_read_b128 v[222:225], v141 offset:18528
	ds_read_b128 v[226:229], v141 offset:23136
	ds_read_b128 v[230:233], v140 offset:4704
	s_waitcnt lgkmcnt(4)
	v_mfma_f32_32x32x16_bf16 v[50:65], v[198:201], v[202:205], v[50:65]
	v_mfma_f32_32x32x16_bf16 v[34:49], v[198:201], v[206:209], v[34:49]
	v_mfma_f32_32x32x16_bf16 v[18:33], v[214:217], v[202:205], v[18:33]
	v_mfma_f32_32x32x16_bf16 v[2:17], v[214:217], v[206:209], v[2:17]
	s_waitcnt lgkmcnt(0)
	v_mfma_f32_32x32x16_bf16 v[50:65], v[218:221], v[222:225], v[50:65]
	v_mfma_f32_32x32x16_bf16 v[34:49], v[218:221], v[226:229], v[34:49]
	v_mfma_f32_32x32x16_bf16 v[18:33], v[230:233], v[222:225], v[18:33]
	v_mfma_f32_32x32x16_bf16 v[2:17], v[230:233], v[226:229], v[2:17]
	s_setprio 0
	s_waitcnt vmcnt(8)
	ds_write_b128 v188, v[66:69] offset:36864
	ds_write_b128 v188, v[70:73] offset:41472
	ds_write_b128 v188, v[74:77] offset:46080
	ds_write_b128 v188, v[78:81] offset:50688
	ds_write_b128 v188, v[82:85] offset:55296
	ds_write_b128 v188, v[86:89] offset:59904
	ds_write_b128 v188, v[90:93] offset:64512
	ds_write_b128 v189, v[94:97] offset:13824
	s_waitcnt lgkmcnt(0)
	s_barrier
; __device__ void gemm_phase(const u16* __restrict__ Wb, int ldw, const u16* __restrict__ Xb, int ldx, int K,
;                            u16* __restrict__ outb, int ldo, int ntn, int ntiles, u16* lds) {
;     ...
;     for (int kt = 0; kt < nk; kt += 2) {
;       if (kt + 2 < nk) gs_load(B, gw, ldw, gx, ldx, (kt + 2) * 64);
;       else if (has_next) gs_load(B, gwn, ldw, gxn, ldx, 0);
;       gemm_kstep(lds, wn, wt, r, h, acc);
;       gs_store(A, lds + 2 * TILE_U16, lo);
;       __syncthreads();
;       if (kt + 3 < nk) gs_load(A, gw, ldw, gx, ldx, (kt + 3) * 64);
;       else if (has_next) gs_load(A, gwn, ldw, gxn, ldx, 64);
;       gemm_kstep(lds + 2 * TILE_U16, wn, wt, r, h, acc);
;       if (kt + 2 < nk) gs_store(B, lds, lo);
;       __syncthreads();
	global_load_dwordx4 v[66:69], v[160:161], off offset:896
	global_load_dwordx4 v[70:73], v[162:163], off offset:896
	global_load_dwordx4 v[74:77], v[164:165], off offset:896
	global_load_dwordx4 v[78:81], v[166:167], off offset:896
	global_load_dwordx4 v[82:85], v[158:159], off offset:896
	global_load_dwordx4 v[86:89], v[168:169], off offset:896
	global_load_dwordx4 v[90:93], v[170:171], off offset:896
	global_load_dwordx4 v[94:97], v[172:173], off offset:896
	s_setprio 1
	ds_read_b128 v[198:201], v140 offset:36864
	ds_read_b128 v[202:205], v141 offset:55296
	ds_read_b128 v[206:209], v141 offset:59904
	ds_read_b128 v[214:217], v140 offset:41472
	ds_read_b128 v[218:221], v140 offset:36896
	ds_read_b128 v[222:225], v141 offset:55328
	ds_read_b128 v[226:229], v141 offset:59936
	ds_read_b128 v[230:233], v140 offset:41504
	s_waitcnt lgkmcnt(4)
	v_mfma_f32_32x32x16_bf16 v[50:65], v[198:201], v[202:205], v[50:65]
	v_mfma_f32_32x32x16_bf16 v[34:49], v[198:201], v[206:209], v[34:49]
	v_mfma_f32_32x32x16_bf16 v[18:33], v[214:217], v[202:205], v[18:33]
	v_mfma_f32_32x32x16_bf16 v[2:17], v[214:217], v[206:209], v[2:17]
	ds_read_b128 v[198:201], v140 offset:36928
	ds_read_b128 v[202:205], v141 offset:55360
	ds_read_b128 v[206:209], v141 offset:59968
	ds_read_b128 v[214:217], v140 offset:41536
	s_waitcnt lgkmcnt(4)
	v_mfma_f32_32x32x16_bf16 v[50:65], v[218:221], v[222:225], v[50:65]
	v_mfma_f32_32x32x16_bf16 v[34:49], v[218:221], v[226:229], v[34:49]
	v_mfma_f32_32x32x16_bf16 v[18:33], v[230:233], v[222:225], v[18:33]
	v_mfma_f32_32x32x16_bf16 v[2:17], v[230:233], v[226:229], v[2:17]
	ds_read_b128 v[218:221], v140 offset:36960
	ds_read_b128 v[222:225], v141 offset:55392
	ds_read_b128 v[226:229], v141 offset:60000
	ds_read_b128 v[230:233], v140 offset:41568
	s_waitcnt lgkmcnt(4)
	v_mfma_f32_32x32x16_bf16 v[50:65], v[198:201], v[202:205], v[50:65]
	v_mfma_f32_32x32x16_bf16 v[34:49], v[198:201], v[206:209], v[34:49]
	v_mfma_f32_32x32x16_bf16 v[18:33], v[214:217], v[202:205], v[18:33]
	v_mfma_f32_32x32x16_bf16 v[2:17], v[214:217], v[206:209], v[2:17]
	s_waitcnt lgkmcnt(0)
	v_mfma_f32_32x32x16_bf16 v[50:65], v[218:221], v[222:225], v[50:65]
	v_mfma_f32_32x32x16_bf16 v[34:49], v[218:221], v[226:229], v[34:49]
	v_mfma_f32_32x32x16_bf16 v[18:33], v[230:233], v[222:225], v[18:33]
	v_mfma_f32_32x32x16_bf16 v[2:17], v[230:233], v[226:229], v[2:17]
	s_setprio 0
	s_waitcnt vmcnt(8)
	ds_write_b128 v188, v[98:101]
	ds_write_b128 v188, v[102:105] offset:4608
	ds_write_b128 v188, v[106:109] offset:9216
	ds_write_b128 v188, v[110:113] offset:13824
	ds_write_b128 v188, v[114:117] offset:18432
	ds_write_b128 v188, v[118:121] offset:23040
	ds_write_b128 v188, v[122:125] offset:27648
	ds_write_b128 v188, v[126:129] offset:32256
	s_waitcnt lgkmcnt(0)
	s_barrier
	global_load_dwordx4 v[98:101], v[160:161], off offset:1024
	global_load_dwordx4 v[102:105], v[162:163], off offset:1024
	global_load_dwordx4 v[106:109], v[164:165], off offset:1024
	global_load_dwordx4 v[110:113], v[166:167], off offset:1024
	global_load_dwordx4 v[114:117], v[158:159], off offset:1024
	global_load_dwordx4 v[118:121], v[168:169], off offset:1024
	global_load_dwordx4 v[122:125], v[170:171], off offset:1024
	global_load_dwordx4 v[126:129], v[172:173], off offset:1024
	s_setprio 1
	ds_read_b128 v[198:201], v140
	ds_read_b128 v[202:205], v141 offset:18432
	ds_read_b128 v[206:209], v141 offset:23040
	ds_read_b128 v[214:217], v140 offset:4608
	ds_read_b128 v[218:221], v140 offset:32
	ds_read_b128 v[222:225], v141 offset:18464
	ds_read_b128 v[226:229], v141 offset:23072
	ds_read_b128 v[230:233], v140 offset:4640
	s_waitcnt lgkmcnt(4)
	v_mfma_f32_32x32x16_bf16 v[50:65], v[198:201], v[202:205], v[50:65]
	v_mfma_f32_32x32x16_bf16 v[34:49], v[198:201], v[206:209], v[34:49]
	v_mfma_f32_32x32x16_bf16 v[18:33], v[214:217], v[202:205], v[18:33]
	v_mfma_f32_32x32x16_bf16 v[2:17], v[214:217], v[206:209], v[2:17]
	ds_read_b128 v[198:201], v140 offset:64
	ds_read_b128 v[202:205], v141 offset:18496
	ds_read_b128 v[206:209], v141 offset:23104
	ds_read_b128 v[214:217], v140 offset:4672
	s_waitcnt lgkmcnt(4)
	v_mfma_f32_32x32x16_bf16 v[50:65], v[218:221], v[222:225], v[50:65]
	v_mfma_f32_32x32x16_bf16 v[34:49], v[218:221], v[226:229], v[34:49]
	v_mfma_f32_32x32x16_bf16 v[18:33], v[230:233], v[222:225], v[18:33]
	v_mfma_f32_32x32x16_bf16 v[2:17], v[230:233], v[226:229], v[2:17]
	ds_read_b128 v[218:221], v140 offset:96
	ds_read_b128 v[222:225], v141 offset:18528
	ds_read_b128 v[226:229], v141 offset:23136
	ds_read_b128 v[230:233], v140 offset:4704
	s_waitcnt lgkmcnt(4)
	v_mfma_f32_32x32x16_bf16 v[50:65], v[198:201], v[202:205], v[50:65]
	v_mfma_f32_32x32x16_bf16 v[34:49], v[198:201], v[206:209], v[34:49]
	v_mfma_f32_32x32x16_bf16 v[18:33], v[214:217], v[202:205], v[18:33]
	v_mfma_f32_32x32x16_bf16 v[2:17], v[214:217], v[206:209], v[2:17]
	s_waitcnt lgkmcnt(0)
	v_mfma_f32_32x32x16_bf16 v[50:65], v[218:221], v[222:225], v[50:65]
	v_mfma_f32_32x32x16_bf16 v[34:49], v[218:221], v[226:229], v[34:49]
	v_mfma_f32_32x32x16_bf16 v[18:33], v[230:233], v[222:225], v[18:33]
	v_mfma_f32_32x32x16_bf16 v[2:17], v[230:233], v[226:229], v[2:17]
	s_setprio 0
	s_waitcnt vmcnt(8)
	ds_write_b128 v188, v[66:69] offset:36864
	ds_write_b128 v188, v[70:73] offset:41472
	ds_write_b128 v188, v[74:77] offset:46080
	ds_write_b128 v188, v[78:81] offset:50688
	ds_write_b128 v188, v[82:85] offset:55296
	ds_write_b128 v188, v[86:89] offset:59904
	ds_write_b128 v188, v[90:93] offset:64512
	ds_write_b128 v189, v[94:97] offset:13824
	s_waitcnt lgkmcnt(0)
	s_barrier
; __device__ void gemm_phase(const u16* __restrict__ Wb, int ldw, const u16* __restrict__ Xb, int ldx, int K,
;                            u16* __restrict__ outb, int ldo, int ntn, int ntiles, u16* lds) {
;     ...
;     for (int kt = 0; kt < nk; kt += 2) {
;       if (kt + 2 < nk) gs_load(B, gw, ldw, gx, ldx, (kt + 2) * 64);
;       else if (has_next) gs_load(B, gwn, ldw, gxn, ldx, 0);
;       gemm_kstep(lds, wn, wt, r, h, acc);
;       gs_store(A, lds + 2 * TILE_U16, lo);
;       __syncthreads();
;       if (kt + 3 < nk) gs_load(A, gw, ldw, gx, ldx, (kt + 3) * 64);
;       else if (has_next) gs_load(A, gwn, ldw, gxn, ldx, 64);
;       gemm_kstep(lds + 2 * TILE_U16, wn, wt, r, h, acc);
;       if (kt + 2 < nk) gs_store(B, lds, lo);
;       __syncthreads();
	global_load_dwordx4 v[66:69], v[160:161], off offset:1152
	global_load_dwordx4 v[70:73], v[162:163], off offset:1152
	global_load_dwordx4 v[74:77], v[164:165], off offset:1152
	global_load_dwordx4 v[78:81], v[166:167], off offset:1152
	global_load_dwordx4 v[82:85], v[158:159], off offset:1152
	global_load_dwordx4 v[86:89], v[168:169], off offset:1152
	global_load_dwordx4 v[90:93], v[170:171], off offset:1152
	global_load_dwordx4 v[94:97], v[172:173], off offset:1152
	s_setprio 1
	ds_read_b128 v[198:201], v140 offset:36864
	ds_read_b128 v[202:205], v141 offset:55296
	ds_read_b128 v[206:209], v141 offset:59904
	ds_read_b128 v[214:217], v140 offset:41472
	ds_read_b128 v[218:221], v140 offset:36896
	ds_read_b128 v[222:225], v141 offset:55328
	ds_read_b128 v[226:229], v141 offset:59936
	ds_read_b128 v[230:233], v140 offset:41504
	s_waitcnt lgkmcnt(4)
	v_mfma_f32_32x32x16_bf16 v[50:65], v[198:201], v[202:205], v[50:65]
	v_mfma_f32_32x32x16_bf16 v[34:49], v[198:201], v[206:209], v[34:49]
	v_mfma_f32_32x32x16_bf16 v[18:33], v[214:217], v[202:205], v[18:33]
	v_mfma_f32_32x32x16_bf16 v[2:17], v[214:217], v[206:209], v[2:17]
	ds_read_b128 v[198:201], v140 offset:36928
	ds_read_b128 v[202:205], v141 offset:55360
	ds_read_b128 v[206:209], v141 offset:59968
	ds_read_b128 v[214:217], v140 offset:41536
	s_waitcnt lgkmcnt(4)
	v_mfma_f32_32x32x16_bf16 v[50:65], v[218:221], v[222:225], v[50:65]
	v_mfma_f32_32x32x16_bf16 v[34:49], v[218:221], v[226:229], v[34:49]
	v_mfma_f32_32x32x16_bf16 v[18:33], v[230:233], v[222:225], v[18:33]
	v_mfma_f32_32x32x16_bf16 v[2:17], v[230:233], v[226:229], v[2:17]
	ds_read_b128 v[218:221], v140 offset:36960
	ds_read_b128 v[222:225], v141 offset:55392
	ds_read_b128 v[226:229], v141 offset:60000
	ds_read_b128 v[230:233], v140 offset:41568
	s_waitcnt lgkmcnt(4)
	v_mfma_f32_32x32x16_bf16 v[50:65], v[198:201], v[202:205], v[50:65]
	v_mfma_f32_32x32x16_bf16 v[34:49], v[198:201], v[206:209], v[34:49]
	v_mfma_f32_32x32x16_bf16 v[18:33], v[214:217], v[202:205], v[18:33]
	v_mfma_f32_32x32x16_bf16 v[2:17], v[214:217], v[206:209], v[2:17]
	s_waitcnt lgkmcnt(0)
	v_mfma_f32_32x32x16_bf16 v[50:65], v[218:221], v[222:225], v[50:65]
	v_mfma_f32_32x32x16_bf16 v[34:49], v[218:221], v[226:229], v[34:49]
	v_mfma_f32_32x32x16_bf16 v[18:33], v[230:233], v[222:225], v[18:33]
	v_mfma_f32_32x32x16_bf16 v[2:17], v[230:233], v[226:229], v[2:17]
	s_setprio 0
	s_waitcnt vmcnt(8)
	ds_write_b128 v188, v[98:101]
	ds_write_b128 v188, v[102:105] offset:4608
	ds_write_b128 v188, v[106:109] offset:9216
	ds_write_b128 v188, v[110:113] offset:13824
	ds_write_b128 v188, v[114:117] offset:18432
	ds_write_b128 v188, v[118:121] offset:23040
	ds_write_b128 v188, v[122:125] offset:27648
	ds_write_b128 v188, v[126:129] offset:32256
	s_waitcnt lgkmcnt(0)
	s_barrier
	global_load_dwordx4 v[98:101], v[160:161], off offset:1280
	global_load_dwordx4 v[102:105], v[162:163], off offset:1280
	global_load_dwordx4 v[106:109], v[164:165], off offset:1280
	global_load_dwordx4 v[110:113], v[166:167], off offset:1280
	global_load_dwordx4 v[114:117], v[158:159], off offset:1280
	global_load_dwordx4 v[118:121], v[168:169], off offset:1280
	global_load_dwordx4 v[122:125], v[170:171], off offset:1280
	global_load_dwordx4 v[126:129], v[172:173], off offset:1280
	s_setprio 1
	ds_read_b128 v[198:201], v140
	ds_read_b128 v[202:205], v141 offset:18432
	ds_read_b128 v[206:209], v141 offset:23040
	ds_read_b128 v[214:217], v140 offset:4608
	ds_read_b128 v[218:221], v140 offset:32
	ds_read_b128 v[222:225], v141 offset:18464
	ds_read_b128 v[226:229], v141 offset:23072
	ds_read_b128 v[230:233], v140 offset:4640
	s_waitcnt lgkmcnt(4)
	v_mfma_f32_32x32x16_bf16 v[50:65], v[198:201], v[202:205], v[50:65]
	v_mfma_f32_32x32x16_bf16 v[34:49], v[198:201], v[206:209], v[34:49]
	v_mfma_f32_32x32x16_bf16 v[18:33], v[214:217], v[202:205], v[18:33]
	v_mfma_f32_32x32x16_bf16 v[2:17], v[214:217], v[206:209], v[2:17]
	ds_read_b128 v[198:201], v140 offset:64
	ds_read_b128 v[202:205], v141 offset:18496
	ds_read_b128 v[206:209], v141 offset:23104
	ds_read_b128 v[214:217], v140 offset:4672
	s_waitcnt lgkmcnt(4)
	v_mfma_f32_32x32x16_bf16 v[50:65], v[218:221], v[222:225], v[50:65]
	v_mfma_f32_32x32x16_bf16 v[34:49], v[218:221], v[226:229], v[34:49]
	v_mfma_f32_32x32x16_bf16 v[18:33], v[230:233], v[222:225], v[18:33]
	v_mfma_f32_32x32x16_bf16 v[2:17], v[230:233], v[226:229], v[2:17]
	ds_read_b128 v[218:221], v140 offset:96
	ds_read_b128 v[222:225], v141 offset:18528
	ds_read_b128 v[226:229], v141 offset:23136
	ds_read_b128 v[230:233], v140 offset:4704
	s_waitcnt lgkmcnt(4)
	v_mfma_f32_32x32x16_bf16 v[50:65], v[198:201], v[202:205], v[50:65]
	v_mfma_f32_32x32x16_bf16 v[34:49], v[198:201], v[206:209], v[34:49]
	v_mfma_f32_32x32x16_bf16 v[18:33], v[214:217], v[202:205], v[18:33]
	v_mfma_f32_32x32x16_bf16 v[2:17], v[214:217], v[206:209], v[2:17]
	s_waitcnt lgkmcnt(0)
	v_mfma_f32_32x32x16_bf16 v[50:65], v[218:221], v[222:225], v[50:65]
	v_mfma_f32_32x32x16_bf16 v[34:49], v[218:221], v[226:229], v[34:49]
	v_mfma_f32_32x32x16_bf16 v[18:33], v[230:233], v[222:225], v[18:33]
	v_mfma_f32_32x32x16_bf16 v[2:17], v[230:233], v[226:229], v[2:17]
	s_setprio 0
	s_waitcnt vmcnt(8)
	ds_write_b128 v188, v[66:69] offset:36864
	ds_write_b128 v188, v[70:73] offset:41472
	ds_write_b128 v188, v[74:77] offset:46080
	ds_write_b128 v188, v[78:81] offset:50688
	ds_write_b128 v188, v[82:85] offset:55296
	ds_write_b128 v188, v[86:89] offset:59904
	ds_write_b128 v188, v[90:93] offset:64512
	ds_write_b128 v189, v[94:97] offset:13824
	s_waitcnt lgkmcnt(0)
	s_barrier
; __device__ void gemm_phase(const u16* __restrict__ Wb, int ldw, const u16* __restrict__ Xb, int ldx, int K,
;                            u16* __restrict__ outb, int ldo, int ntn, int ntiles, u16* lds) {
;     ...
;     for (int kt = 0; kt < nk; kt += 2) {
;       if (kt + 2 < nk) gs_load(B, gw, ldw, gx, ldx, (kt + 2) * 64);
;       else if (has_next) gs_load(B, gwn, ldw, gxn, ldx, 0);
;       gemm_kstep(lds, wn, wt, r, h, acc);
;       gs_store(A, lds + 2 * TILE_U16, lo);
;       __syncthreads();
;       if (kt + 3 < nk) gs_load(A, gw, ldw, gx, ldx, (kt + 3) * 64);
;       else if (has_next) gs_load(A, gwn, ldw, gxn, ldx, 64);
;       gemm_kstep(lds + 2 * TILE_U16, wn, wt, r, h, acc);
;       if (kt + 2 < nk) gs_store(B, lds, lo);
;       __syncthreads();
	global_load_dwordx4 v[66:69], v[160:161], off offset:1408
	global_load_dwordx4 v[70:73], v[162:163], off offset:1408
	global_load_dwordx4 v[74:77], v[164:165], off offset:1408
	global_load_dwordx4 v[78:81], v[166:167], off offset:1408
	global_load_dwordx4 v[82:85], v[158:159], off offset:1408
	global_load_dwordx4 v[86:89], v[168:169], off offset:1408
	global_load_dwordx4 v[90:93], v[170:171], off offset:1408
	global_load_dwordx4 v[94:97], v[172:173], off offset:1408
	s_setprio 1
	ds_read_b128 v[198:201], v140 offset:36864
	ds_read_b128 v[202:205], v141 offset:55296
	ds_read_b128 v[206:209], v141 offset:59904
	ds_read_b128 v[214:217], v140 offset:41472
	ds_read_b128 v[218:221], v140 offset:36896
	ds_read_b128 v[222:225], v141 offset:55328
	ds_read_b128 v[226:229], v141 offset:59936
	ds_read_b128 v[230:233], v140 offset:41504
	s_waitcnt lgkmcnt(4)
	v_mfma_f32_32x32x16_bf16 v[50:65], v[198:201], v[202:205], v[50:65]
	v_mfma_f32_32x32x16_bf16 v[34:49], v[198:201], v[206:209], v[34:49]
	v_mfma_f32_32x32x16_bf16 v[18:33], v[214:217], v[202:205], v[18:33]
	v_mfma_f32_32x32x16_bf16 v[2:17], v[214:217], v[206:209], v[2:17]
	ds_read_b128 v[198:201], v140 offset:36928
	ds_read_b128 v[202:205], v141 offset:55360
	ds_read_b128 v[206:209], v141 offset:59968
	ds_read_b128 v[214:217], v140 offset:41536
	s_waitcnt lgkmcnt(4)
	v_mfma_f32_32x32x16_bf16 v[50:65], v[218:221], v[222:225], v[50:65]
	v_mfma_f32_32x32x16_bf16 v[34:49], v[218:221], v[226:229], v[34:49]
	v_mfma_f32_32x32x16_bf16 v[18:33], v[230:233], v[222:225], v[18:33]
	v_mfma_f32_32x32x16_bf16 v[2:17], v[230:233], v[226:229], v[2:17]
	ds_read_b128 v[218:221], v140 offset:36960
	ds_read_b128 v[222:225], v141 offset:55392
	ds_read_b128 v[226:229], v141 offset:60000
	ds_read_b128 v[230:233], v140 offset:41568
	s_waitcnt lgkmcnt(4)
	v_mfma_f32_32x32x16_bf16 v[50:65], v[198:201], v[202:205], v[50:65]
	v_mfma_f32_32x32x16_bf16 v[34:49], v[198:201], v[206:209], v[34:49]
	v_mfma_f32_32x32x16_bf16 v[18:33], v[214:217], v[202:205], v[18:33]
	v_mfma_f32_32x32x16_bf16 v[2:17], v[214:217], v[206:209], v[2:17]
	s_waitcnt lgkmcnt(0)
	v_mfma_f32_32x32x16_bf16 v[50:65], v[218:221], v[222:225], v[50:65]
	v_mfma_f32_32x32x16_bf16 v[34:49], v[218:221], v[226:229], v[34:49]
	v_mfma_f32_32x32x16_bf16 v[18:33], v[230:233], v[222:225], v[18:33]
	v_mfma_f32_32x32x16_bf16 v[2:17], v[230:233], v[226:229], v[2:17]
	s_setprio 0
	s_waitcnt vmcnt(8)
	ds_write_b128 v188, v[98:101]
	ds_write_b128 v188, v[102:105] offset:4608
	ds_write_b128 v188, v[106:109] offset:9216
	ds_write_b128 v188, v[110:113] offset:13824
	ds_write_b128 v188, v[114:117] offset:18432
	ds_write_b128 v188, v[118:121] offset:23040
	ds_write_b128 v188, v[122:125] offset:27648
	ds_write_b128 v188, v[126:129] offset:32256
	s_waitcnt lgkmcnt(0)
	s_barrier
	global_load_dwordx4 v[98:101], v[160:161], off offset:1536
	global_load_dwordx4 v[102:105], v[162:163], off offset:1536
	global_load_dwordx4 v[106:109], v[164:165], off offset:1536
	global_load_dwordx4 v[110:113], v[166:167], off offset:1536
	global_load_dwordx4 v[114:117], v[158:159], off offset:1536
	global_load_dwordx4 v[118:121], v[168:169], off offset:1536
	global_load_dwordx4 v[122:125], v[170:171], off offset:1536
	global_load_dwordx4 v[126:129], v[172:173], off offset:1536
	s_setprio 1
	ds_read_b128 v[198:201], v140
	ds_read_b128 v[202:205], v141 offset:18432
	ds_read_b128 v[206:209], v141 offset:23040
	ds_read_b128 v[214:217], v140 offset:4608
	ds_read_b128 v[218:221], v140 offset:32
	ds_read_b128 v[222:225], v141 offset:18464
	ds_read_b128 v[226:229], v141 offset:23072
	ds_read_b128 v[230:233], v140 offset:4640
	s_waitcnt lgkmcnt(4)
	v_mfma_f32_32x32x16_bf16 v[50:65], v[198:201], v[202:205], v[50:65]
	v_mfma_f32_32x32x16_bf16 v[34:49], v[198:201], v[206:209], v[34:49]
	v_mfma_f32_32x32x16_bf16 v[18:33], v[214:217], v[202:205], v[18:33]
	v_mfma_f32_32x32x16_bf16 v[2:17], v[214:217], v[206:209], v[2:17]
	ds_read_b128 v[198:201], v140 offset:64
	ds_read_b128 v[202:205], v141 offset:18496
	ds_read_b128 v[206:209], v141 offset:23104
	ds_read_b128 v[214:217], v140 offset:4672
	s_waitcnt lgkmcnt(4)
	v_mfma_f32_32x32x16_bf16 v[50:65], v[218:221], v[222:225], v[50:65]
	v_mfma_f32_32x32x16_bf16 v[34:49], v[218:221], v[226:229], v[34:49]
	v_mfma_f32_32x32x16_bf16 v[18:33], v[230:233], v[222:225], v[18:33]
	v_mfma_f32_32x32x16_bf16 v[2:17], v[230:233], v[226:229], v[2:17]
	ds_read_b128 v[218:221], v140 offset:96
	ds_read_b128 v[222:225], v141 offset:18528
	ds_read_b128 v[226:229], v141 offset:23136
	ds_read_b128 v[230:233], v140 offset:4704
	s_waitcnt lgkmcnt(4)
	v_mfma_f32_32x32x16_bf16 v[50:65], v[198:201], v[202:205], v[50:65]
	v_mfma_f32_32x32x16_bf16 v[34:49], v[198:201], v[206:209], v[34:49]
	v_mfma_f32_32x32x16_bf16 v[18:33], v[214:217], v[202:205], v[18:33]
	v_mfma_f32_32x32x16_bf16 v[2:17], v[214:217], v[206:209], v[2:17]
	s_waitcnt lgkmcnt(0)
	v_mfma_f32_32x32x16_bf16 v[50:65], v[218:221], v[222:225], v[50:65]
	v_mfma_f32_32x32x16_bf16 v[34:49], v[218:221], v[226:229], v[34:49]
	v_mfma_f32_32x32x16_bf16 v[18:33], v[230:233], v[222:225], v[18:33]
	v_mfma_f32_32x32x16_bf16 v[2:17], v[230:233], v[226:229], v[2:17]
	s_setprio 0
	s_waitcnt vmcnt(8)
	ds_write_b128 v188, v[66:69] offset:36864
	ds_write_b128 v188, v[70:73] offset:41472
	ds_write_b128 v188, v[74:77] offset:46080
	ds_write_b128 v188, v[78:81] offset:50688
	ds_write_b128 v188, v[82:85] offset:55296
	ds_write_b128 v188, v[86:89] offset:59904
	ds_write_b128 v188, v[90:93] offset:64512
	ds_write_b128 v189, v[94:97] offset:13824
	s_waitcnt lgkmcnt(0)
	s_barrier
; __device__ void gemm_phase(const u16* __restrict__ Wb, int ldw, const u16* __restrict__ Xb, int ldx, int K,
;                            u16* __restrict__ outb, int ldo, int ntn, int ntiles, u16* lds) {
;     ...
;     for (int kt = 0; kt < nk; kt += 2) {
;       if (kt + 2 < nk) gs_load(B, gw, ldw, gx, ldx, (kt + 2) * 64);
;       else if (has_next) gs_load(B, gwn, ldw, gxn, ldx, 0);
;       gemm_kstep(lds, wn, wt, r, h, acc);
;       gs_store(A, lds + 2 * TILE_U16, lo);
;       __syncthreads();
;       if (kt + 3 < nk) gs_load(A, gw, ldw, gx, ldx, (kt + 3) * 64);
;       else if (has_next) gs_load(A, gwn, ldw, gxn, ldx, 64);
;       gemm_kstep(lds + 2 * TILE_U16, wn, wt, r, h, acc);
;       if (kt + 2 < nk) gs_store(B, lds, lo);
;       __syncthreads();
	global_load_dwordx4 v[66:69], v[160:161], off offset:1664
	global_load_dwordx4 v[70:73], v[162:163], off offset:1664
	global_load_dwordx4 v[74:77], v[164:165], off offset:1664
	global_load_dwordx4 v[78:81], v[166:167], off offset:1664
	global_load_dwordx4 v[82:85], v[158:159], off offset:1664
	global_load_dwordx4 v[86:89], v[168:169], off offset:1664
	global_load_dwordx4 v[90:93], v[170:171], off offset:1664
	global_load_dwordx4 v[94:97], v[172:173], off offset:1664
	s_setprio 1
	ds_read_b128 v[198:201], v140 offset:36864
	ds_read_b128 v[202:205], v141 offset:55296
	ds_read_b128 v[206:209], v141 offset:59904
	ds_read_b128 v[214:217], v140 offset:41472
	ds_read_b128 v[218:221], v140 offset:36896
	ds_read_b128 v[222:225], v141 offset:55328
	ds_read_b128 v[226:229], v141 offset:59936
	ds_read_b128 v[230:233], v140 offset:41504
	s_waitcnt lgkmcnt(4)
	v_mfma_f32_32x32x16_bf16 v[50:65], v[198:201], v[202:205], v[50:65]
	v_mfma_f32_32x32x16_bf16 v[34:49], v[198:201], v[206:209], v[34:49]
	v_mfma_f32_32x32x16_bf16 v[18:33], v[214:217], v[202:205], v[18:33]
	v_mfma_f32_32x32x16_bf16 v[2:17], v[214:217], v[206:209], v[2:17]
	ds_read_b128 v[198:201], v140 offset:36928
	ds_read_b128 v[202:205], v141 offset:55360
	ds_read_b128 v[206:209], v141 offset:59968
	ds_read_b128 v[214:217], v140 offset:41536
	s_waitcnt lgkmcnt(4)
	v_mfma_f32_32x32x16_bf16 v[50:65], v[218:221], v[222:225], v[50:65]
	v_mfma_f32_32x32x16_bf16 v[34:49], v[218:221], v[226:229], v[34:49]
	v_mfma_f32_32x32x16_bf16 v[18:33], v[230:233], v[222:225], v[18:33]
	v_mfma_f32_32x32x16_bf16 v[2:17], v[230:233], v[226:229], v[2:17]
	ds_read_b128 v[218:221], v140 offset:36960
	ds_read_b128 v[222:225], v141 offset:55392
	ds_read_b128 v[226:229], v141 offset:60000
	ds_read_b128 v[230:233], v140 offset:41568
	s_waitcnt lgkmcnt(4)
	v_mfma_f32_32x32x16_bf16 v[50:65], v[198:201], v[202:205], v[50:65]
	v_mfma_f32_32x32x16_bf16 v[34:49], v[198:201], v[206:209], v[34:49]
	v_mfma_f32_32x32x16_bf16 v[18:33], v[214:217], v[202:205], v[18:33]
	v_mfma_f32_32x32x16_bf16 v[2:17], v[214:217], v[206:209], v[2:17]
	s_waitcnt lgkmcnt(0)
	v_mfma_f32_32x32x16_bf16 v[50:65], v[218:221], v[222:225], v[50:65]
	v_mfma_f32_32x32x16_bf16 v[34:49], v[218:221], v[226:229], v[34:49]
	v_mfma_f32_32x32x16_bf16 v[18:33], v[230:233], v[222:225], v[18:33]
	v_mfma_f32_32x32x16_bf16 v[2:17], v[230:233], v[226:229], v[2:17]
	s_setprio 0
	s_waitcnt vmcnt(8)
	ds_write_b128 v188, v[98:101]
	ds_write_b128 v188, v[102:105] offset:4608
	ds_write_b128 v188, v[106:109] offset:9216
	ds_write_b128 v188, v[110:113] offset:13824
	ds_write_b128 v188, v[114:117] offset:18432
	ds_write_b128 v188, v[118:121] offset:23040
	ds_write_b128 v188, v[122:125] offset:27648
	ds_write_b128 v188, v[126:129] offset:32256
	s_waitcnt lgkmcnt(0)
	s_barrier
	global_load_dwordx4 v[98:101], v[160:161], off offset:1792
	global_load_dwordx4 v[102:105], v[162:163], off offset:1792
	global_load_dwordx4 v[106:109], v[164:165], off offset:1792
	global_load_dwordx4 v[110:113], v[166:167], off offset:1792
	global_load_dwordx4 v[114:117], v[158:159], off offset:1792
	global_load_dwordx4 v[118:121], v[168:169], off offset:1792
	global_load_dwordx4 v[122:125], v[170:171], off offset:1792
	global_load_dwordx4 v[126:129], v[172:173], off offset:1792
	s_setprio 1
	ds_read_b128 v[198:201], v140
	ds_read_b128 v[202:205], v141 offset:18432
	ds_read_b128 v[206:209], v141 offset:23040
	ds_read_b128 v[214:217], v140 offset:4608
	ds_read_b128 v[218:221], v140 offset:32
	ds_read_b128 v[222:225], v141 offset:18464
	ds_read_b128 v[226:229], v141 offset:23072
	ds_read_b128 v[230:233], v140 offset:4640
	s_waitcnt lgkmcnt(4)
	v_mfma_f32_32x32x16_bf16 v[50:65], v[198:201], v[202:205], v[50:65]
	v_mfma_f32_32x32x16_bf16 v[34:49], v[198:201], v[206:209], v[34:49]
	v_mfma_f32_32x32x16_bf16 v[18:33], v[214:217], v[202:205], v[18:33]
	v_mfma_f32_32x32x16_bf16 v[2:17], v[214:217], v[206:209], v[2:17]
	ds_read_b128 v[198:201], v140 offset:64
	ds_read_b128 v[202:205], v141 offset:18496
	ds_read_b128 v[206:209], v141 offset:23104
	ds_read_b128 v[214:217], v140 offset:4672
	s_waitcnt lgkmcnt(4)
	v_mfma_f32_32x32x16_bf16 v[50:65], v[218:221], v[222:225], v[50:65]
	v_mfma_f32_32x32x16_bf16 v[34:49], v[218:221], v[226:229], v[34:49]
	v_mfma_f32_32x32x16_bf16 v[18:33], v[230:233], v[222:225], v[18:33]
	v_mfma_f32_32x32x16_bf16 v[2:17], v[230:233], v[226:229], v[2:17]
	ds_read_b128 v[218:221], v140 offset:96
	ds_read_b128 v[222:225], v141 offset:18528
	ds_read_b128 v[226:229], v141 offset:23136
	ds_read_b128 v[230:233], v140 offset:4704
	s_waitcnt lgkmcnt(4)
	v_mfma_f32_32x32x16_bf16 v[50:65], v[198:201], v[202:205], v[50:65]
	v_mfma_f32_32x32x16_bf16 v[34:49], v[198:201], v[206:209], v[34:49]
	v_mfma_f32_32x32x16_bf16 v[18:33], v[214:217], v[202:205], v[18:33]
	v_mfma_f32_32x32x16_bf16 v[2:17], v[214:217], v[206:209], v[2:17]
	s_waitcnt lgkmcnt(0)
	v_mfma_f32_32x32x16_bf16 v[50:65], v[218:221], v[222:225], v[50:65]
	v_mfma_f32_32x32x16_bf16 v[34:49], v[218:221], v[226:229], v[34:49]
	v_mfma_f32_32x32x16_bf16 v[18:33], v[230:233], v[222:225], v[18:33]
	v_mfma_f32_32x32x16_bf16 v[2:17], v[230:233], v[226:229], v[2:17]
	s_setprio 0
	s_waitcnt vmcnt(8)
	ds_write_b128 v188, v[66:69] offset:36864
	ds_write_b128 v188, v[70:73] offset:41472
	ds_write_b128 v188, v[74:77] offset:46080
	ds_write_b128 v188, v[78:81] offset:50688
	ds_write_b128 v188, v[82:85] offset:55296
	ds_write_b128 v188, v[86:89] offset:59904
	ds_write_b128 v188, v[90:93] offset:64512
	ds_write_b128 v189, v[94:97] offset:13824
	s_waitcnt lgkmcnt(0)
	s_barrier
; __device__ void gemm_phase(const u16* __restrict__ Wb, int ldw, const u16* __restrict__ Xb, int ldx, int K,
;                            u16* __restrict__ outb, int ldo, int ntn, int ntiles, u16* lds) {
;     ...
;     for (int kt = 0; kt < nk; kt += 2) {
;       if (kt + 2 < nk) gs_load(B, gw, ldw, gx, ldx, (kt + 2) * 64);
;       else if (has_next) gs_load(B, gwn, ldw, gxn, ldx, 0);
;       gemm_kstep(lds, wn, wt, r, h, acc);
;       gs_store(A, lds + 2 * TILE_U16, lo);
;       __syncthreads();
;       if (kt + 3 < nk) gs_load(A, gw, ldw, gx, ldx, (kt + 3) * 64);
;       else if (has_next) gs_load(A, gwn, ldw, gxn, ldx, 64);
;       gemm_kstep(lds + 2 * TILE_U16, wn, wt, r, h, acc);
;       if (kt + 2 < nk) gs_store(B, lds, lo);
	global_load_dwordx4 v[66:69], v[160:161], off offset:1920
	global_load_dwordx4 v[70:73], v[162:163], off offset:1920
	global_load_dwordx4 v[74:77], v[164:165], off offset:1920
	global_load_dwordx4 v[78:81], v[166:167], off offset:1920
	global_load_dwordx4 v[82:85], v[158:159], off offset:1920
	global_load_dwordx4 v[86:89], v[168:169], off offset:1920
	global_load_dwordx4 v[90:93], v[170:171], off offset:1920
	global_load_dwordx4 v[94:97], v[172:173], off offset:1920
	s_setprio 1
	ds_read_b128 v[158:161], v140 offset:36864
	ds_read_b128 v[162:165], v141 offset:55296
	ds_read_b128 v[166:169], v141 offset:59904
	ds_read_b128 v[214:217], v140 offset:41472
	ds_read_b128 v[218:221], v140 offset:36896
	ds_read_b128 v[222:225], v141 offset:55328
	ds_read_b128 v[226:229], v141 offset:59936
	ds_read_b128 v[230:233], v140 offset:41504
	s_waitcnt lgkmcnt(4)
	v_mfma_f32_32x32x16_bf16 v[50:65], v[158:161], v[162:165], v[50:65]
	v_mfma_f32_32x32x16_bf16 v[34:49], v[158:161], v[166:169], v[34:49]
	v_mfma_f32_32x32x16_bf16 v[18:33], v[214:217], v[162:165], v[18:33]
	v_mfma_f32_32x32x16_bf16 v[2:17], v[214:217], v[166:169], v[2:17]
	ds_read_b128 v[158:161], v140 offset:36928
	ds_read_b128 v[162:165], v141 offset:55360
	ds_read_b128 v[166:169], v141 offset:59968
	ds_read_b128 v[214:217], v140 offset:41536
	s_waitcnt lgkmcnt(4)
	v_mfma_f32_32x32x16_bf16 v[50:65], v[218:221], v[222:225], v[50:65]
	v_mfma_f32_32x32x16_bf16 v[34:49], v[218:221], v[226:229], v[34:49]
	v_mfma_f32_32x32x16_bf16 v[18:33], v[230:233], v[222:225], v[18:33]
	v_mfma_f32_32x32x16_bf16 v[2:17], v[230:233], v[226:229], v[2:17]
	ds_read_b128 v[218:221], v140 offset:36960
	ds_read_b128 v[222:225], v141 offset:55392
	ds_read_b128 v[226:229], v141 offset:60000
	ds_read_b128 v[230:233], v140 offset:41568
	s_waitcnt lgkmcnt(4)
	v_mfma_f32_32x32x16_bf16 v[50:65], v[158:161], v[162:165], v[50:65]
	v_mfma_f32_32x32x16_bf16 v[34:49], v[158:161], v[166:169], v[34:49]
	v_mfma_f32_32x32x16_bf16 v[18:33], v[214:217], v[162:165], v[18:33]
	v_mfma_f32_32x32x16_bf16 v[2:17], v[214:217], v[166:169], v[2:17]
	s_waitcnt lgkmcnt(0)
	v_mfma_f32_32x32x16_bf16 v[50:65], v[218:221], v[222:225], v[50:65]
	v_mfma_f32_32x32x16_bf16 v[34:49], v[218:221], v[226:229], v[34:49]
	v_mfma_f32_32x32x16_bf16 v[18:33], v[230:233], v[222:225], v[18:33]
	v_mfma_f32_32x32x16_bf16 v[2:17], v[230:233], v[226:229], v[2:17]
	s_setprio 0
	s_and_b64 vcc, exec, s[16:17]
	s_waitcnt vmcnt(8)
	ds_write_b128 v188, v[98:101]
	ds_write_b128 v188, v[102:105] offset:4608
	ds_write_b128 v188, v[106:109] offset:9216
	ds_write_b128 v188, v[110:113] offset:13824
	ds_write_b128 v188, v[114:117] offset:18432
	ds_write_b128 v188, v[118:121] offset:23040
	ds_write_b128 v188, v[122:125] offset:27648
	ds_write_b128 v188, v[126:129] offset:32256
	s_waitcnt lgkmcnt(0)
	s_barrier
	s_cbranch_vccnz .LBB0_600
	v_add_co_u32_e32 v102, vcc, 0x10000, v132
	global_load_dwordx4 v[98:101], v[132:133], off
	s_nop 0
	v_addc_co_u32_e32 v103, vcc, 0, v133, vcc
	v_add_co_u32_e32 v106, vcc, 0x20000, v132
	s_nop 1
	v_addc_co_u32_e32 v107, vcc, 0, v133, vcc
	v_add_co_u32_e32 v110, vcc, 0x30000, v132
	global_load_dwordx4 v[102:105], v[102:103], off
	s_nop 0
	global_load_dwordx4 v[106:109], v[106:107], off
	v_addc_co_u32_e32 v111, vcc, 0, v133, vcc
	v_add_co_u32_e32 v118, vcc, 0x10000, v134
	global_load_dwordx4 v[110:113], v[110:111], off
	s_nop 0
	global_load_dwordx4 v[114:117], v[134:135], off
	v_addc_co_u32_e32 v119, vcc, 0, v135, vcc
	v_add_co_u32_e32 v122, vcc, 0x20000, v134
	s_nop 1
	v_addc_co_u32_e32 v123, vcc, 0, v135, vcc
	v_add_co_u32_e32 v126, vcc, 0x30000, v134
	global_load_dwordx4 v[118:121], v[118:119], off
	s_nop 0
	global_load_dwordx4 v[122:125], v[122:123], off
	v_addc_co_u32_e32 v127, vcc, 0, v135, vcc
	global_load_dwordx4 v[126:129], v[126:127], off
; __device__ void gemm_phase(const u16* __restrict__ Wb, int ldw, const u16* __restrict__ Xb, int ldx, int K,
;                            u16* __restrict__ outb, int ldo, int ntn, int ntiles, u16* lds) {
;     ...
;       if (kt + 3 < nk) gs_load(A, gw, ldw, gx, ldx, (kt + 3) * 64);
;       else if (has_next) gs_load(A, gwn, ldw, gxn, ldx, 64);
;       gemm_kstep(lds + 2 * TILE_U16, wn, wt, r, h, acc);
;       if (kt + 2 < nk) gs_store(B, lds, lo);
;       __syncthreads();
.LBB0_600:
	s_setprio 1
	ds_read_b128 v[158:161], v140
	ds_read_b128 v[162:165], v141 offset:18432
	ds_read_b128 v[166:169], v141 offset:23040
	ds_read_b128 v[214:217], v140 offset:4608
	ds_read_b128 v[218:221], v140 offset:32
	ds_read_b128 v[222:225], v141 offset:18464
	ds_read_b128 v[226:229], v141 offset:23072
	ds_read_b128 v[230:233], v140 offset:4640
	s_waitcnt lgkmcnt(4)
	v_mfma_f32_32x32x16_bf16 v[50:65], v[158:161], v[162:165], v[50:65]
	v_mfma_f32_32x32x16_bf16 v[34:49], v[158:161], v[166:169], v[34:49]
	v_mfma_f32_32x32x16_bf16 v[18:33], v[214:217], v[162:165], v[18:33]
	v_mfma_f32_32x32x16_bf16 v[2:17], v[214:217], v[166:169], v[2:17]
	ds_read_b128 v[158:161], v140 offset:64
	ds_read_b128 v[162:165], v141 offset:18496
	ds_read_b128 v[166:169], v141 offset:23104
	ds_read_b128 v[214:217], v140 offset:4672
	s_waitcnt lgkmcnt(4)
	v_mfma_f32_32x32x16_bf16 v[50:65], v[218:221], v[222:225], v[50:65]
	v_mfma_f32_32x32x16_bf16 v[34:49], v[218:221], v[226:229], v[34:49]
	v_mfma_f32_32x32x16_bf16 v[18:33], v[230:233], v[222:225], v[18:33]
	v_mfma_f32_32x32x16_bf16 v[2:17], v[230:233], v[226:229], v[2:17]
	ds_read_b128 v[218:221], v140 offset:96
	ds_read_b128 v[222:225], v141 offset:18528
	ds_read_b128 v[226:229], v141 offset:23136
	ds_read_b128 v[230:233], v140 offset:4704
	s_waitcnt lgkmcnt(4)
	v_mfma_f32_32x32x16_bf16 v[50:65], v[158:161], v[162:165], v[50:65]
	v_mfma_f32_32x32x16_bf16 v[34:49], v[158:161], v[166:169], v[34:49]
	v_mfma_f32_32x32x16_bf16 v[18:33], v[214:217], v[162:165], v[18:33]
	v_mfma_f32_32x32x16_bf16 v[2:17], v[214:217], v[166:169], v[2:17]
	s_waitcnt lgkmcnt(0)
	v_mfma_f32_32x32x16_bf16 v[50:65], v[218:221], v[222:225], v[50:65]
	v_mfma_f32_32x32x16_bf16 v[34:49], v[218:221], v[226:229], v[34:49]
	v_mfma_f32_32x32x16_bf16 v[18:33], v[230:233], v[222:225], v[18:33]
	v_mfma_f32_32x32x16_bf16 v[2:17], v[230:233], v[226:229], v[2:17]
	s_setprio 0
	s_andn2_b64 vcc, exec, s[0:1]
	s_waitcnt vmcnt(0)
	ds_write_b128 v188, v[66:69] offset:36864
	ds_write_b128 v188, v[70:73] offset:41472
	ds_write_b128 v188, v[74:77] offset:46080
	ds_write_b128 v188, v[78:81] offset:50688
	ds_write_b128 v188, v[82:85] offset:55296
	ds_write_b128 v188, v[86:89] offset:59904
	ds_write_b128 v188, v[90:93] offset:64512
	ds_write_b128 v189, v[94:97] offset:13824
	s_waitcnt lgkmcnt(0)
	s_barrier
	s_cbranch_vccnz .LBB0_597
	v_add_co_u32_e32 v70, vcc, 0x10000, v132
	global_load_dwordx4 v[66:69], v[132:133], off offset:128
	s_nop 0
	v_addc_co_u32_e32 v71, vcc, 0, v133, vcc
	v_add_co_u32_e32 v74, vcc, 0x20000, v132
	s_nop 1
	v_addc_co_u32_e32 v75, vcc, 0, v133, vcc
	v_add_co_u32_e32 v78, vcc, 0x30000, v132
	global_load_dwordx4 v[70:73], v[70:71], off offset:128
	s_nop 0
	global_load_dwordx4 v[74:77], v[74:75], off offset:128
	v_addc_co_u32_e32 v79, vcc, 0, v133, vcc
	v_add_co_u32_e32 v86, vcc, 0x10000, v134
	global_load_dwordx4 v[78:81], v[78:79], off offset:128
	s_nop 0
	global_load_dwordx4 v[82:85], v[134:135], off offset:128
	v_addc_co_u32_e32 v87, vcc, 0, v135, vcc
	v_add_co_u32_e32 v90, vcc, 0x20000, v134
	s_nop 1
	v_addc_co_u32_e32 v91, vcc, 0, v135, vcc
	v_add_co_u32_e32 v94, vcc, 0x30000, v134
	global_load_dwordx4 v[86:89], v[86:87], off offset:128
	s_nop 0
	global_load_dwordx4 v[90:93], v[90:91], off offset:128
	v_addc_co_u32_e32 v95, vcc, 0, v135, vcc
	global_load_dwordx4 v[94:97], v[94:95], off offset:128
	s_branch .LBB0_597

; __device__ void gemm_phase(const u16* __restrict__ Wb, int ldw, const u16* __restrict__ Xb, int ldx, int K,
;                            u16* __restrict__ outb, int ldo, int ntn, int ntiles, u16* lds) {
;     ...
;       gemm_kstep(lds + 2 * TILE_U16, wn, wt, r, h, acc);
;       if (kt + 2 < nk) gs_store(B, lds, lo);
;       __syncthreads();
;     }
;     stage_bf16(lds, acc);
;     __syncthreads();
;     u16* out = outb + (size_t)GP_MT(q) * 128 * ldo + GP_NT(q) * 128;
; #pragma unroll
;     for (int i = 0; i < 8; ++i) {
;       const int id = tid + 256 * i;
;       const int row = id >> 4, c = id & 15;
;       uint4 v = *(const uint4*)(lds + row * 136 + c * 8);
;       *(uint4*)(out + (size_t)row * ldo + c * 8) = v;
;     }
;     __syncthreads();
.LBB0_608:
	s_setprio 1
	ds_read_b128 v[158:161], v140 offset:36864
	ds_read_b128 v[162:165], v141 offset:55296
	ds_read_b128 v[166:169], v141 offset:59904
	ds_read_b128 v[214:217], v140 offset:41472
	ds_read_b128 v[218:221], v140 offset:36896
	ds_read_b128 v[222:225], v141 offset:55328
	ds_read_b128 v[226:229], v141 offset:59936
	ds_read_b128 v[230:233], v140 offset:41504
	s_waitcnt lgkmcnt(4)
	v_mfma_f32_32x32x16_bf16 v[50:65], v[158:161], v[162:165], v[50:65]
	v_mfma_f32_32x32x16_bf16 v[34:49], v[158:161], v[166:169], v[34:49]
	v_mfma_f32_32x32x16_bf16 v[18:33], v[214:217], v[162:165], v[18:33]
	v_mfma_f32_32x32x16_bf16 v[2:17], v[214:217], v[166:169], v[2:17]
	ds_read_b128 v[158:161], v140 offset:36928
	ds_read_b128 v[162:165], v141 offset:55360
	ds_read_b128 v[166:169], v141 offset:59968
	ds_read_b128 v[214:217], v140 offset:41536
	s_waitcnt lgkmcnt(4)
	v_mfma_f32_32x32x16_bf16 v[50:65], v[218:221], v[222:225], v[50:65]
	v_mfma_f32_32x32x16_bf16 v[34:49], v[218:221], v[226:229], v[34:49]
	v_mfma_f32_32x32x16_bf16 v[18:33], v[230:233], v[222:225], v[18:33]
	v_mfma_f32_32x32x16_bf16 v[2:17], v[230:233], v[226:229], v[2:17]
	ds_read_b128 v[218:221], v140 offset:36960
	ds_read_b128 v[222:225], v141 offset:55392
	ds_read_b128 v[226:229], v141 offset:60000
	ds_read_b128 v[230:233], v140 offset:41568
	s_waitcnt lgkmcnt(4)
	v_mfma_f32_32x32x16_bf16 v[50:65], v[158:161], v[162:165], v[50:65]
	v_mfma_f32_32x32x16_bf16 v[34:49], v[158:161], v[166:169], v[34:49]
	v_mfma_f32_32x32x16_bf16 v[18:33], v[214:217], v[162:165], v[18:33]
	v_mfma_f32_32x32x16_bf16 v[2:17], v[214:217], v[166:169], v[2:17]
	s_waitcnt lgkmcnt(0)
	v_mfma_f32_32x32x16_bf16 v[50:65], v[218:221], v[222:225], v[50:65]
	v_mfma_f32_32x32x16_bf16 v[34:49], v[218:221], v[226:229], v[34:49]
	v_mfma_f32_32x32x16_bf16 v[18:33], v[230:233], v[222:225], v[18:33]
	v_mfma_f32_32x32x16_bf16 v[2:17], v[230:233], v[226:229], v[2:17]
	s_setprio 0
	v_mov_b32_e32 v158, v174
	s_lshr_b32 s38, s41, 3
	s_barrier
	s_and_b32 s38, s38, 0xffffff8
	v_lshrrev_b32_e32 v160, 2, v158
	v_and_b32_e32 v160, 8, v160
	s_add_i32 s38, s38, s18
	s_and_b32 s39, s41, 7
	v_and_b32_e32 v159, 0x5f, v158
	v_and_or_b32 v158, v158, s29, v160
	s_or_b32 s82, s38, s39
	v_mad_u32_u24 v158, v159, s28, v158
	s_lshl_b64 s[38:39], s[82:83], 18
	v_cvt_pk_bf16_f32 v53, v52, v53
	v_cvt_pk_bf16_f32 v52, v50, v51
	v_cvt_pk_bf16_f32 v51, v56, v57
	v_cvt_pk_bf16_f32 v50, v54, v55
	v_cvt_pk_bf16_f32 v37, v36, v37
	v_cvt_pk_bf16_f32 v36, v34, v35
	v_cvt_pk_bf16_f32 v35, v40, v41
	v_cvt_pk_bf16_f32 v34, v38, v39
	v_add_u32_e32 v38, 0x2000, v158
	v_cvt_pk_bf16_f32 v21, v20, v21
	v_cvt_pk_bf16_f32 v20, v18, v19
	v_cvt_pk_bf16_f32 v19, v24, v25
	v_cvt_pk_bf16_f32 v18, v22, v23
	v_cvt_pk_bf16_f32 v5, v4, v5
	v_cvt_pk_bf16_f32 v4, v2, v3
	v_cvt_pk_bf16_f32 v3, v8, v9
	v_cvt_pk_bf16_f32 v2, v6, v7
	s_add_u32 s38, s16, s38
	ds_write2_b64 v158, v[52:53], v[50:51] offset1:2
	v_cvt_pk_bf16_f32 v51, v60, v61
	v_cvt_pk_bf16_f32 v50, v58, v59
	v_cvt_pk_bf16_f32 v53, v64, v65
	v_cvt_pk_bf16_f32 v52, v62, v63
	ds_write2_b64 v38, v[36:37], v[34:35] offset0:64 offset1:66
	v_cvt_pk_bf16_f32 v35, v44, v45
	v_cvt_pk_bf16_f32 v34, v42, v43
	v_cvt_pk_bf16_f32 v37, v48, v49
	v_cvt_pk_bf16_f32 v36, v46, v47
	ds_write2_b64 v158, v[20:21], v[18:19] offset0:8 offset1:10
	v_cvt_pk_bf16_f32 v19, v28, v29
	v_cvt_pk_bf16_f32 v18, v26, v27
	v_cvt_pk_bf16_f32 v21, v32, v33
	v_cvt_pk_bf16_f32 v20, v30, v31
	ds_write2_b64 v38, v[4:5], v[2:3] offset0:72 offset1:74
	v_cvt_pk_bf16_f32 v3, v12, v13
	v_cvt_pk_bf16_f32 v2, v10, v11
	v_cvt_pk_bf16_f32 v5, v16, v17
	v_cvt_pk_bf16_f32 v4, v14, v15
	s_addc_u32 s39, s17, s39
	s_and_b32 s41, s40, 0x380
	ds_write2_b64 v158, v[50:51], v[52:53] offset0:4 offset1:6
	ds_write2_b64 v38, v[34:35], v[36:37] offset0:68 offset1:70
	ds_write2_b64 v158, v[18:19], v[20:21] offset0:12 offset1:14
	ds_write2_b64 v38, v[2:3], v[4:5] offset0:76 offset1:78
	s_waitcnt lgkmcnt(0)
	s_barrier
	s_lshl_b32 s41, s41, 1
	ds_read_b128 v[2:5], v190
	ds_read_b128 v[6:9], v191
	s_add_u32 s38, s38, s41
	s_addc_u32 s39, s39, 0
	v_lshl_add_u64 v[14:15], s[38:39], 0, v[0:1]
	v_lshl_add_u64 v[10:11], v[14:15], 0, v[142:143]
	s_waitcnt lgkmcnt(1)
	global_store_dwordx4 v[10:11], v[2:5], off
	ds_read_b128 v[2:5], v192
	v_lshl_add_u64 v[10:11], v[14:15], 0, v[144:145]
	s_waitcnt lgkmcnt(1)
	global_store_dwordx4 v[10:11], v[6:9], off
	ds_read_b128 v[6:9], v193
	v_lshl_add_u64 v[10:11], v[14:15], 0, v[146:147]
	s_waitcnt lgkmcnt(1)
	global_store_dwordx4 v[10:11], v[2:5], off
	ds_read_b128 v[2:5], v194
	v_lshl_add_u64 v[10:11], v[14:15], 0, v[148:149]
	s_waitcnt lgkmcnt(1)
	global_store_dwordx4 v[10:11], v[6:9], off
	v_lshl_add_u64 v[10:11], v[14:15], 0, v[150:151]
	ds_read_b128 v[6:9], v195
	s_waitcnt lgkmcnt(1)
	global_store_dwordx4 v[10:11], v[2:5], off
	ds_read_b128 v[2:5], v196
	ds_read_b128 v[10:13], v197
	v_lshl_add_u64 v[16:17], v[14:15], 0, v[152:153]
	s_waitcnt lgkmcnt(2)
	global_store_dwordx4 v[16:17], v[6:9], off
	s_add_i32 s40, s40, s77
	s_and_b64 vcc, exec, s[0:1]
	v_lshl_add_u64 v[6:7], v[14:15], 0, v[154:155]
	s_waitcnt lgkmcnt(1)
	global_store_dwordx4 v[6:7], v[2:5], off
	s_mov_b32 s41, s42
	s_nop 0
	v_lshl_add_u64 v[2:3], v[14:15], 0, v[156:157]
	s_waitcnt lgkmcnt(0)
	global_store_dwordx4 v[2:3], v[10:13], off
	s_barrier
	s_cbranch_vccnz .LBB0_613
; __device__ void gemm_phase(const u16* __restrict__ Wb, int ldw, const u16* __restrict__ Xb, int ldx, int K,
;                            u16* __restrict__ outb, int ldo, int ntn, int ntiles, u16* lds) {
;     ...
;   for (; q < L; q += nbl) {
;     const int qn = q + nbl;
;     const bool has_next = qn < L;
;     const int qq = has_next ? qn : q;
;     const u16* gwn = Wb + (size_t)(GP_NT(qq) * 128 + lrow) * ldw + lc * 8;
;     const u16* gxn = Xb + (size_t)(GP_MT(qq) * 128 + lrow) * ldx + lc * 8;
;     f32x16 acc[2][2];
; #pragma unroll
;     for (int a = 0; a < 2; ++a)
; #pragma unroll
;       for (int b = 0; b < 2; ++b)
; #pragma unroll
;         for (int i = 0; i < 16; ++i) acc[a][b][i] = 0.f;
;     gs_store(B, lds, lo);
;     __syncthreads();
;     for (int kt = 0; kt < nk; kt += 2) {
;       if (kt + 2 < nk) gs_load(B, gw, ldw, gx, ldx, (kt + 2) * 64);
;       else if (has_next) gs_load(B, gwn, ldw, gxn, ldx, 0);
;       gemm_kstep(lds, wn, wt, r, h, acc);
;       gs_store(A, lds + 2 * TILE_U16, lo);
;       __syncthreads();
;       if (kt + 3 < nk) gs_load(A, gw, ldw, gx, ldx, (kt + 3) * 64);
.LBB0_609:
	v_mov_b64_e32 v[160:161], v[132:133]
	v_add_co_u32_e32 v162, vcc, s81, v160
	v_mov_b64_e32 v[158:159], v[134:135]
	s_nop 0
	v_addc_co_u32_e32 v163, vcc, 0, v161, vcc
	v_add_co_u32_e32 v164, vcc, s80, v160
	s_waitcnt vmcnt(1)
	ds_write_b128 v188, v[86:89]
	ds_write_b128 v188, v[98:101] offset:4608
	ds_write_b128 v188, v[102:105] offset:9216
	ds_write_b128 v188, v[110:113] offset:13824
	ds_write_b128 v188, v[114:117] offset:18432
	ds_write_b128 v188, v[118:121] offset:23040
	ds_write_b128 v188, v[122:125] offset:27648
	ds_write_b128 v188, v[126:129] offset:32256
	v_addc_co_u32_e32 v165, vcc, 0, v161, vcc
	v_add_co_u32_e32 v166, vcc, s84, v160
	s_waitcnt lgkmcnt(0)
	s_nop 0
	v_addc_co_u32_e32 v167, vcc, 0, v161, vcc
	v_add_co_u32_e32 v168, vcc, s81, v158
	s_barrier
	s_nop 0
	v_addc_co_u32_e32 v169, vcc, 0, v159, vcc
	v_add_co_u32_e32 v170, vcc, s80, v158
	s_nop 1
	v_addc_co_u32_e32 v171, vcc, 0, v159, vcc
	v_add_co_u32_e32 v172, vcc, s84, v158
	global_load_dwordx4 v[86:89], v[132:133], off offset:256
	s_nop 0
	v_addc_co_u32_e32 v173, vcc, 0, v159, vcc
	global_load_dwordx4 v[98:101], v[162:163], off offset:256
	global_load_dwordx4 v[102:105], v[164:165], off offset:256
	global_load_dwordx4 v[110:113], v[166:167], off offset:256
	global_load_dwordx4 v[114:117], v[134:135], off offset:256
	global_load_dwordx4 v[118:121], v[168:169], off offset:256
	global_load_dwordx4 v[122:125], v[170:171], off offset:256
	global_load_dwordx4 v[126:129], v[172:173], off offset:256
	s_add_i32 s42, s41, s87
	s_cmpk_gt_u32 s42, 0xff
	s_cselect_b64 s[0:1], -1, 0
	s_cmpk_lt_u32 s42, 0x100
	s_cselect_b64 s[38:39], -1, 0
	s_and_b64 s[44:45], s[38:39], exec
	s_cselect_b32 s43, s42, s41
	s_lshl_b32 s44, s43, 4
	s_and_b32 s43, s43, 7
	s_or_b32 s43, s43, s18
	s_and_b32 s45, s44, 0x380
	s_and_b32 s44, s44, 0xfffffc00
	s_lshl_b32 s43, s43, 7
	s_add_i32 s43, s43, s44
	v_add_u32_e32 v2, s45, v131
	v_add_u32_e32 v4, s43, v131
	v_ashrrev_i32_e32 v3, 31, v2
	v_ashrrev_i32_e32 v5, 31, v4
	v_lshlrev_b64 v[2:3], 11, v[2:3]
	v_lshlrev_b64 v[4:5], 11, v[4:5]
	v_lshl_add_u64 v[132:133], v[136:137], 0, v[2:3]
	v_lshl_add_u64 v[134:135], v[138:139], 0, v[4:5]
	s_setprio 1
	ds_read_b128 v[2:5], v140
	ds_read_b128 v[6:9], v141 offset:18432
	ds_read_b128 v[10:13], v141 offset:23040
	s_waitcnt lgkmcnt(1)
	v_mfma_f32_32x32x16_bf16 v[50:65], v[2:5], v[6:9], 0
	s_waitcnt lgkmcnt(0)
	v_mfma_f32_32x32x16_bf16 v[34:49], v[2:5], v[10:13], 0
	ds_read_b128 v[2:5], v140 offset:4608
	ds_read_b128 v[198:201], v140 offset:32
	ds_read_b128 v[202:205], v141 offset:18464
	ds_read_b128 v[206:209], v141 offset:23072
	s_waitcnt lgkmcnt(1)
	v_mfma_f32_32x32x16_bf16 v[50:65], v[198:201], v[202:205], v[50:65]
	s_waitcnt lgkmcnt(0)
	v_mfma_f32_32x32x16_bf16 v[34:49], v[198:201], v[206:209], v[34:49]
	ds_read_b128 v[198:201], v140 offset:4640
	v_mfma_f32_32x32x16_bf16 v[18:33], v[2:5], v[6:9], 0
	v_mfma_f32_32x32x16_bf16 v[2:17], v[2:5], v[10:13], 0
	s_waitcnt lgkmcnt(0)
	v_mfma_f32_32x32x16_bf16 v[18:33], v[198:201], v[202:205], v[18:33]
	v_mfma_f32_32x32x16_bf16 v[2:17], v[198:201], v[206:209], v[2:17]
	ds_read_b128 v[198:201], v140 offset:64
	ds_read_b128 v[202:205], v141 offset:18496
	ds_read_b128 v[206:209], v141 offset:23104
	s_waitcnt lgkmcnt(1)
	v_mfma_f32_32x32x16_bf16 v[50:65], v[198:201], v[202:205], v[50:65]
	s_waitcnt lgkmcnt(0)
	v_mfma_f32_32x32x16_bf16 v[34:49], v[198:201], v[206:209], v[34:49]
	ds_read_b128 v[198:201], v140 offset:4672
	s_waitcnt lgkmcnt(0)
	v_mfma_f32_32x32x16_bf16 v[18:33], v[198:201], v[202:205], v[18:33]
	v_mfma_f32_32x32x16_bf16 v[2:17], v[198:201], v[206:209], v[2:17]
	ds_read_b128 v[198:201], v140 offset:96
	ds_read_b128 v[202:205], v141 offset:18528
	ds_read_b128 v[206:209], v141 offset:23136
	s_waitcnt lgkmcnt(1)
	v_mfma_f32_32x32x16_bf16 v[50:65], v[198:201], v[202:205], v[50:65]
	s_waitcnt lgkmcnt(0)
	v_mfma_f32_32x32x16_bf16 v[34:49], v[198:201], v[206:209], v[34:49]
	ds_read_b128 v[198:201], v140 offset:4704
	s_waitcnt lgkmcnt(0)
	v_mfma_f32_32x32x16_bf16 v[18:33], v[198:201], v[202:205], v[18:33]
	v_mfma_f32_32x32x16_bf16 v[2:17], v[198:201], v[206:209], v[2:17]
	s_setprio 0
	ds_write_b128 v188, v[66:69] offset:36864
	ds_write_b128 v188, v[70:73] offset:41472
	ds_write_b128 v188, v[74:77] offset:46080
	ds_write_b128 v188, v[78:81] offset:50688
	ds_write_b128 v188, v[82:85] offset:55296
	ds_write_b128 v188, v[90:93] offset:59904
	ds_write_b128 v188, v[94:97] offset:64512
	s_waitcnt vmcnt(8)
	ds_write_b128 v189, v[106:109] offset:13824
	s_waitcnt lgkmcnt(0)
	s_barrier
; __device__ void gemm_phase(const u16* __restrict__ Wb, int ldw, const u16* __restrict__ Xb, int ldx, int K,
;                            u16* __restrict__ outb, int ldo, int ntn, int ntiles, u16* lds) {
;     ...
;     for (int kt = 0; kt < nk; kt += 2) {
;       if (kt + 2 < nk) gs_load(B, gw, ldw, gx, ldx, (kt + 2) * 64);
;       else if (has_next) gs_load(B, gwn, ldw, gxn, ldx, 0);
;       gemm_kstep(lds, wn, wt, r, h, acc);
;       gs_store(A, lds + 2 * TILE_U16, lo);
;       __syncthreads();
;       if (kt + 3 < nk) gs_load(A, gw, ldw, gx, ldx, (kt + 3) * 64);
;       else if (has_next) gs_load(A, gwn, ldw, gxn, ldx, 64);
;       gemm_kstep(lds + 2 * TILE_U16, wn, wt, r, h, acc);
;       if (kt + 2 < nk) gs_store(B, lds, lo);
;       __syncthreads();
	global_load_dwordx4 v[66:69], v[160:161], off offset:384
	global_load_dwordx4 v[70:73], v[162:163], off offset:384
	global_load_dwordx4 v[74:77], v[164:165], off offset:384
	global_load_dwordx4 v[78:81], v[166:167], off offset:384
	global_load_dwordx4 v[82:85], v[158:159], off offset:384
	global_load_dwordx4 v[90:93], v[168:169], off offset:384
	global_load_dwordx4 v[94:97], v[170:171], off offset:384
	global_load_dwordx4 v[106:109], v[172:173], off offset:384
	s_setprio 1
	ds_read_b128 v[198:201], v140 offset:36864
	ds_read_b128 v[202:205], v141 offset:55296
	ds_read_b128 v[206:209], v141 offset:59904
	ds_read_b128 v[214:217], v140 offset:41472
	ds_read_b128 v[218:221], v140 offset:36896
	ds_read_b128 v[222:225], v141 offset:55328
	ds_read_b128 v[226:229], v141 offset:59936
	ds_read_b128 v[230:233], v140 offset:41504
	s_waitcnt lgkmcnt(4)
	v_mfma_f32_32x32x16_bf16 v[50:65], v[198:201], v[202:205], v[50:65]
	v_mfma_f32_32x32x16_bf16 v[34:49], v[198:201], v[206:209], v[34:49]
	v_mfma_f32_32x32x16_bf16 v[18:33], v[214:217], v[202:205], v[18:33]
	v_mfma_f32_32x32x16_bf16 v[2:17], v[214:217], v[206:209], v[2:17]
	ds_read_b128 v[198:201], v140 offset:36928
	ds_read_b128 v[202:205], v141 offset:55360
	ds_read_b128 v[206:209], v141 offset:59968
	ds_read_b128 v[214:217], v140 offset:41536
	s_waitcnt lgkmcnt(4)
	v_mfma_f32_32x32x16_bf16 v[50:65], v[218:221], v[222:225], v[50:65]
	v_mfma_f32_32x32x16_bf16 v[34:49], v[218:221], v[226:229], v[34:49]
	v_mfma_f32_32x32x16_bf16 v[18:33], v[230:233], v[222:225], v[18:33]
	v_mfma_f32_32x32x16_bf16 v[2:17], v[230:233], v[226:229], v[2:17]
	ds_read_b128 v[218:221], v140 offset:36960
	ds_read_b128 v[222:225], v141 offset:55392
	ds_read_b128 v[226:229], v141 offset:60000
	ds_read_b128 v[230:233], v140 offset:41568
	s_waitcnt lgkmcnt(4)
	v_mfma_f32_32x32x16_bf16 v[50:65], v[198:201], v[202:205], v[50:65]
	v_mfma_f32_32x32x16_bf16 v[34:49], v[198:201], v[206:209], v[34:49]
	v_mfma_f32_32x32x16_bf16 v[18:33], v[214:217], v[202:205], v[18:33]
	v_mfma_f32_32x32x16_bf16 v[2:17], v[214:217], v[206:209], v[2:17]
	s_waitcnt lgkmcnt(0)
	v_mfma_f32_32x32x16_bf16 v[50:65], v[218:221], v[222:225], v[50:65]
	v_mfma_f32_32x32x16_bf16 v[34:49], v[218:221], v[226:229], v[34:49]
	v_mfma_f32_32x32x16_bf16 v[18:33], v[230:233], v[222:225], v[18:33]
	v_mfma_f32_32x32x16_bf16 v[2:17], v[230:233], v[226:229], v[2:17]
	s_setprio 0
	s_waitcnt vmcnt(8)
	ds_write_b128 v188, v[86:89]
	ds_write_b128 v188, v[98:101] offset:4608
	ds_write_b128 v188, v[102:105] offset:9216
	ds_write_b128 v188, v[110:113] offset:13824
	ds_write_b128 v188, v[114:117] offset:18432
	ds_write_b128 v188, v[118:121] offset:23040
	ds_write_b128 v188, v[122:125] offset:27648
	ds_write_b128 v188, v[126:129] offset:32256
	s_waitcnt lgkmcnt(0)
	s_barrier
	global_load_dwordx4 v[86:89], v[160:161], off offset:512
	global_load_dwordx4 v[98:101], v[162:163], off offset:512
	global_load_dwordx4 v[102:105], v[164:165], off offset:512
	global_load_dwordx4 v[110:113], v[166:167], off offset:512
	global_load_dwordx4 v[114:117], v[158:159], off offset:512
	global_load_dwordx4 v[118:121], v[168:169], off offset:512
	global_load_dwordx4 v[122:125], v[170:171], off offset:512
	global_load_dwordx4 v[126:129], v[172:173], off offset:512
	s_setprio 1
	ds_read_b128 v[198:201], v140
	ds_read_b128 v[202:205], v141 offset:18432
	ds_read_b128 v[206:209], v141 offset:23040
	ds_read_b128 v[214:217], v140 offset:4608
	ds_read_b128 v[218:221], v140 offset:32
	ds_read_b128 v[222:225], v141 offset:18464
	ds_read_b128 v[226:229], v141 offset:23072
	ds_read_b128 v[230:233], v140 offset:4640
	s_waitcnt lgkmcnt(4)
	v_mfma_f32_32x32x16_bf16 v[50:65], v[198:201], v[202:205], v[50:65]
	v_mfma_f32_32x32x16_bf16 v[34:49], v[198:201], v[206:209], v[34:49]
	v_mfma_f32_32x32x16_bf16 v[18:33], v[214:217], v[202:205], v[18:33]
	v_mfma_f32_32x32x16_bf16 v[2:17], v[214:217], v[206:209], v[2:17]
	ds_read_b128 v[198:201], v140 offset:64
	ds_read_b128 v[202:205], v141 offset:18496
	ds_read_b128 v[206:209], v141 offset:23104
	ds_read_b128 v[214:217], v140 offset:4672
	s_waitcnt lgkmcnt(4)
	v_mfma_f32_32x32x16_bf16 v[50:65], v[218:221], v[222:225], v[50:65]
	v_mfma_f32_32x32x16_bf16 v[34:49], v[218:221], v[226:229], v[34:49]
	v_mfma_f32_32x32x16_bf16 v[18:33], v[230:233], v[222:225], v[18:33]
	v_mfma_f32_32x32x16_bf16 v[2:17], v[230:233], v[226:229], v[2:17]
	ds_read_b128 v[218:221], v140 offset:96
	ds_read_b128 v[222:225], v141 offset:18528
	ds_read_b128 v[226:229], v141 offset:23136
	ds_read_b128 v[230:233], v140 offset:4704
	s_waitcnt lgkmcnt(4)
	v_mfma_f32_32x32x16_bf16 v[50:65], v[198:201], v[202:205], v[50:65]
	v_mfma_f32_32x32x16_bf16 v[34:49], v[198:201], v[206:209], v[34:49]
	v_mfma_f32_32x32x16_bf16 v[18:33], v[214:217], v[202:205], v[18:33]
	v_mfma_f32_32x32x16_bf16 v[2:17], v[214:217], v[206:209], v[2:17]
	s_waitcnt lgkmcnt(0)
	v_mfma_f32_32x32x16_bf16 v[50:65], v[218:221], v[222:225], v[50:65]
	v_mfma_f32_32x32x16_bf16 v[34:49], v[218:221], v[226:229], v[34:49]
	v_mfma_f32_32x32x16_bf16 v[18:33], v[230:233], v[222:225], v[18:33]
	v_mfma_f32_32x32x16_bf16 v[2:17], v[230:233], v[226:229], v[2:17]
	s_setprio 0
	s_waitcnt vmcnt(8)
	ds_write_b128 v188, v[66:69] offset:36864
	ds_write_b128 v188, v[70:73] offset:41472
	ds_write_b128 v188, v[74:77] offset:46080
	ds_write_b128 v188, v[78:81] offset:50688
	ds_write_b128 v188, v[82:85] offset:55296
	ds_write_b128 v188, v[90:93] offset:59904
	ds_write_b128 v188, v[94:97] offset:64512
	ds_write_b128 v189, v[106:109] offset:13824
	s_waitcnt lgkmcnt(0)
	s_barrier
; __device__ void gemm_phase(const u16* __restrict__ Wb, int ldw, const u16* __restrict__ Xb, int ldx, int K,
;                            u16* __restrict__ outb, int ldo, int ntn, int ntiles, u16* lds) {
;     ...
;     for (int kt = 0; kt < nk; kt += 2) {
;       if (kt + 2 < nk) gs_load(B, gw, ldw, gx, ldx, (kt + 2) * 64);
;       else if (has_next) gs_load(B, gwn, ldw, gxn, ldx, 0);
;       gemm_kstep(lds, wn, wt, r, h, acc);
;       gs_store(A, lds + 2 * TILE_U16, lo);
;       __syncthreads();
;       if (kt + 3 < nk) gs_load(A, gw, ldw, gx, ldx, (kt + 3) * 64);
;       else if (has_next) gs_load(A, gwn, ldw, gxn, ldx, 64);
;       gemm_kstep(lds + 2 * TILE_U16, wn, wt, r, h, acc);
;       if (kt + 2 < nk) gs_store(B, lds, lo);
;       __syncthreads();
	global_load_dwordx4 v[66:69], v[160:161], off offset:640
	global_load_dwordx4 v[70:73], v[162:163], off offset:640
	global_load_dwordx4 v[74:77], v[164:165], off offset:640
	global_load_dwordx4 v[78:81], v[166:167], off offset:640
	global_load_dwordx4 v[82:85], v[158:159], off offset:640
	global_load_dwordx4 v[90:93], v[168:169], off offset:640
	global_load_dwordx4 v[94:97], v[170:171], off offset:640
	global_load_dwordx4 v[106:109], v[172:173], off offset:640
	s_setprio 1
	ds_read_b128 v[198:201], v140 offset:36864
	ds_read_b128 v[202:205], v141 offset:55296
	ds_read_b128 v[206:209], v141 offset:59904
	ds_read_b128 v[214:217], v140 offset:41472
	ds_read_b128 v[218:221], v140 offset:36896
	ds_read_b128 v[222:225], v141 offset:55328
	ds_read_b128 v[226:229], v141 offset:59936
	ds_read_b128 v[230:233], v140 offset:41504
	s_waitcnt lgkmcnt(4)
	v_mfma_f32_32x32x16_bf16 v[50:65], v[198:201], v[202:205], v[50:65]
	v_mfma_f32_32x32x16_bf16 v[34:49], v[198:201], v[206:209], v[34:49]
	v_mfma_f32_32x32x16_bf16 v[18:33], v[214:217], v[202:205], v[18:33]
	v_mfma_f32_32x32x16_bf16 v[2:17], v[214:217], v[206:209], v[2:17]
	ds_read_b128 v[198:201], v140 offset:36928
	ds_read_b128 v[202:205], v141 offset:55360
	ds_read_b128 v[206:209], v141 offset:59968
	ds_read_b128 v[214:217], v140 offset:41536
	s_waitcnt lgkmcnt(4)
	v_mfma_f32_32x32x16_bf16 v[50:65], v[218:221], v[222:225], v[50:65]
	v_mfma_f32_32x32x16_bf16 v[34:49], v[218:221], v[226:229], v[34:49]
	v_mfma_f32_32x32x16_bf16 v[18:33], v[230:233], v[222:225], v[18:33]
	v_mfma_f32_32x32x16_bf16 v[2:17], v[230:233], v[226:229], v[2:17]
	ds_read_b128 v[218:221], v140 offset:36960
	ds_read_b128 v[222:225], v141 offset:55392
	ds_read_b128 v[226:229], v141 offset:60000
	ds_read_b128 v[230:233], v140 offset:41568
	s_waitcnt lgkmcnt(4)
	v_mfma_f32_32x32x16_bf16 v[50:65], v[198:201], v[202:205], v[50:65]
	v_mfma_f32_32x32x16_bf16 v[34:49], v[198:201], v[206:209], v[34:49]
	v_mfma_f32_32x32x16_bf16 v[18:33], v[214:217], v[202:205], v[18:33]
	v_mfma_f32_32x32x16_bf16 v[2:17], v[214:217], v[206:209], v[2:17]
	s_waitcnt lgkmcnt(0)
	v_mfma_f32_32x32x16_bf16 v[50:65], v[218:221], v[222:225], v[50:65]
	v_mfma_f32_32x32x16_bf16 v[34:49], v[218:221], v[226:229], v[34:49]
	v_mfma_f32_32x32x16_bf16 v[18:33], v[230:233], v[222:225], v[18:33]
	v_mfma_f32_32x32x16_bf16 v[2:17], v[230:233], v[226:229], v[2:17]
	s_setprio 0
	s_waitcnt vmcnt(8)
	ds_write_b128 v188, v[86:89]
	ds_write_b128 v188, v[98:101] offset:4608
	ds_write_b128 v188, v[102:105] offset:9216
	ds_write_b128 v188, v[110:113] offset:13824
	ds_write_b128 v188, v[114:117] offset:18432
	ds_write_b128 v188, v[118:121] offset:23040
	ds_write_b128 v188, v[122:125] offset:27648
	ds_write_b128 v188, v[126:129] offset:32256
	s_waitcnt lgkmcnt(0)
	s_barrier
	global_load_dwordx4 v[86:89], v[160:161], off offset:768
	global_load_dwordx4 v[98:101], v[162:163], off offset:768
	global_load_dwordx4 v[102:105], v[164:165], off offset:768
	global_load_dwordx4 v[110:113], v[166:167], off offset:768
	global_load_dwordx4 v[114:117], v[158:159], off offset:768
	global_load_dwordx4 v[118:121], v[168:169], off offset:768
	global_load_dwordx4 v[122:125], v[170:171], off offset:768
	global_load_dwordx4 v[126:129], v[172:173], off offset:768
	s_setprio 1
	ds_read_b128 v[198:201], v140
	ds_read_b128 v[202:205], v141 offset:18432
	ds_read_b128 v[206:209], v141 offset:23040
	ds_read_b128 v[214:217], v140 offset:4608
	ds_read_b128 v[218:221], v140 offset:32
	ds_read_b128 v[222:225], v141 offset:18464
	ds_read_b128 v[226:229], v141 offset:23072
	ds_read_b128 v[230:233], v140 offset:4640
	s_waitcnt lgkmcnt(4)
	v_mfma_f32_32x32x16_bf16 v[50:65], v[198:201], v[202:205], v[50:65]
	v_mfma_f32_32x32x16_bf16 v[34:49], v[198:201], v[206:209], v[34:49]
	v_mfma_f32_32x32x16_bf16 v[18:33], v[214:217], v[202:205], v[18:33]
	v_mfma_f32_32x32x16_bf16 v[2:17], v[214:217], v[206:209], v[2:17]
	ds_read_b128 v[198:201], v140 offset:64
	ds_read_b128 v[202:205], v141 offset:18496
	ds_read_b128 v[206:209], v141 offset:23104
	ds_read_b128 v[214:217], v140 offset:4672
	s_waitcnt lgkmcnt(4)
	v_mfma_f32_32x32x16_bf16 v[50:65], v[218:221], v[222:225], v[50:65]
	v_mfma_f32_32x32x16_bf16 v[34:49], v[218:221], v[226:229], v[34:49]
	v_mfma_f32_32x32x16_bf16 v[18:33], v[230:233], v[222:225], v[18:33]
	v_mfma_f32_32x32x16_bf16 v[2:17], v[230:233], v[226:229], v[2:17]
	ds_read_b128 v[218:221], v140 offset:96
	ds_read_b128 v[222:225], v141 offset:18528
	ds_read_b128 v[226:229], v141 offset:23136
	ds_read_b128 v[230:233], v140 offset:4704
	s_waitcnt lgkmcnt(4)
	v_mfma_f32_32x32x16_bf16 v[50:65], v[198:201], v[202:205], v[50:65]
	v_mfma_f32_32x32x16_bf16 v[34:49], v[198:201], v[206:209], v[34:49]
	v_mfma_f32_32x32x16_bf16 v[18:33], v[214:217], v[202:205], v[18:33]
	v_mfma_f32_32x32x16_bf16 v[2:17], v[214:217], v[206:209], v[2:17]
	s_waitcnt lgkmcnt(0)
	v_mfma_f32_32x32x16_bf16 v[50:65], v[218:221], v[222:225], v[50:65]
	v_mfma_f32_32x32x16_bf16 v[34:49], v[218:221], v[226:229], v[34:49]
	v_mfma_f32_32x32x16_bf16 v[18:33], v[230:233], v[222:225], v[18:33]
	v_mfma_f32_32x32x16_bf16 v[2:17], v[230:233], v[226:229], v[2:17]
	s_setprio 0
	s_waitcnt vmcnt(8)
	ds_write_b128 v188, v[66:69] offset:36864
	ds_write_b128 v188, v[70:73] offset:41472
	ds_write_b128 v188, v[74:77] offset:46080
	ds_write_b128 v188, v[78:81] offset:50688
	ds_write_b128 v188, v[82:85] offset:55296
	ds_write_b128 v188, v[90:93] offset:59904
	ds_write_b128 v188, v[94:97] offset:64512
	ds_write_b128 v189, v[106:109] offset:13824
	s_waitcnt lgkmcnt(0)
	s_barrier
; __device__ void gemm_phase(const u16* __restrict__ Wb, int ldw, const u16* __restrict__ Xb, int ldx, int K,
;                            u16* __restrict__ outb, int ldo, int ntn, int ntiles, u16* lds) {
;     ...
;     for (int kt = 0; kt < nk; kt += 2) {
;       if (kt + 2 < nk) gs_load(B, gw, ldw, gx, ldx, (kt + 2) * 64);
;       else if (has_next) gs_load(B, gwn, ldw, gxn, ldx, 0);
;       gemm_kstep(lds, wn, wt, r, h, acc);
;       gs_store(A, lds + 2 * TILE_U16, lo);
;       __syncthreads();
;       if (kt + 3 < nk) gs_load(A, gw, ldw, gx, ldx, (kt + 3) * 64);
;       else if (has_next) gs_load(A, gwn, ldw, gxn, ldx, 64);
;       gemm_kstep(lds + 2 * TILE_U16, wn, wt, r, h, acc);
;       if (kt + 2 < nk) gs_store(B, lds, lo);
;       __syncthreads();
	global_load_dwordx4 v[66:69], v[160:161], off offset:896
	global_load_dwordx4 v[70:73], v[162:163], off offset:896
	global_load_dwordx4 v[74:77], v[164:165], off offset:896
	global_load_dwordx4 v[78:81], v[166:167], off offset:896
	global_load_dwordx4 v[82:85], v[158:159], off offset:896
	global_load_dwordx4 v[90:93], v[168:169], off offset:896
	global_load_dwordx4 v[94:97], v[170:171], off offset:896
	global_load_dwordx4 v[106:109], v[172:173], off offset:896
	s_setprio 1
	ds_read_b128 v[198:201], v140 offset:36864
	ds_read_b128 v[202:205], v141 offset:55296
	ds_read_b128 v[206:209], v141 offset:59904
	ds_read_b128 v[214:217], v140 offset:41472
	ds_read_b128 v[218:221], v140 offset:36896
	ds_read_b128 v[222:225], v141 offset:55328
	ds_read_b128 v[226:229], v141 offset:59936
	ds_read_b128 v[230:233], v140 offset:41504
	s_waitcnt lgkmcnt(4)
	v_mfma_f32_32x32x16_bf16 v[50:65], v[198:201], v[202:205], v[50:65]
	v_mfma_f32_32x32x16_bf16 v[34:49], v[198:201], v[206:209], v[34:49]
	v_mfma_f32_32x32x16_bf16 v[18:33], v[214:217], v[202:205], v[18:33]
	v_mfma_f32_32x32x16_bf16 v[2:17], v[214:217], v[206:209], v[2:17]
	ds_read_b128 v[198:201], v140 offset:36928
	ds_read_b128 v[202:205], v141 offset:55360
	ds_read_b128 v[206:209], v141 offset:59968
	ds_read_b128 v[214:217], v140 offset:41536
	s_waitcnt lgkmcnt(4)
	v_mfma_f32_32x32x16_bf16 v[50:65], v[218:221], v[222:225], v[50:65]
	v_mfma_f32_32x32x16_bf16 v[34:49], v[218:221], v[226:229], v[34:49]
	v_mfma_f32_32x32x16_bf16 v[18:33], v[230:233], v[222:225], v[18:33]
	v_mfma_f32_32x32x16_bf16 v[2:17], v[230:233], v[226:229], v[2:17]
	ds_read_b128 v[218:221], v140 offset:36960
	ds_read_b128 v[222:225], v141 offset:55392
	ds_read_b128 v[226:229], v141 offset:60000
	ds_read_b128 v[230:233], v140 offset:41568
	s_waitcnt lgkmcnt(4)
	v_mfma_f32_32x32x16_bf16 v[50:65], v[198:201], v[202:205], v[50:65]
	v_mfma_f32_32x32x16_bf16 v[34:49], v[198:201], v[206:209], v[34:49]
	v_mfma_f32_32x32x16_bf16 v[18:33], v[214:217], v[202:205], v[18:33]
	v_mfma_f32_32x32x16_bf16 v[2:17], v[214:217], v[206:209], v[2:17]
	s_waitcnt lgkmcnt(0)
	v_mfma_f32_32x32x16_bf16 v[50:65], v[218:221], v[222:225], v[50:65]
	v_mfma_f32_32x32x16_bf16 v[34:49], v[218:221], v[226:229], v[34:49]
	v_mfma_f32_32x32x16_bf16 v[18:33], v[230:233], v[222:225], v[18:33]
	v_mfma_f32_32x32x16_bf16 v[2:17], v[230:233], v[226:229], v[2:17]
	s_setprio 0
	s_waitcnt vmcnt(8)
	ds_write_b128 v188, v[86:89]
	ds_write_b128 v188, v[98:101] offset:4608
	ds_write_b128 v188, v[102:105] offset:9216
	ds_write_b128 v188, v[110:113] offset:13824
	ds_write_b128 v188, v[114:117] offset:18432
	ds_write_b128 v188, v[118:121] offset:23040
	ds_write_b128 v188, v[122:125] offset:27648
	ds_write_b128 v188, v[126:129] offset:32256
	s_waitcnt lgkmcnt(0)
	s_barrier
	global_load_dwordx4 v[86:89], v[160:161], off offset:1024
	global_load_dwordx4 v[98:101], v[162:163], off offset:1024
	global_load_dwordx4 v[102:105], v[164:165], off offset:1024
	global_load_dwordx4 v[110:113], v[166:167], off offset:1024
	global_load_dwordx4 v[114:117], v[158:159], off offset:1024
	global_load_dwordx4 v[118:121], v[168:169], off offset:1024
	global_load_dwordx4 v[122:125], v[170:171], off offset:1024
	global_load_dwordx4 v[126:129], v[172:173], off offset:1024
	s_setprio 1
	ds_read_b128 v[198:201], v140
	ds_read_b128 v[202:205], v141 offset:18432
	ds_read_b128 v[206:209], v141 offset:23040
	ds_read_b128 v[214:217], v140 offset:4608
	ds_read_b128 v[218:221], v140 offset:32
	ds_read_b128 v[222:225], v141 offset:18464
	ds_read_b128 v[226:229], v141 offset:23072
	ds_read_b128 v[230:233], v140 offset:4640
	s_waitcnt lgkmcnt(4)
	v_mfma_f32_32x32x16_bf16 v[50:65], v[198:201], v[202:205], v[50:65]
	v_mfma_f32_32x32x16_bf16 v[34:49], v[198:201], v[206:209], v[34:49]
	v_mfma_f32_32x32x16_bf16 v[18:33], v[214:217], v[202:205], v[18:33]
	v_mfma_f32_32x32x16_bf16 v[2:17], v[214:217], v[206:209], v[2:17]
	ds_read_b128 v[198:201], v140 offset:64
	ds_read_b128 v[202:205], v141 offset:18496
	ds_read_b128 v[206:209], v141 offset:23104
	ds_read_b128 v[214:217], v140 offset:4672
	s_waitcnt lgkmcnt(4)
	v_mfma_f32_32x32x16_bf16 v[50:65], v[218:221], v[222:225], v[50:65]
	v_mfma_f32_32x32x16_bf16 v[34:49], v[218:221], v[226:229], v[34:49]
	v_mfma_f32_32x32x16_bf16 v[18:33], v[230:233], v[222:225], v[18:33]
	v_mfma_f32_32x32x16_bf16 v[2:17], v[230:233], v[226:229], v[2:17]
	ds_read_b128 v[218:221], v140 offset:96
	ds_read_b128 v[222:225], v141 offset:18528
	ds_read_b128 v[226:229], v141 offset:23136
	ds_read_b128 v[230:233], v140 offset:4704
	s_waitcnt lgkmcnt(4)
	v_mfma_f32_32x32x16_bf16 v[50:65], v[198:201], v[202:205], v[50:65]
	v_mfma_f32_32x32x16_bf16 v[34:49], v[198:201], v[206:209], v[34:49]
	v_mfma_f32_32x32x16_bf16 v[18:33], v[214:217], v[202:205], v[18:33]
	v_mfma_f32_32x32x16_bf16 v[2:17], v[214:217], v[206:209], v[2:17]
	s_waitcnt lgkmcnt(0)
	v_mfma_f32_32x32x16_bf16 v[50:65], v[218:221], v[222:225], v[50:65]
	v_mfma_f32_32x32x16_bf16 v[34:49], v[218:221], v[226:229], v[34:49]
	v_mfma_f32_32x32x16_bf16 v[18:33], v[230:233], v[222:225], v[18:33]
	v_mfma_f32_32x32x16_bf16 v[2:17], v[230:233], v[226:229], v[2:17]
	s_setprio 0
	s_waitcnt vmcnt(8)
	ds_write_b128 v188, v[66:69] offset:36864
	ds_write_b128 v188, v[70:73] offset:41472
	ds_write_b128 v188, v[74:77] offset:46080
	ds_write_b128 v188, v[78:81] offset:50688
	ds_write_b128 v188, v[82:85] offset:55296
	ds_write_b128 v188, v[90:93] offset:59904
	ds_write_b128 v188, v[94:97] offset:64512
	ds_write_b128 v189, v[106:109] offset:13824
	s_waitcnt lgkmcnt(0)
	s_barrier
; __device__ void gemm_phase(const u16* __restrict__ Wb, int ldw, const u16* __restrict__ Xb, int ldx, int K,
;                            u16* __restrict__ outb, int ldo, int ntn, int ntiles, u16* lds) {
;     ...
;     for (int kt = 0; kt < nk; kt += 2) {
;       if (kt + 2 < nk) gs_load(B, gw, ldw, gx, ldx, (kt + 2) * 64);
;       else if (has_next) gs_load(B, gwn, ldw, gxn, ldx, 0);
;       gemm_kstep(lds, wn, wt, r, h, acc);
;       gs_store(A, lds + 2 * TILE_U16, lo);
;       __syncthreads();
;       if (kt + 3 < nk) gs_load(A, gw, ldw, gx, ldx, (kt + 3) * 64);
;       else if (has_next) gs_load(A, gwn, ldw, gxn, ldx, 64);
;       gemm_kstep(lds + 2 * TILE_U16, wn, wt, r, h, acc);
;       if (kt + 2 < nk) gs_store(B, lds, lo);
;       __syncthreads();
	global_load_dwordx4 v[66:69], v[160:161], off offset:1152
	global_load_dwordx4 v[70:73], v[162:163], off offset:1152
	global_load_dwordx4 v[74:77], v[164:165], off offset:1152
	global_load_dwordx4 v[78:81], v[166:167], off offset:1152
	global_load_dwordx4 v[82:85], v[158:159], off offset:1152
	global_load_dwordx4 v[90:93], v[168:169], off offset:1152
	global_load_dwordx4 v[94:97], v[170:171], off offset:1152
	global_load_dwordx4 v[106:109], v[172:173], off offset:1152
	s_setprio 1
	ds_read_b128 v[198:201], v140 offset:36864
	ds_read_b128 v[202:205], v141 offset:55296
	ds_read_b128 v[206:209], v141 offset:59904
	ds_read_b128 v[214:217], v140 offset:41472
	ds_read_b128 v[218:221], v140 offset:36896
	ds_read_b128 v[222:225], v141 offset:55328
	ds_read_b128 v[226:229], v141 offset:59936
	ds_read_b128 v[230:233], v140 offset:41504
	s_waitcnt lgkmcnt(4)
	v_mfma_f32_32x32x16_bf16 v[50:65], v[198:201], v[202:205], v[50:65]
	v_mfma_f32_32x32x16_bf16 v[34:49], v[198:201], v[206:209], v[34:49]
	v_mfma_f32_32x32x16_bf16 v[18:33], v[214:217], v[202:205], v[18:33]
	v_mfma_f32_32x32x16_bf16 v[2:17], v[214:217], v[206:209], v[2:17]
	ds_read_b128 v[198:201], v140 offset:36928
	ds_read_b128 v[202:205], v141 offset:55360
	ds_read_b128 v[206:209], v141 offset:59968
	ds_read_b128 v[214:217], v140 offset:41536
	s_waitcnt lgkmcnt(4)
	v_mfma_f32_32x32x16_bf16 v[50:65], v[218:221], v[222:225], v[50:65]
	v_mfma_f32_32x32x16_bf16 v[34:49], v[218:221], v[226:229], v[34:49]
	v_mfma_f32_32x32x16_bf16 v[18:33], v[230:233], v[222:225], v[18:33]
	v_mfma_f32_32x32x16_bf16 v[2:17], v[230:233], v[226:229], v[2:17]
	ds_read_b128 v[218:221], v140 offset:36960
	ds_read_b128 v[222:225], v141 offset:55392
	ds_read_b128 v[226:229], v141 offset:60000
	ds_read_b128 v[230:233], v140 offset:41568
	s_waitcnt lgkmcnt(4)
	v_mfma_f32_32x32x16_bf16 v[50:65], v[198:201], v[202:205], v[50:65]
	v_mfma_f32_32x32x16_bf16 v[34:49], v[198:201], v[206:209], v[34:49]
	v_mfma_f32_32x32x16_bf16 v[18:33], v[214:217], v[202:205], v[18:33]
	v_mfma_f32_32x32x16_bf16 v[2:17], v[214:217], v[206:209], v[2:17]
	s_waitcnt lgkmcnt(0)
	v_mfma_f32_32x32x16_bf16 v[50:65], v[218:221], v[222:225], v[50:65]
	v_mfma_f32_32x32x16_bf16 v[34:49], v[218:221], v[226:229], v[34:49]
	v_mfma_f32_32x32x16_bf16 v[18:33], v[230:233], v[222:225], v[18:33]
	v_mfma_f32_32x32x16_bf16 v[2:17], v[230:233], v[226:229], v[2:17]
	s_setprio 0
	s_waitcnt vmcnt(8)
	ds_write_b128 v188, v[86:89]
	ds_write_b128 v188, v[98:101] offset:4608
	ds_write_b128 v188, v[102:105] offset:9216
	ds_write_b128 v188, v[110:113] offset:13824
	ds_write_b128 v188, v[114:117] offset:18432
	ds_write_b128 v188, v[118:121] offset:23040
	ds_write_b128 v188, v[122:125] offset:27648
	ds_write_b128 v188, v[126:129] offset:32256
	s_waitcnt lgkmcnt(0)
	s_barrier
	global_load_dwordx4 v[86:89], v[160:161], off offset:1280
	global_load_dwordx4 v[98:101], v[162:163], off offset:1280
	global_load_dwordx4 v[102:105], v[164:165], off offset:1280
	global_load_dwordx4 v[110:113], v[166:167], off offset:1280
	global_load_dwordx4 v[114:117], v[158:159], off offset:1280
	global_load_dwordx4 v[118:121], v[168:169], off offset:1280
	global_load_dwordx4 v[122:125], v[170:171], off offset:1280
	global_load_dwordx4 v[126:129], v[172:173], off offset:1280
	s_setprio 1
	ds_read_b128 v[198:201], v140
	ds_read_b128 v[202:205], v141 offset:18432
	ds_read_b128 v[206:209], v141 offset:23040
	ds_read_b128 v[214:217], v140 offset:4608
	ds_read_b128 v[218:221], v140 offset:32
	ds_read_b128 v[222:225], v141 offset:18464
	ds_read_b128 v[226:229], v141 offset:23072
	ds_read_b128 v[230:233], v140 offset:4640
	s_waitcnt lgkmcnt(4)
	v_mfma_f32_32x32x16_bf16 v[50:65], v[198:201], v[202:205], v[50:65]
	v_mfma_f32_32x32x16_bf16 v[34:49], v[198:201], v[206:209], v[34:49]
	v_mfma_f32_32x32x16_bf16 v[18:33], v[214:217], v[202:205], v[18:33]
	v_mfma_f32_32x32x16_bf16 v[2:17], v[214:217], v[206:209], v[2:17]
	ds_read_b128 v[198:201], v140 offset:64
	ds_read_b128 v[202:205], v141 offset:18496
	ds_read_b128 v[206:209], v141 offset:23104
	ds_read_b128 v[214:217], v140 offset:4672
	s_waitcnt lgkmcnt(4)
	v_mfma_f32_32x32x16_bf16 v[50:65], v[218:221], v[222:225], v[50:65]
	v_mfma_f32_32x32x16_bf16 v[34:49], v[218:221], v[226:229], v[34:49]
	v_mfma_f32_32x32x16_bf16 v[18:33], v[230:233], v[222:225], v[18:33]
	v_mfma_f32_32x32x16_bf16 v[2:17], v[230:233], v[226:229], v[2:17]
	ds_read_b128 v[218:221], v140 offset:96
	ds_read_b128 v[222:225], v141 offset:18528
	ds_read_b128 v[226:229], v141 offset:23136
	ds_read_b128 v[230:233], v140 offset:4704
	s_waitcnt lgkmcnt(4)
	v_mfma_f32_32x32x16_bf16 v[50:65], v[198:201], v[202:205], v[50:65]
	v_mfma_f32_32x32x16_bf16 v[34:49], v[198:201], v[206:209], v[34:49]
	v_mfma_f32_32x32x16_bf16 v[18:33], v[214:217], v[202:205], v[18:33]
	v_mfma_f32_32x32x16_bf16 v[2:17], v[214:217], v[206:209], v[2:17]
	s_waitcnt lgkmcnt(0)
	v_mfma_f32_32x32x16_bf16 v[50:65], v[218:221], v[222:225], v[50:65]
	v_mfma_f32_32x32x16_bf16 v[34:49], v[218:221], v[226:229], v[34:49]
	v_mfma_f32_32x32x16_bf16 v[18:33], v[230:233], v[222:225], v[18:33]
	v_mfma_f32_32x32x16_bf16 v[2:17], v[230:233], v[226:229], v[2:17]
	s_setprio 0
	s_waitcnt vmcnt(8)
	ds_write_b128 v188, v[66:69] offset:36864
	ds_write_b128 v188, v[70:73] offset:41472
	ds_write_b128 v188, v[74:77] offset:46080
	ds_write_b128 v188, v[78:81] offset:50688
	ds_write_b128 v188, v[82:85] offset:55296
	ds_write_b128 v188, v[90:93] offset:59904
	ds_write_b128 v188, v[94:97] offset:64512
	ds_write_b128 v189, v[106:109] offset:13824
	s_waitcnt lgkmcnt(0)
	s_barrier
; __device__ void gemm_phase(const u16* __restrict__ Wb, int ldw, const u16* __restrict__ Xb, int ldx, int K,
;                            u16* __restrict__ outb, int ldo, int ntn, int ntiles, u16* lds) {
;     ...
;     for (int kt = 0; kt < nk; kt += 2) {
;       if (kt + 2 < nk) gs_load(B, gw, ldw, gx, ldx, (kt + 2) * 64);
;       else if (has_next) gs_load(B, gwn, ldw, gxn, ldx, 0);
;       gemm_kstep(lds, wn, wt, r, h, acc);
;       gs_store(A, lds + 2 * TILE_U16, lo);
;       __syncthreads();
;       if (kt + 3 < nk) gs_load(A, gw, ldw, gx, ldx, (kt + 3) * 64);
;       else if (has_next) gs_load(A, gwn, ldw, gxn, ldx, 64);
;       gemm_kstep(lds + 2 * TILE_U16, wn, wt, r, h, acc);
;       if (kt + 2 < nk) gs_store(B, lds, lo);
;       __syncthreads();
	global_load_dwordx4 v[66:69], v[160:161], off offset:1408
	global_load_dwordx4 v[70:73], v[162:163], off offset:1408
	global_load_dwordx4 v[74:77], v[164:165], off offset:1408
	global_load_dwordx4 v[78:81], v[166:167], off offset:1408
	global_load_dwordx4 v[82:85], v[158:159], off offset:1408
	global_load_dwordx4 v[90:93], v[168:169], off offset:1408
	global_load_dwordx4 v[94:97], v[170:171], off offset:1408
	global_load_dwordx4 v[106:109], v[172:173], off offset:1408
	s_setprio 1
	ds_read_b128 v[198:201], v140 offset:36864
	ds_read_b128 v[202:205], v141 offset:55296
	ds_read_b128 v[206:209], v141 offset:59904
	ds_read_b128 v[214:217], v140 offset:41472
	ds_read_b128 v[218:221], v140 offset:36896
	ds_read_b128 v[222:225], v141 offset:55328
	ds_read_b128 v[226:229], v141 offset:59936
	ds_read_b128 v[230:233], v140 offset:41504
	s_waitcnt lgkmcnt(4)
	v_mfma_f32_32x32x16_bf16 v[50:65], v[198:201], v[202:205], v[50:65]
	v_mfma_f32_32x32x16_bf16 v[34:49], v[198:201], v[206:209], v[34:49]
	v_mfma_f32_32x32x16_bf16 v[18:33], v[214:217], v[202:205], v[18:33]
	v_mfma_f32_32x32x16_bf16 v[2:17], v[214:217], v[206:209], v[2:17]
	ds_read_b128 v[198:201], v140 offset:36928
	ds_read_b128 v[202:205], v141 offset:55360
	ds_read_b128 v[206:209], v141 offset:59968
	ds_read_b128 v[214:217], v140 offset:41536
	s_waitcnt lgkmcnt(4)
	v_mfma_f32_32x32x16_bf16 v[50:65], v[218:221], v[222:225], v[50:65]
	v_mfma_f32_32x32x16_bf16 v[34:49], v[218:221], v[226:229], v[34:49]
	v_mfma_f32_32x32x16_bf16 v[18:33], v[230:233], v[222:225], v[18:33]
	v_mfma_f32_32x32x16_bf16 v[2:17], v[230:233], v[226:229], v[2:17]
	ds_read_b128 v[218:221], v140 offset:36960
	ds_read_b128 v[222:225], v141 offset:55392
	ds_read_b128 v[226:229], v141 offset:60000
	ds_read_b128 v[230:233], v140 offset:41568
	s_waitcnt lgkmcnt(4)
	v_mfma_f32_32x32x16_bf16 v[50:65], v[198:201], v[202:205], v[50:65]
	v_mfma_f32_32x32x16_bf16 v[34:49], v[198:201], v[206:209], v[34:49]
	v_mfma_f32_32x32x16_bf16 v[18:33], v[214:217], v[202:205], v[18:33]
	v_mfma_f32_32x32x16_bf16 v[2:17], v[214:217], v[206:209], v[2:17]
	s_waitcnt lgkmcnt(0)
	v_mfma_f32_32x32x16_bf16 v[50:65], v[218:221], v[222:225], v[50:65]
	v_mfma_f32_32x32x16_bf16 v[34:49], v[218:221], v[226:229], v[34:49]
	v_mfma_f32_32x32x16_bf16 v[18:33], v[230:233], v[222:225], v[18:33]
	v_mfma_f32_32x32x16_bf16 v[2:17], v[230:233], v[226:229], v[2:17]
	s_setprio 0
	s_waitcnt vmcnt(8)
	ds_write_b128 v188, v[86:89]
	ds_write_b128 v188, v[98:101] offset:4608
	ds_write_b128 v188, v[102:105] offset:9216
	ds_write_b128 v188, v[110:113] offset:13824
	ds_write_b128 v188, v[114:117] offset:18432
	ds_write_b128 v188, v[118:121] offset:23040
	ds_write_b128 v188, v[122:125] offset:27648
	ds_write_b128 v188, v[126:129] offset:32256
	s_waitcnt lgkmcnt(0)
	s_barrier
	global_load_dwordx4 v[86:89], v[160:161], off offset:1536
	global_load_dwordx4 v[98:101], v[162:163], off offset:1536
	global_load_dwordx4 v[102:105], v[164:165], off offset:1536
	global_load_dwordx4 v[110:113], v[166:167], off offset:1536
	global_load_dwordx4 v[114:117], v[158:159], off offset:1536
	global_load_dwordx4 v[118:121], v[168:169], off offset:1536
	global_load_dwordx4 v[122:125], v[170:171], off offset:1536
	global_load_dwordx4 v[126:129], v[172:173], off offset:1536
	s_setprio 1
	ds_read_b128 v[198:201], v140
	ds_read_b128 v[202:205], v141 offset:18432
	ds_read_b128 v[206:209], v141 offset:23040
	ds_read_b128 v[214:217], v140 offset:4608
	ds_read_b128 v[218:221], v140 offset:32
	ds_read_b128 v[222:225], v141 offset:18464
	ds_read_b128 v[226:229], v141 offset:23072
	ds_read_b128 v[230:233], v140 offset:4640
	s_waitcnt lgkmcnt(4)
	v_mfma_f32_32x32x16_bf16 v[50:65], v[198:201], v[202:205], v[50:65]
	v_mfma_f32_32x32x16_bf16 v[34:49], v[198:201], v[206:209], v[34:49]
	v_mfma_f32_32x32x16_bf16 v[18:33], v[214:217], v[202:205], v[18:33]
	v_mfma_f32_32x32x16_bf16 v[2:17], v[214:217], v[206:209], v[2:17]
	ds_read_b128 v[198:201], v140 offset:64
	ds_read_b128 v[202:205], v141 offset:18496
	ds_read_b128 v[206:209], v141 offset:23104
	ds_read_b128 v[214:217], v140 offset:4672
	s_waitcnt lgkmcnt(4)
	v_mfma_f32_32x32x16_bf16 v[50:65], v[218:221], v[222:225], v[50:65]
	v_mfma_f32_32x32x16_bf16 v[34:49], v[218:221], v[226:229], v[34:49]
	v_mfma_f32_32x32x16_bf16 v[18:33], v[230:233], v[222:225], v[18:33]
	v_mfma_f32_32x32x16_bf16 v[2:17], v[230:233], v[226:229], v[2:17]
	ds_read_b128 v[218:221], v140 offset:96
	ds_read_b128 v[222:225], v141 offset:18528
	ds_read_b128 v[226:229], v141 offset:23136
	ds_read_b128 v[230:233], v140 offset:4704
	s_waitcnt lgkmcnt(4)
	v_mfma_f32_32x32x16_bf16 v[50:65], v[198:201], v[202:205], v[50:65]
	v_mfma_f32_32x32x16_bf16 v[34:49], v[198:201], v[206:209], v[34:49]
	v_mfma_f32_32x32x16_bf16 v[18:33], v[214:217], v[202:205], v[18:33]
	v_mfma_f32_32x32x16_bf16 v[2:17], v[214:217], v[206:209], v[2:17]
	s_waitcnt lgkmcnt(0)
	v_mfma_f32_32x32x16_bf16 v[50:65], v[218:221], v[222:225], v[50:65]
	v_mfma_f32_32x32x16_bf16 v[34:49], v[218:221], v[226:229], v[34:49]
	v_mfma_f32_32x32x16_bf16 v[18:33], v[230:233], v[222:225], v[18:33]
	v_mfma_f32_32x32x16_bf16 v[2:17], v[230:233], v[226:229], v[2:17]
	s_setprio 0
	s_waitcnt vmcnt(8)
	ds_write_b128 v188, v[66:69] offset:36864
	ds_write_b128 v188, v[70:73] offset:41472
	ds_write_b128 v188, v[74:77] offset:46080
	ds_write_b128 v188, v[78:81] offset:50688
	ds_write_b128 v188, v[82:85] offset:55296
	ds_write_b128 v188, v[90:93] offset:59904
	ds_write_b128 v188, v[94:97] offset:64512
	ds_write_b128 v189, v[106:109] offset:13824
	s_waitcnt lgkmcnt(0)
	s_barrier
; __device__ __forceinline__ void gemm_kstep(const u16* sb, int wn, int wt, int r, int h, f32x16 (&acc)[2][2]) {
;   const u16* bw = sb + (wn * 64 + r) * LDT + h * 8;
;   const u16* bx = sb + TILE_U16 + (wt * 64 + r) * LDT + h * 8;
;   __builtin_amdgcn_s_setprio(1);
; #pragma unroll
;   for (int ks = 0; ks < 4; ++ks) {
;     bf16x8 a0 = *(const bf16x8*)(bw + ks * 16);
;     bf16x8 a1 = *(const bf16x8*)(bw + 32 * LDT + ks * 16);
;     bf16x8 b0 = *(const bf16x8*)(bx + ks * 16);
;     bf16x8 b1 = *(const bf16x8*)(bx + 32 * LDT + ks * 16);
;     acc[0][0] = mfma32(a0, b0, acc[0][0]);
;     acc[0][1] = mfma32(a0, b1, acc[0][1]);
;     acc[1][0] = mfma32(a1, b0, acc[1][0]);
;     acc[1][1] = mfma32(a1, b1, acc[1][1]);
;   }
;   __builtin_amdgcn_s_setprio(0);
; }
; __device__ void gemm_phase(const u16* __restrict__ Wb, int ldw, const u16* __restrict__ Xb, int ldx, int K,
;                            u16* __restrict__ outb, int ldo, int ntn, int ntiles, u16* lds) {
;     ...
;     for (int kt = 0; kt < nk; kt += 2) {
;       if (kt + 2 < nk) gs_load(B, gw, ldw, gx, ldx, (kt + 2) * 64);
;       else if (has_next) gs_load(B, gwn, ldw, gxn, ldx, 0);
;       gemm_kstep(lds, wn, wt, r, h, acc);
;       gs_store(A, lds + 2 * TILE_U16, lo);
;       __syncthreads();
;       if (kt + 3 < nk) gs_load(A, gw, ldw, gx, ldx, (kt + 3) * 64);
;       else if (has_next) gs_load(A, gwn, ldw, gxn, ldx, 64);
;       gemm_kstep(lds + 2 * TILE_U16, wn, wt, r, h, acc);
;       if (kt + 2 < nk) gs_store(B, lds, lo);
;       __syncthreads();
;     }
	global_load_dwordx4 v[66:69], v[160:161], off offset:1664
	global_load_dwordx4 v[70:73], v[162:163], off offset:1664
	global_load_dwordx4 v[74:77], v[164:165], off offset:1664
	global_load_dwordx4 v[78:81], v[166:167], off offset:1664
	global_load_dwordx4 v[82:85], v[158:159], off offset:1664
	global_load_dwordx4 v[90:93], v[168:169], off offset:1664
	global_load_dwordx4 v[94:97], v[170:171], off offset:1664
	global_load_dwordx4 v[106:109], v[172:173], off offset:1664
	s_setprio 1
	ds_read_b128 v[198:201], v140 offset:36864
	ds_read_b128 v[202:205], v141 offset:55296
	ds_read_b128 v[206:209], v141 offset:59904
	ds_read_b128 v[214:217], v140 offset:41472
	ds_read_b128 v[218:221], v140 offset:36896
	ds_read_b128 v[222:225], v141 offset:55328
	ds_read_b128 v[226:229], v141 offset:59936
	ds_read_b128 v[230:233], v140 offset:41504
	s_waitcnt lgkmcnt(4)
	v_mfma_f32_32x32x16_bf16 v[50:65], v[198:201], v[202:205], v[50:65]
	v_mfma_f32_32x32x16_bf16 v[34:49], v[198:201], v[206:209], v[34:49]
	v_mfma_f32_32x32x16_bf16 v[18:33], v[214:217], v[202:205], v[18:33]
	v_mfma_f32_32x32x16_bf16 v[2:17], v[214:217], v[206:209], v[2:17]
	ds_read_b128 v[198:201], v140 offset:36928
	ds_read_b128 v[202:205], v141 offset:55360
	ds_read_b128 v[206:209], v141 offset:59968
	ds_read_b128 v[214:217], v140 offset:41536
	s_waitcnt lgkmcnt(4)
	v_mfma_f32_32x32x16_bf16 v[50:65], v[218:221], v[222:225], v[50:65]
	v_mfma_f32_32x32x16_bf16 v[34:49], v[218:221], v[226:229], v[34:49]
	v_mfma_f32_32x32x16_bf16 v[18:33], v[230:233], v[222:225], v[18:33]
	v_mfma_f32_32x32x16_bf16 v[2:17], v[230:233], v[226:229], v[2:17]
	ds_read_b128 v[218:221], v140 offset:36960
	ds_read_b128 v[222:225], v141 offset:55392
	ds_read_b128 v[226:229], v141 offset:60000
	ds_read_b128 v[230:233], v140 offset:41568
	s_waitcnt lgkmcnt(4)
	v_mfma_f32_32x32x16_bf16 v[50:65], v[198:201], v[202:205], v[50:65]
	v_mfma_f32_32x32x16_bf16 v[34:49], v[198:201], v[206:209], v[34:49]
	v_mfma_f32_32x32x16_bf16 v[18:33], v[214:217], v[202:205], v[18:33]
	v_mfma_f32_32x32x16_bf16 v[2:17], v[214:217], v[206:209], v[2:17]
	s_waitcnt lgkmcnt(0)
	v_mfma_f32_32x32x16_bf16 v[50:65], v[218:221], v[222:225], v[50:65]
	v_mfma_f32_32x32x16_bf16 v[34:49], v[218:221], v[226:229], v[34:49]
	v_mfma_f32_32x32x16_bf16 v[18:33], v[230:233], v[222:225], v[18:33]
	v_mfma_f32_32x32x16_bf16 v[2:17], v[230:233], v[226:229], v[2:17]
	s_setprio 0
	s_waitcnt vmcnt(8)
	ds_write_b128 v188, v[86:89]
	ds_write_b128 v188, v[98:101] offset:4608
	ds_write_b128 v188, v[102:105] offset:9216
	ds_write_b128 v188, v[110:113] offset:13824
	ds_write_b128 v188, v[114:117] offset:18432
	ds_write_b128 v188, v[118:121] offset:23040
	ds_write_b128 v188, v[122:125] offset:27648
	ds_write_b128 v188, v[126:129] offset:32256
	s_waitcnt lgkmcnt(0)
	s_barrier
	global_load_dwordx4 v[86:89], v[160:161], off offset:1792
	global_load_dwordx4 v[98:101], v[162:163], off offset:1792
	global_load_dwordx4 v[102:105], v[164:165], off offset:1792
	global_load_dwordx4 v[110:113], v[166:167], off offset:1792
	global_load_dwordx4 v[114:117], v[158:159], off offset:1792
	global_load_dwordx4 v[118:121], v[168:169], off offset:1792
	global_load_dwordx4 v[122:125], v[170:171], off offset:1792
	global_load_dwordx4 v[126:129], v[172:173], off offset:1792
	s_setprio 1
	ds_read_b128 v[198:201], v140
	ds_read_b128 v[202:205], v141 offset:18432
	ds_read_b128 v[206:209], v141 offset:23040
	ds_read_b128 v[214:217], v140 offset:4608
	ds_read_b128 v[218:221], v140 offset:32
	ds_read_b128 v[222:225], v141 offset:18464
	ds_read_b128 v[226:229], v141 offset:23072
	ds_read_b128 v[230:233], v140 offset:4640
	s_waitcnt lgkmcnt(4)
	v_mfma_f32_32x32x16_bf16 v[50:65], v[198:201], v[202:205], v[50:65]
	v_mfma_f32_32x32x16_bf16 v[34:49], v[198:201], v[206:209], v[34:49]
	v_mfma_f32_32x32x16_bf16 v[18:33], v[214:217], v[202:205], v[18:33]
	v_mfma_f32_32x32x16_bf16 v[2:17], v[214:217], v[206:209], v[2:17]
	ds_read_b128 v[198:201], v140 offset:64
	ds_read_b128 v[202:205], v141 offset:18496
	ds_read_b128 v[206:209], v141 offset:23104
	ds_read_b128 v[214:217], v140 offset:4672
	s_waitcnt lgkmcnt(4)
	v_mfma_f32_32x32x16_bf16 v[50:65], v[218:221], v[222:225], v[50:65]
	v_mfma_f32_32x32x16_bf16 v[34:49], v[218:221], v[226:229], v[34:49]
	v_mfma_f32_32x32x16_bf16 v[18:33], v[230:233], v[222:225], v[18:33]
	v_mfma_f32_32x32x16_bf16 v[2:17], v[230:233], v[226:229], v[2:17]
	ds_read_b128 v[218:221], v140 offset:96
	ds_read_b128 v[222:225], v141 offset:18528
	ds_read_b128 v[226:229], v141 offset:23136
	ds_read_b128 v[230:233], v140 offset:4704
	s_waitcnt lgkmcnt(4)
	v_mfma_f32_32x32x16_bf16 v[50:65], v[198:201], v[202:205], v[50:65]
	v_mfma_f32_32x32x16_bf16 v[34:49], v[198:201], v[206:209], v[34:49]
	v_mfma_f32_32x32x16_bf16 v[18:33], v[214:217], v[202:205], v[18:33]
	v_mfma_f32_32x32x16_bf16 v[2:17], v[214:217], v[206:209], v[2:17]
	s_waitcnt lgkmcnt(0)
	v_mfma_f32_32x32x16_bf16 v[50:65], v[218:221], v[222:225], v[50:65]
	v_mfma_f32_32x32x16_bf16 v[34:49], v[218:221], v[226:229], v[34:49]
	v_mfma_f32_32x32x16_bf16 v[18:33], v[230:233], v[222:225], v[18:33]
	v_mfma_f32_32x32x16_bf16 v[2:17], v[230:233], v[226:229], v[2:17]
	s_setprio 0
	s_waitcnt vmcnt(8)
	ds_write_b128 v188, v[66:69] offset:36864
	ds_write_b128 v188, v[70:73] offset:41472
	ds_write_b128 v188, v[74:77] offset:46080
	ds_write_b128 v188, v[78:81] offset:50688
	ds_write_b128 v188, v[82:85] offset:55296
	ds_write_b128 v188, v[90:93] offset:59904
	ds_write_b128 v188, v[94:97] offset:64512
	ds_write_b128 v189, v[106:109] offset:13824
	s_waitcnt lgkmcnt(0)
	s_barrier
; __device__ __forceinline__ void gemm_kstep(const u16* sb, int wn, int wt, int r, int h, f32x16 (&acc)[2][2]) {
;   const u16* bw = sb + (wn * 64 + r) * LDT + h * 8;
;   const u16* bx = sb + TILE_U16 + (wt * 64 + r) * LDT + h * 8;
;   __builtin_amdgcn_s_setprio(1);
; #pragma unroll
;   for (int ks = 0; ks < 4; ++ks) {
;     bf16x8 a0 = *(const bf16x8*)(bw + ks * 16);
;     bf16x8 a1 = *(const bf16x8*)(bw + 32 * LDT + ks * 16);
;     bf16x8 b0 = *(const bf16x8*)(bx + ks * 16);
;     bf16x8 b1 = *(const bf16x8*)(bx + 32 * LDT + ks * 16);
;     acc[0][0] = mfma32(a0, b0, acc[0][0]);
;     acc[0][1] = mfma32(a0, b1, acc[0][1]);
;     acc[1][0] = mfma32(a1, b0, acc[1][0]);
;     acc[1][1] = mfma32(a1, b1, acc[1][1]);
;   }
;   __builtin_amdgcn_s_setprio(0);
; }
; __device__ void gemm_phase(const u16* __restrict__ Wb, int ldw, const u16* __restrict__ Xb, int ldx, int K,
;                            u16* __restrict__ outb, int ldo, int ntn, int ntiles, u16* lds) {
;     ...
;     for (int kt = 0; kt < nk; kt += 2) {
;       if (kt + 2 < nk) gs_load(B, gw, ldw, gx, ldx, (kt + 2) * 64);
;       else if (has_next) gs_load(B, gwn, ldw, gxn, ldx, 0);
;       gemm_kstep(lds, wn, wt, r, h, acc);
;       gs_store(A, lds + 2 * TILE_U16, lo);
;       __syncthreads();
;       if (kt + 3 < nk) gs_load(A, gw, ldw, gx, ldx, (kt + 3) * 64);
;       else if (has_next) gs_load(A, gwn, ldw, gxn, ldx, 64);
;       gemm_kstep(lds + 2 * TILE_U16, wn, wt, r, h, acc);
;       if (kt + 2 < nk) gs_store(B, lds, lo);
;       __syncthreads();
;     }
	global_load_dwordx4 v[66:69], v[160:161], off offset:1920
	global_load_dwordx4 v[70:73], v[162:163], off offset:1920
	global_load_dwordx4 v[74:77], v[164:165], off offset:1920
	global_load_dwordx4 v[78:81], v[166:167], off offset:1920
	global_load_dwordx4 v[82:85], v[158:159], off offset:1920
	global_load_dwordx4 v[90:93], v[168:169], off offset:1920
	global_load_dwordx4 v[94:97], v[170:171], off offset:1920
	global_load_dwordx4 v[106:109], v[172:173], off offset:1920
	s_setprio 1
	ds_read_b128 v[158:161], v140 offset:36864
	ds_read_b128 v[162:165], v141 offset:55296
	ds_read_b128 v[166:169], v141 offset:59904
	ds_read_b128 v[214:217], v140 offset:41472
	ds_read_b128 v[218:221], v140 offset:36896
	ds_read_b128 v[222:225], v141 offset:55328
	ds_read_b128 v[226:229], v141 offset:59936
	ds_read_b128 v[230:233], v140 offset:41504
	s_waitcnt lgkmcnt(4)
	v_mfma_f32_32x32x16_bf16 v[50:65], v[158:161], v[162:165], v[50:65]
	v_mfma_f32_32x32x16_bf16 v[34:49], v[158:161], v[166:169], v[34:49]
	v_mfma_f32_32x32x16_bf16 v[18:33], v[214:217], v[162:165], v[18:33]
	v_mfma_f32_32x32x16_bf16 v[2:17], v[214:217], v[166:169], v[2:17]
	ds_read_b128 v[158:161], v140 offset:36928
	ds_read_b128 v[162:165], v141 offset:55360
	ds_read_b128 v[166:169], v141 offset:59968
	ds_read_b128 v[214:217], v140 offset:41536
	s_waitcnt lgkmcnt(4)
	v_mfma_f32_32x32x16_bf16 v[50:65], v[218:221], v[222:225], v[50:65]
	v_mfma_f32_32x32x16_bf16 v[34:49], v[218:221], v[226:229], v[34:49]
	v_mfma_f32_32x32x16_bf16 v[18:33], v[230:233], v[222:225], v[18:33]
	v_mfma_f32_32x32x16_bf16 v[2:17], v[230:233], v[226:229], v[2:17]
	ds_read_b128 v[218:221], v140 offset:36960
	ds_read_b128 v[222:225], v141 offset:55392
	ds_read_b128 v[226:229], v141 offset:60000
	ds_read_b128 v[230:233], v140 offset:41568
	s_waitcnt lgkmcnt(4)
	v_mfma_f32_32x32x16_bf16 v[50:65], v[158:161], v[162:165], v[50:65]
	v_mfma_f32_32x32x16_bf16 v[34:49], v[158:161], v[166:169], v[34:49]
	v_mfma_f32_32x32x16_bf16 v[18:33], v[214:217], v[162:165], v[18:33]
	v_mfma_f32_32x32x16_bf16 v[2:17], v[214:217], v[166:169], v[2:17]
	s_waitcnt lgkmcnt(0)
	v_mfma_f32_32x32x16_bf16 v[50:65], v[218:221], v[222:225], v[50:65]
	v_mfma_f32_32x32x16_bf16 v[34:49], v[218:221], v[226:229], v[34:49]
	v_mfma_f32_32x32x16_bf16 v[18:33], v[230:233], v[222:225], v[18:33]
	v_mfma_f32_32x32x16_bf16 v[2:17], v[230:233], v[226:229], v[2:17]
	s_setprio 0
	s_and_b64 vcc, exec, s[0:1]
	s_waitcnt vmcnt(8)
	ds_write_b128 v188, v[86:89]
	ds_write_b128 v188, v[98:101] offset:4608
	ds_write_b128 v188, v[102:105] offset:9216
	ds_write_b128 v188, v[110:113] offset:13824
	ds_write_b128 v188, v[114:117] offset:18432
	ds_write_b128 v188, v[118:121] offset:23040
	ds_write_b128 v188, v[122:125] offset:27648
	ds_write_b128 v188, v[126:129] offset:32256
	s_waitcnt lgkmcnt(0)
	s_barrier
	s_cbranch_vccnz .LBB0_611
	v_add_co_u32_e32 v98, vcc, 0x10000, v132
	global_load_dwordx4 v[86:89], v[132:133], off
	s_nop 0
	v_addc_co_u32_e32 v99, vcc, 0, v133, vcc
	v_add_co_u32_e32 v102, vcc, 0x20000, v132
	s_nop 1
	v_addc_co_u32_e32 v103, vcc, 0, v133, vcc
	v_add_co_u32_e32 v110, vcc, 0x30000, v132
	global_load_dwordx4 v[98:101], v[98:99], off
	s_nop 0
	global_load_dwordx4 v[102:105], v[102:103], off
	v_addc_co_u32_e32 v111, vcc, 0, v133, vcc
	v_add_co_u32_e32 v118, vcc, 0x10000, v134
	global_load_dwordx4 v[110:113], v[110:111], off
	s_nop 0
	global_load_dwordx4 v[114:117], v[134:135], off
	v_addc_co_u32_e32 v119, vcc, 0, v135, vcc
	v_add_co_u32_e32 v122, vcc, 0x20000, v134
	s_nop 1
	v_addc_co_u32_e32 v123, vcc, 0, v135, vcc
	v_add_co_u32_e32 v126, vcc, 0x30000, v134
	global_load_dwordx4 v[118:121], v[118:119], off
	s_nop 0
	global_load_dwordx4 v[122:125], v[122:123], off
	v_addc_co_u32_e32 v127, vcc, 0, v135, vcc
	global_load_dwordx4 v[126:129], v[126:127], off
; __device__ __forceinline__ void gemm_kstep(const u16* sb, int wn, int wt, int r, int h, f32x16 (&acc)[2][2]) {
;   const u16* bw = sb + (wn * 64 + r) * LDT + h * 8;
;   const u16* bx = sb + TILE_U16 + (wt * 64 + r) * LDT + h * 8;
;   __builtin_amdgcn_s_setprio(1);
; #pragma unroll
;   for (int ks = 0; ks < 4; ++ks) {
;     bf16x8 a0 = *(const bf16x8*)(bw + ks * 16);
;     bf16x8 a1 = *(const bf16x8*)(bw + 32 * LDT + ks * 16);
;     bf16x8 b0 = *(const bf16x8*)(bx + ks * 16);
;     bf16x8 b1 = *(const bf16x8*)(bx + 32 * LDT + ks * 16);
;     acc[0][0] = mfma32(a0, b0, acc[0][0]);
;     acc[0][1] = mfma32(a0, b1, acc[0][1]);
;     acc[1][0] = mfma32(a1, b0, acc[1][0]);
;     acc[1][1] = mfma32(a1, b1, acc[1][1]);
;   }
;   __builtin_amdgcn_s_setprio(0);
; }
; __device__ void gemm_phase(const u16* __restrict__ Wb, int ldw, const u16* __restrict__ Xb, int ldx, int K,
;                            u16* __restrict__ outb, int ldo, int ntn, int ntiles, u16* lds) {
;     ...
;     for (int kt = 0; kt < nk; kt += 2) {
;       if (kt + 2 < nk) gs_load(B, gw, ldw, gx, ldx, (kt + 2) * 64);
;       else if (has_next) gs_load(B, gwn, ldw, gxn, ldx, 0);
;       gemm_kstep(lds, wn, wt, r, h, acc);
;       gs_store(A, lds + 2 * TILE_U16, lo);
;       __syncthreads();
;       if (kt + 3 < nk) gs_load(A, gw, ldw, gx, ldx, (kt + 3) * 64);
;       else if (has_next) gs_load(A, gwn, ldw, gxn, ldx, 64);
;       gemm_kstep(lds + 2 * TILE_U16, wn, wt, r, h, acc);
;       if (kt + 2 < nk) gs_store(B, lds, lo);
;       __syncthreads();
;     }
.LBB0_611:
	s_setprio 1
	ds_read_b128 v[158:161], v140
	ds_read_b128 v[162:165], v141 offset:18432
	ds_read_b128 v[166:169], v141 offset:23040
	ds_read_b128 v[214:217], v140 offset:4608
	ds_read_b128 v[218:221], v140 offset:32
	ds_read_b128 v[222:225], v141 offset:18464
	ds_read_b128 v[226:229], v141 offset:23072
	ds_read_b128 v[230:233], v140 offset:4640
	s_waitcnt lgkmcnt(4)
	v_mfma_f32_32x32x16_bf16 v[50:65], v[158:161], v[162:165], v[50:65]
	v_mfma_f32_32x32x16_bf16 v[34:49], v[158:161], v[166:169], v[34:49]
	v_mfma_f32_32x32x16_bf16 v[18:33], v[214:217], v[162:165], v[18:33]
	v_mfma_f32_32x32x16_bf16 v[2:17], v[214:217], v[166:169], v[2:17]
	ds_read_b128 v[158:161], v140 offset:64
	ds_read_b128 v[162:165], v141 offset:18496
	ds_read_b128 v[166:169], v141 offset:23104
	ds_read_b128 v[214:217], v140 offset:4672
	s_waitcnt lgkmcnt(4)
	v_mfma_f32_32x32x16_bf16 v[50:65], v[218:221], v[222:225], v[50:65]
	v_mfma_f32_32x32x16_bf16 v[34:49], v[218:221], v[226:229], v[34:49]
	v_mfma_f32_32x32x16_bf16 v[18:33], v[230:233], v[222:225], v[18:33]
	v_mfma_f32_32x32x16_bf16 v[2:17], v[230:233], v[226:229], v[2:17]
	ds_read_b128 v[218:221], v140 offset:96
	ds_read_b128 v[222:225], v141 offset:18528
	ds_read_b128 v[226:229], v141 offset:23136
	ds_read_b128 v[230:233], v140 offset:4704
	s_waitcnt lgkmcnt(4)
	v_mfma_f32_32x32x16_bf16 v[50:65], v[158:161], v[162:165], v[50:65]
	v_mfma_f32_32x32x16_bf16 v[34:49], v[158:161], v[166:169], v[34:49]
	v_mfma_f32_32x32x16_bf16 v[18:33], v[214:217], v[162:165], v[18:33]
	v_mfma_f32_32x32x16_bf16 v[2:17], v[214:217], v[166:169], v[2:17]
	s_waitcnt lgkmcnt(0)
	v_mfma_f32_32x32x16_bf16 v[50:65], v[218:221], v[222:225], v[50:65]
	v_mfma_f32_32x32x16_bf16 v[34:49], v[218:221], v[226:229], v[34:49]
	v_mfma_f32_32x32x16_bf16 v[18:33], v[230:233], v[222:225], v[18:33]
	v_mfma_f32_32x32x16_bf16 v[2:17], v[230:233], v[226:229], v[2:17]
	s_setprio 0
	s_andn2_b64 vcc, exec, s[38:39]
	s_waitcnt vmcnt(7)
	ds_write_b128 v188, v[66:69] offset:36864
	s_waitcnt vmcnt(6)
	ds_write_b128 v188, v[70:73] offset:41472
	s_waitcnt vmcnt(5)
	ds_write_b128 v188, v[74:77] offset:46080
	s_waitcnt vmcnt(4)
	ds_write_b128 v188, v[78:81] offset:50688
	s_waitcnt vmcnt(3)
	ds_write_b128 v188, v[82:85] offset:55296
	s_waitcnt vmcnt(2)
	ds_write_b128 v188, v[90:93] offset:59904
	s_waitcnt vmcnt(1)
	ds_write_b128 v188, v[94:97] offset:64512
	s_waitcnt vmcnt(0)
	ds_write_b128 v189, v[106:109] offset:13824
	s_waitcnt lgkmcnt(0)
	s_barrier
	s_cbranch_vccnz .LBB0_608
	v_add_co_u32_e32 v70, vcc, 0x10000, v132
	global_load_dwordx4 v[66:69], v[132:133], off offset:128
	s_nop 0
	v_addc_co_u32_e32 v71, vcc, 0, v133, vcc
	v_add_co_u32_e32 v74, vcc, 0x20000, v132
	s_nop 1
	v_addc_co_u32_e32 v75, vcc, 0, v133, vcc
	v_add_co_u32_e32 v78, vcc, 0x30000, v132
	global_load_dwordx4 v[70:73], v[70:71], off offset:128
	s_nop 0
	global_load_dwordx4 v[74:77], v[74:75], off offset:128
	v_addc_co_u32_e32 v79, vcc, 0, v133, vcc
	v_add_co_u32_e32 v90, vcc, 0x10000, v134
	global_load_dwordx4 v[78:81], v[78:79], off offset:128
	s_nop 0
	global_load_dwordx4 v[82:85], v[134:135], off offset:128
	v_addc_co_u32_e32 v91, vcc, 0, v135, vcc
	v_add_co_u32_e32 v94, vcc, 0x20000, v134
	s_nop 1
	v_addc_co_u32_e32 v95, vcc, 0, v135, vcc
	v_add_co_u32_e32 v106, vcc, 0x30000, v134
	global_load_dwordx4 v[90:93], v[90:91], off offset:128
	s_nop 0
	global_load_dwordx4 v[94:97], v[94:95], off offset:128
	v_addc_co_u32_e32 v107, vcc, 0, v135, vcc
	global_load_dwordx4 v[106:109], v[106:107], off offset:128
	s_branch .LBB0_608
